# v15 + first K-tile peeled in 8 GEMM K-loops: first-touch MFMAs take C=0 inline, per-unit accumulator zeroing (64-128 v_mov) removed
# speedup vs baseline: 1.0027x; 1.0027x over previous
; #define PG8_STAGE(bufoff, gbase, voff) do { _Pragma("unroll") for (int _i = 0; _i < 2; ++_i) \
;         __builtin_amdgcn_global_load_lds((const unsigned*)((const char*)(gbase) + (voff)[_i]), (PG8_LAS unsigned*)(lds + (bufoff) + ldsw + _i * 8192), 16, 0, 0); } while (0)
; #define PG8_LDA(dst, b, h) do { _Pragma("unroll") for (int m = 0; m < 4; ++m) _Pragma("unroll") for (int k = 0; k < 2; ++k) dst[m][k] = *(const PG8_LAS bf16x8*)(lds + PG8_SA(b, h) + aoff + m * 2048 + k * 1024); } while (0)
; #define PG8_LDB(dst, b, h) do { _Pragma("unroll") for (int n = 0; n < 2; ++n) _Pragma("unroll") for (int k = 0; k < 2; ++k) dst[n][k] = *(const PG8_LAS bf16x8*)(lds + PG8_SB(b, h) + boff + n * 2048 + k * 1024); } while (0)
; #define PG8_WAIT_V(n) asm volatile("s_waitcnt vmcnt(" #n ")" ::: "memory")
; #define PG8_WAIT_L(n) asm volatile("s_waitcnt lgkmcnt(" #n ")" ::: "memory")
; #define PG8_BAR __builtin_amdgcn_s_barrier()
; #define PG8_SCHED __builtin_amdgcn_sched_barrier(0)
;     ...
; #pragma unroll
;     for (int a = 0; a < 2; ++a)
; #pragma unroll
;         for (int b = 0; b < 2; ++b)
; #pragma unroll
;             for (int m = 0; m < 4; ++m)
; #pragma unroll
;                 for (int n = 0; n < 2; ++n) acc[a][b][m][n] = (f32x4){0.f, 0.f, 0.f, 0.f};
;     ...
;             PG8_LDB(B0, 0, 0); PG8_LDB(B1, 0, 1); PG8_SCHED; PG8_LDA(At, 0, 0); PG8_STAGE(PG8_SA(1, 1), a1 + hstepA, voffA);
;             PG8_WAIT_V(8); PG8_WAIT_L(0); PG8_BAR; PG8_MMA(0, 0, At, B0); PG8_MMA(0, 1, At, B1); PG8_BAR; PG8_SCHED;
;             PG8_LDA(At, 0, 1); PG8_STAGE(PG8_SB(0, 0), b2, voffB); PG8_STAGE(PG8_SB(0, 1), b2 + hstepB, voffB); PG8_STAGE(PG8_SA(0, 0), a2, voffA);
;             PG8_WAIT_V(8); PG8_WAIT_L(0); PG8_BAR; PG8_MMA(1, 0, At, B0); PG8_MMA(1, 1, At, B1); PG8_BAR; PG8_SCHED;
.LBB0_537:
	s_ashr_i32 s57, s56, 31
	s_lshl_b64 s[34:35], s[56:57], 19
	s_add_u32 s58, s11, s34
	s_addc_u32 s59, s24, s35
	s_and_b64 s[34:35], s[42:43], exec
	s_cselect_b32 s6, s59, s65
	s_cselect_b32 s15, s58, s64
	s_ashr_i32 s55, s54, 31
	s_lshl_b64 s[34:35], s[54:55], 19
	s_add_u32 s60, s79, s34
	s_addc_u32 s61, s80, s35
	s_and_b64 s[34:35], s[42:43], exec
	s_cselect_b32 s34, s61, s67
	s_cselect_b32 s35, s60, s66
	s_add_u32 s64, s64, 0x40080
	s_addc_u32 s65, s65, 0
	s_add_u32 s45, s66, 0x100
	s_addc_u32 s55, s67, 0
	s_mov_b32 s57, -2
	s_waitcnt lgkmcnt(0)
	v_add_u32_e32 v162, 0x10000, v153
	s_add_u32 s63, s64, 0xfffc0080
	s_addc_u32 s66, s65, -1
	s_add_i32 s68, 0, 0x10000
	s_cmp_eq_u32 s57, 12
	s_cselect_b32 s75, s6, s66
	s_cselect_b32 s74, s15, s63
	s_cselect_b32 s67, s34, s55
	s_cselect_b32 s66, s35, s45
	s_add_i32 s63, 0, 0x14000
	ds_read_b128 v[142:145], v162
	ds_read_b128 v[146:149], v162 offset:1024
	ds_read_b128 v[158:161], v162 offset:2048
	ds_read_b128 v[186:189], v162 offset:3072
	ds_read_b128 v[190:193], v162 offset:16384
	ds_read_b128 v[194:197], v162 offset:17408
	ds_read_b128 v[198:201], v162 offset:18432
	ds_read_b128 v[202:205], v162 offset:19456
	s_add_i32 m0, s81, 0xc000
	ds_read_b128 v[206:209], v156
	ds_read_b128 v[210:213], v156 offset:1024
	ds_read_b128 v[214:217], v156 offset:2048
	ds_read_b128 v[218:221], v156 offset:3072
	ds_read_b128 v[222:225], v156 offset:4096
	ds_read_b128 v[234:237], v156 offset:5120
	ds_read_b128 v[238:241], v156 offset:6144
	ds_read_b128 v[242:245], v156 offset:7168
	global_load_lds_dwordx4 v138, s[64:65]
	s_add_i32 m0, s81, 0xe000
	s_nop 0
	global_load_lds_dwordx4 v140, s[64:65]
	s_waitcnt vmcnt(8)
	s_waitcnt lgkmcnt(0)
	s_barrier
	v_mfma_i32_16x16x64_i8 v[128:131], v[142:145], v[206:209], 0
	v_mfma_i32_16x16x64_i8 v[120:123], v[158:161], v[206:209], 0
	v_mfma_i32_16x16x64_i8 v[112:115], v[142:145], v[214:217], 0
	v_mfma_i32_16x16x64_i8 v[104:107], v[158:161], v[214:217], 0
	v_mfma_i32_16x16x64_i8 v[96:99], v[142:145], v[222:225], 0
	v_mfma_i32_16x16x64_i8 v[88:91], v[158:161], v[222:225], 0
	v_mfma_i32_16x16x64_i8 v[80:83], v[142:145], v[238:241], 0
	v_mfma_i32_16x16x64_i8 v[72:75], v[158:161], v[238:241], 0
	v_mfma_i32_16x16x64_i8 v[128:131], v[146:149], v[210:213], v[128:131]
	v_mfma_i32_16x16x64_i8 v[120:123], v[186:189], v[210:213], v[120:123]
	v_mfma_i32_16x16x64_i8 v[112:115], v[146:149], v[218:221], v[112:115]
	v_mfma_i32_16x16x64_i8 v[104:107], v[186:189], v[218:221], v[104:107]
	v_mfma_i32_16x16x64_i8 v[96:99], v[146:149], v[234:237], v[96:99]
	v_mfma_i32_16x16x64_i8 v[88:91], v[186:189], v[234:237], v[88:91]
	v_mfma_i32_16x16x64_i8 v[80:83], v[146:149], v[242:245], v[80:83]
	v_mfma_i32_16x16x64_i8 v[72:75], v[186:189], v[242:245], v[72:75]
	v_mfma_i32_16x16x64_i8 v[124:127], v[190:193], v[206:209], 0
	v_mfma_i32_16x16x64_i8 v[116:119], v[198:201], v[206:209], 0
	v_mfma_i32_16x16x64_i8 v[108:111], v[190:193], v[214:217], 0
	v_mfma_i32_16x16x64_i8 v[100:103], v[198:201], v[214:217], 0
	v_mfma_i32_16x16x64_i8 v[92:95], v[190:193], v[222:225], 0
	v_mfma_i32_16x16x64_i8 v[84:87], v[198:201], v[222:225], 0
	v_mfma_i32_16x16x64_i8 v[76:79], v[190:193], v[238:241], 0
	v_mfma_i32_16x16x64_i8 v[68:71], v[198:201], v[238:241], 0
	v_mfma_i32_16x16x64_i8 v[124:127], v[194:197], v[210:213], v[124:127]
	v_mfma_i32_16x16x64_i8 v[116:119], v[202:205], v[210:213], v[116:119]
	v_mfma_i32_16x16x64_i8 v[108:111], v[194:197], v[218:221], v[108:111]
	v_mfma_i32_16x16x64_i8 v[100:103], v[202:205], v[218:221], v[100:103]
	v_mfma_i32_16x16x64_i8 v[92:95], v[194:197], v[234:237], v[92:95]
	v_mfma_i32_16x16x64_i8 v[84:87], v[202:205], v[234:237], v[84:87]
	v_mfma_i32_16x16x64_i8 v[76:79], v[194:197], v[242:245], v[76:79]
	v_mfma_i32_16x16x64_i8 v[68:71], v[202:205], v[242:245], v[68:71]
	s_barrier
	s_add_i32 s68, s68, s10
	s_mov_b32 m0, s68
	ds_read_b128 v[206:209], v156 offset:16384
	ds_read_b128 v[210:213], v156 offset:17408
	ds_read_b128 v[214:217], v156 offset:18432
	ds_read_b128 v[218:221], v156 offset:19456
	ds_read_b128 v[222:225], v156 offset:20480
	ds_read_b128 v[234:237], v156 offset:21504
	ds_read_b128 v[238:241], v156 offset:22528
	ds_read_b128 v[242:245], v156 offset:23552
	global_load_lds_dwordx4 v34, s[66:67]
	s_add_i32 m0, s68, 0x2000
	s_add_u32 s70, s66, 0x40000
	s_addc_u32 s71, s67, 0
	s_add_i32 s63, s63, s10
	global_load_lds_dwordx4 v136, s[66:67]
	s_mov_b32 m0, s63
	s_nop 0
	global_load_lds_dwordx4 v34, s[70:71]
	s_add_i32 m0, s63, 0x2000
	s_nop 0
	global_load_lds_dwordx4 v136, s[70:71]
	s_mov_b32 m0, s81
	s_nop 0
	global_load_lds_dwordx4 v132, s[74:75]
	s_mov_b32 m0, s82
	s_nop 0
	global_load_lds_dwordx4 v134, s[74:75]
	s_waitcnt vmcnt(8)
	s_waitcnt lgkmcnt(0)
	s_barrier
	v_mfma_i32_16x16x64_i8 v[64:67], v[142:145], v[206:209], 0
	v_mfma_i32_16x16x64_i8 v[56:59], v[158:161], v[206:209], 0
	v_mfma_i32_16x16x64_i8 v[48:51], v[142:145], v[214:217], 0
	v_mfma_i32_16x16x64_i8 v[40:43], v[158:161], v[214:217], 0
	v_mfma_i32_16x16x64_i8 v[30:33], v[142:145], v[222:225], 0
	v_mfma_i32_16x16x64_i8 v[22:25], v[158:161], v[222:225], 0
	v_mfma_i32_16x16x64_i8 v[14:17], v[142:145], v[238:241], 0
	v_mfma_i32_16x16x64_i8 v[6:9], v[158:161], v[238:241], 0
	v_mfma_i32_16x16x64_i8 v[64:67], v[146:149], v[210:213], v[64:67]
	v_mfma_i32_16x16x64_i8 v[56:59], v[186:189], v[210:213], v[56:59]
	v_mfma_i32_16x16x64_i8 v[48:51], v[146:149], v[218:221], v[48:51]
	v_mfma_i32_16x16x64_i8 v[40:43], v[186:189], v[218:221], v[40:43]
	v_mfma_i32_16x16x64_i8 v[30:33], v[146:149], v[234:237], v[30:33]
	v_mfma_i32_16x16x64_i8 v[22:25], v[186:189], v[234:237], v[22:25]
	v_mfma_i32_16x16x64_i8 v[14:17], v[146:149], v[242:245], v[14:17]
	v_mfma_i32_16x16x64_i8 v[6:9], v[186:189], v[242:245], v[6:9]
	v_mfma_i32_16x16x64_i8 v[60:63], v[190:193], v[206:209], 0
	v_mfma_i32_16x16x64_i8 v[52:55], v[198:201], v[206:209], 0
	v_mfma_i32_16x16x64_i8 v[44:47], v[190:193], v[214:217], 0
	v_mfma_i32_16x16x64_i8 v[36:39], v[198:201], v[214:217], 0
	v_mfma_i32_16x16x64_i8 v[26:29], v[190:193], v[222:225], 0
	v_mfma_i32_16x16x64_i8 v[18:21], v[198:201], v[222:225], 0
	v_mfma_i32_16x16x64_i8 v[10:13], v[190:193], v[238:241], 0
	v_mfma_i32_16x16x64_i8 v[2:5], v[198:201], v[238:241], 0
	v_mfma_i32_16x16x64_i8 v[60:63], v[194:197], v[210:213], v[60:63]
	v_mfma_i32_16x16x64_i8 v[52:55], v[202:205], v[210:213], v[52:55]
	v_mfma_i32_16x16x64_i8 v[44:47], v[194:197], v[218:221], v[44:47]
	v_mfma_i32_16x16x64_i8 v[36:39], v[202:205], v[218:221], v[36:39]
	v_mfma_i32_16x16x64_i8 v[26:29], v[194:197], v[234:237], v[26:29]
	v_mfma_i32_16x16x64_i8 v[18:21], v[202:205], v[234:237], v[18:21]
	v_mfma_i32_16x16x64_i8 v[10:13], v[194:197], v[242:245], v[10:13]
	v_mfma_i32_16x16x64_i8 v[2:5], v[202:205], v[242:245], v[2:5]
	s_barrier
	s_branch .Lpeel_mid_538
	.p2align	6

; #define PG8_STAGE(bufoff, gbase, voff) do { _Pragma("unroll") for (int _i = 0; _i < 2; ++_i) \
;         __builtin_amdgcn_global_load_lds((const unsigned*)((const char*)(gbase) + (voff)[_i]), (PG8_LAS unsigned*)(lds + (bufoff) + ldsw + _i * 8192), 16, 0, 0); } while (0)
; #define PG8_LDA(dst, b, h) do { _Pragma("unroll") for (int m = 0; m < 4; ++m) _Pragma("unroll") for (int k = 0; k < 2; ++k) dst[m][k] = *(const PG8_LAS bf16x8*)(lds + PG8_SA(b, h) + aoff + m * 2048 + k * 1024); } while (0)
; #define PG8_LDB(dst, b, h) do { _Pragma("unroll") for (int n = 0; n < 2; ++n) _Pragma("unroll") for (int k = 0; k < 2; ++k) dst[n][k] = *(const PG8_LAS bf16x8*)(lds + PG8_SB(b, h) + boff + n * 2048 + k * 1024); } while (0)
; #define PG8_WAIT_V(n) asm volatile("s_waitcnt vmcnt(" #n ")" ::: "memory")
; #define PG8_WAIT_L(n) asm volatile("s_waitcnt lgkmcnt(" #n ")" ::: "memory")
; #define PG8_BAR __builtin_amdgcn_s_barrier()
; #define PG8_SCHED __builtin_amdgcn_sched_barrier(0)
;     ...
;             PG8_LDB(B0, 1, 0); PG8_LDB(B1, 1, 1); PG8_SCHED; PG8_LDA(At, 1, 0); PG8_STAGE(PG8_SA(0, 1), a2 + hstepA, voffA);
;             PG8_WAIT_V(8); PG8_WAIT_L(0); PG8_BAR; PG8_MMA(0, 0, At, B0); PG8_MMA(0, 1, At, B1); PG8_BAR; PG8_SCHED;
.Lpeel_mid_538:
	s_add_i32 s63, 0, 0x18000
	s_add_i32 s68, 0, 0x1c000
	ds_read_b128 v[142:145], v162 offset:32768
	ds_read_b128 v[146:149], v162 offset:33792
	ds_read_b128 v[158:161], v162 offset:34816
	ds_read_b128 v[186:189], v162 offset:35840
	ds_read_b128 v[190:193], v162 offset:49152
	ds_read_b128 v[194:197], v162 offset:50176
	ds_read_b128 v[198:201], v162 offset:51200
	ds_read_b128 v[202:205], v162 offset:52224
	s_add_u32 s70, s74, 0x40000
	s_addc_u32 s71, s75, 0
	s_mov_b32 m0, s83
	ds_read_b128 v[206:209], v156 offset:32768
	ds_read_b128 v[210:213], v156 offset:33792
	ds_read_b128 v[214:217], v156 offset:34816
	ds_read_b128 v[218:221], v156 offset:35840
	ds_read_b128 v[222:225], v156 offset:36864
	ds_read_b128 v[234:237], v156 offset:37888
	ds_read_b128 v[238:241], v156 offset:38912
	ds_read_b128 v[242:245], v156 offset:39936
	global_load_lds_dwordx4 v132, s[70:71]
	s_mov_b32 m0, s84
	s_nop 0
	global_load_lds_dwordx4 v134, s[70:71]
	s_waitcnt vmcnt(8)
	s_waitcnt lgkmcnt(0)
	s_barrier
	v_mfma_i32_16x16x64_i8 v[128:131], v[142:145], v[206:209], v[128:131]
	v_mfma_i32_16x16x64_i8 v[120:123], v[158:161], v[206:209], v[120:123]
	v_mfma_i32_16x16x64_i8 v[112:115], v[142:145], v[214:217], v[112:115]
	v_mfma_i32_16x16x64_i8 v[104:107], v[158:161], v[214:217], v[104:107]
	v_mfma_i32_16x16x64_i8 v[96:99], v[142:145], v[222:225], v[96:99]
	v_mfma_i32_16x16x64_i8 v[88:91], v[158:161], v[222:225], v[88:91]
	v_mfma_i32_16x16x64_i8 v[80:83], v[142:145], v[238:241], v[80:83]
	v_mfma_i32_16x16x64_i8 v[72:75], v[158:161], v[238:241], v[72:75]
	v_mfma_i32_16x16x64_i8 v[128:131], v[146:149], v[210:213], v[128:131]
	v_mfma_i32_16x16x64_i8 v[120:123], v[186:189], v[210:213], v[120:123]
	v_mfma_i32_16x16x64_i8 v[112:115], v[146:149], v[218:221], v[112:115]
	v_mfma_i32_16x16x64_i8 v[104:107], v[186:189], v[218:221], v[104:107]
	v_mfma_i32_16x16x64_i8 v[96:99], v[146:149], v[234:237], v[96:99]
	v_mfma_i32_16x16x64_i8 v[88:91], v[186:189], v[234:237], v[88:91]
	v_mfma_i32_16x16x64_i8 v[80:83], v[146:149], v[242:245], v[80:83]
	v_mfma_i32_16x16x64_i8 v[72:75], v[186:189], v[242:245], v[72:75]
	v_mfma_i32_16x16x64_i8 v[124:127], v[190:193], v[206:209], v[124:127]
	v_mfma_i32_16x16x64_i8 v[116:119], v[198:201], v[206:209], v[116:119]
	v_mfma_i32_16x16x64_i8 v[108:111], v[190:193], v[214:217], v[108:111]
	v_mfma_i32_16x16x64_i8 v[100:103], v[198:201], v[214:217], v[100:103]
	v_mfma_i32_16x16x64_i8 v[92:95], v[190:193], v[222:225], v[92:95]
	v_mfma_i32_16x16x64_i8 v[84:87], v[198:201], v[222:225], v[84:87]
	v_mfma_i32_16x16x64_i8 v[76:79], v[190:193], v[238:241], v[76:79]
	v_mfma_i32_16x16x64_i8 v[68:71], v[198:201], v[238:241], v[68:71]
	v_mfma_i32_16x16x64_i8 v[124:127], v[194:197], v[210:213], v[124:127]
	v_mfma_i32_16x16x64_i8 v[116:119], v[202:205], v[210:213], v[116:119]
	v_mfma_i32_16x16x64_i8 v[108:111], v[194:197], v[218:221], v[108:111]
	v_mfma_i32_16x16x64_i8 v[100:103], v[202:205], v[218:221], v[100:103]
	v_mfma_i32_16x16x64_i8 v[92:95], v[194:197], v[234:237], v[92:95]
	v_mfma_i32_16x16x64_i8 v[84:87], v[202:205], v[234:237], v[84:87]
	v_mfma_i32_16x16x64_i8 v[76:79], v[194:197], v[242:245], v[76:79]
	v_mfma_i32_16x16x64_i8 v[68:71], v[202:205], v[242:245], v[68:71]
	s_barrier
; #define PG8_STAGE(bufoff, gbase, voff) do { _Pragma("unroll") for (int _i = 0; _i < 2; ++_i) \
;         __builtin_amdgcn_global_load_lds((const unsigned*)((const char*)(gbase) + (voff)[_i]), (PG8_LAS unsigned*)(lds + (bufoff) + ldsw + _i * 8192), 16, 0, 0); } while (0)
; #define PG8_LDA(dst, b, h) do { _Pragma("unroll") for (int m = 0; m < 4; ++m) _Pragma("unroll") for (int k = 0; k < 2; ++k) dst[m][k] = *(const PG8_LAS bf16x8*)(lds + PG8_SA(b, h) + aoff + m * 2048 + k * 1024); } while (0)
; #define PG8_WAIT_V(n) asm volatile("s_waitcnt vmcnt(" #n ")" ::: "memory")
; #define PG8_WAIT_L(n) asm volatile("s_waitcnt lgkmcnt(" #n ")" ::: "memory")
; #define PG8_BAR __builtin_amdgcn_s_barrier()
; #define PG8_SCHED __builtin_amdgcn_sched_barrier(0)
;     __device__ __forceinline__ void operator()(const f32x4 (&acc)[2][2][4][2], const Unit& u, int wr, int wc, int fr, int fq) const {
;     ...
;                 float r[8]; const float scr_ = rs ? rs[row0 + ai * HALF + m * 16] * sc : sc;
;     ...
;             PG8_LDA(At, 1, 1); PG8_STAGE(PG8_SB(1, 0), b3, voffB); PG8_STAGE(PG8_SB(1, 1), b3 + hstepB, voffB); PG8_STAGE(PG8_SA(1, 0), a3, voffA);
;             PG8_WAIT_V(8); PG8_WAIT_L(0); PG8_BAR; PG8_MMA(1, 0, At, B0); PG8_MMA(1, 1, At, B1); PG8_BAR; PG8_SCHED;
	s_add_i32 s63, s63, s10
	s_mov_b32 m0, s63
	ds_read_b128 v[206:209], v156 offset:49152
	ds_read_b128 v[210:213], v156 offset:50176
	ds_read_b128 v[214:217], v156 offset:51200
	ds_read_b128 v[218:221], v156 offset:52224
	ds_read_b128 v[222:225], v156 offset:53248
	ds_read_b128 v[234:237], v156 offset:54272
	ds_read_b128 v[238:241], v156 offset:55296
	ds_read_b128 v[242:245], v156 offset:56320
	s_add_u32 vcc_lo, s66, 0x80
	s_addc_u32 vcc_hi, s67, 0
	global_load_lds_dwordx4 v34, vcc
	s_add_i32 m0, s63, 0x2000
	s_add_u32 s66, s66, 0x40080
	s_addc_u32 s67, s67, 0
	s_add_i32 s63, s68, s10
	s_add_u32 vcc_lo, s66, 0xfffc0000
	s_addc_u32 vcc_hi, s67, -1
	global_load_lds_dwordx4 v136, vcc
	s_mov_b32 m0, s63
	s_nop 0
	global_load_lds_dwordx4 v34, s[66:67]
	s_add_i32 m0, s63, 0x2000
	s_nop 0
	global_load_lds_dwordx4 v136, s[66:67]
	s_mov_b32 m0, s86
	s_nop 0
	s_add_u32 vcc_lo, s74, 0x80
	s_addc_u32 vcc_hi, s75, 0
	global_load_lds_dwordx4 v132, vcc
	s_mov_b32 m0, s87
	s_nop 0
	s_add_u32 vcc_lo, s74, 0x80
	s_addc_u32 vcc_hi, s75, 0
	global_load_lds_dwordx4 v134, vcc
	s_waitcnt vmcnt(8)
	s_waitcnt lgkmcnt(0)
	s_barrier
	v_mfma_i32_16x16x64_i8 v[64:67], v[142:145], v[206:209], v[64:67]
	v_mfma_i32_16x16x64_i8 v[56:59], v[158:161], v[206:209], v[56:59]
	v_mfma_i32_16x16x64_i8 v[48:51], v[142:145], v[214:217], v[48:51]
	v_mfma_i32_16x16x64_i8 v[40:43], v[158:161], v[214:217], v[40:43]
	v_mfma_i32_16x16x64_i8 v[30:33], v[142:145], v[222:225], v[30:33]
	v_mfma_i32_16x16x64_i8 v[22:25], v[158:161], v[222:225], v[22:25]
	v_mfma_i32_16x16x64_i8 v[14:17], v[142:145], v[238:241], v[14:17]
	v_mfma_i32_16x16x64_i8 v[6:9], v[158:161], v[238:241], v[6:9]
	v_mfma_i32_16x16x64_i8 v[64:67], v[146:149], v[210:213], v[64:67]
	v_mfma_i32_16x16x64_i8 v[56:59], v[186:189], v[210:213], v[56:59]
	v_mfma_i32_16x16x64_i8 v[48:51], v[146:149], v[218:221], v[48:51]
	v_mfma_i32_16x16x64_i8 v[40:43], v[186:189], v[218:221], v[40:43]
	v_mfma_i32_16x16x64_i8 v[30:33], v[146:149], v[234:237], v[30:33]
	v_mfma_i32_16x16x64_i8 v[22:25], v[186:189], v[234:237], v[22:25]
	v_mfma_i32_16x16x64_i8 v[14:17], v[146:149], v[242:245], v[14:17]
	v_mfma_i32_16x16x64_i8 v[6:9], v[186:189], v[242:245], v[6:9]
	v_mfma_i32_16x16x64_i8 v[60:63], v[190:193], v[206:209], v[60:63]
	v_mfma_i32_16x16x64_i8 v[52:55], v[198:201], v[206:209], v[52:55]
	v_mfma_i32_16x16x64_i8 v[44:47], v[190:193], v[214:217], v[44:47]
	v_mfma_i32_16x16x64_i8 v[36:39], v[198:201], v[214:217], v[36:39]
	v_mfma_i32_16x16x64_i8 v[26:29], v[190:193], v[222:225], v[26:29]
	v_mfma_i32_16x16x64_i8 v[18:21], v[198:201], v[222:225], v[18:21]
	v_mfma_i32_16x16x64_i8 v[10:13], v[190:193], v[238:241], v[10:13]
	v_mfma_i32_16x16x64_i8 v[2:5], v[198:201], v[238:241], v[2:5]
	v_mfma_i32_16x16x64_i8 v[60:63], v[194:197], v[210:213], v[60:63]
	v_mfma_i32_16x16x64_i8 v[52:55], v[202:205], v[210:213], v[52:55]
	v_mfma_i32_16x16x64_i8 v[44:47], v[194:197], v[218:221], v[44:47]
	v_mfma_i32_16x16x64_i8 v[36:39], v[202:205], v[218:221], v[36:39]
	v_mfma_i32_16x16x64_i8 v[26:29], v[194:197], v[234:237], v[26:29]
	v_mfma_i32_16x16x64_i8 v[18:21], v[202:205], v[234:237], v[18:21]
	v_mfma_i32_16x16x64_i8 v[10:13], v[194:197], v[242:245], v[10:13]
	v_mfma_i32_16x16x64_i8 v[2:5], v[202:205], v[242:245], v[2:5]
	s_barrier
	s_add_i32 s57, s57, 2
	s_add_u32 s64, s64, 0x100
	s_addc_u32 s65, s65, 0
	s_add_u32 s45, s45, 0x100
	s_addc_u32 s55, s55, 0
	s_cmp_gt_u32 s57, 13
	s_cbranch_scc0 .LBB0_538
	v_lshl_add_u32 v144, s62, 8, v152
	v_ashrrev_i32_e32 v145, 31, v144
	v_lshl_add_u64 v[146:147], v[144:145], 2, s[50:51]
	global_load_dword v186, v[146:147], off
	global_load_dword v187, v[146:147], off offset:64
	global_load_dword v188, v[146:147], off offset:128
	global_load_dword v189, v[146:147], off offset:192
	global_load_dword v190, v[146:147], off offset:512
	global_load_dword v191, v[146:147], off offset:576
	global_load_dword v192, v[146:147], off offset:640
	global_load_dword v193, v[146:147], off offset:704
	s_and_b64 vcc, exec, s[52:53]
	s_cbranch_vccz .LBB0_541
	s_barrier

; #define PG8_STAGE(bufoff, gbase, voff) do { _Pragma("unroll") for (int _i = 0; _i < 2; ++_i) \
;         __builtin_amdgcn_global_load_lds((const unsigned*)((const char*)(gbase) + (voff)[_i]), (PG8_LAS unsigned*)(lds + (bufoff) + ldsw + _i * 8192), 16, 0, 0); } while (0)
; #define PG8_LDA(dst, b, h) do { _Pragma("unroll") for (int m = 0; m < 4; ++m) _Pragma("unroll") for (int k = 0; k < 2; ++k) dst[m][k] = *(const PG8_LAS bf16x8*)(lds + PG8_SA(b, h) + aoff + m * 2048 + k * 1024); } while (0)
; #define PG8_LDB(dst, b, h) do { _Pragma("unroll") for (int n = 0; n < 2; ++n) _Pragma("unroll") for (int k = 0; k < 2; ++k) dst[n][k] = *(const PG8_LAS bf16x8*)(lds + PG8_SB(b, h) + boff + n * 2048 + k * 1024); } while (0)
; #define PG8_WAIT_V(n) asm volatile("s_waitcnt vmcnt(" #n ")" ::: "memory")
; #define PG8_WAIT_L(n) asm volatile("s_waitcnt lgkmcnt(" #n ")" ::: "memory")
; #define PG8_BAR __builtin_amdgcn_s_barrier()
; #define PG8_SCHED __builtin_amdgcn_sched_barrier(0)
;     ...
; #pragma unroll
;     for (int a = 0; a < 2; ++a)
; #pragma unroll
;         for (int b = 0; b < 2; ++b)
; #pragma unroll
;             for (int m = 0; m < 4; ++m)
; #pragma unroll
;                 for (int n = 0; n < 2; ++n) acc[a][b][m][n] = (f32x4){0.f, 0.f, 0.f, 0.f};
;     ...
;             PG8_LDB(B0, 0, 0); PG8_LDB(B1, 0, 1); PG8_SCHED; PG8_LDA(At, 0, 0); PG8_STAGE(PG8_SA(1, 1), a1 + hstepA, voffA);
;             PG8_WAIT_V(8); PG8_WAIT_L(0); PG8_BAR; PG8_MMA(0, 0, At, B0); PG8_MMA(0, 1, At, B1); PG8_BAR; PG8_SCHED;
;             PG8_LDA(At, 0, 1); PG8_STAGE(PG8_SB(0, 0), b2, voffB); PG8_STAGE(PG8_SB(0, 1), b2 + hstepB, voffB); PG8_STAGE(PG8_SA(0, 0), a2, voffA);
;             PG8_WAIT_V(8); PG8_WAIT_L(0); PG8_BAR; PG8_MMA(1, 0, At, B0); PG8_MMA(1, 1, At, B1); PG8_BAR; PG8_SCHED;
.LBB0_607:
	s_ashr_i32 s37, s36, 31
	s_lshl_b64 s[40:41], s[36:37], 20
	s_add_u32 s40, s8, s40
	s_addc_u32 s41, s10, s41
	s_and_b64 s[42:43], s[38:39], exec
	s_cselect_b32 s37, s41, s51
	s_cselect_b32 s58, s40, s50
	s_ashr_i32 s31, s30, 31
	s_lshl_b64 s[42:43], s[30:31], 20
	s_add_u32 s42, s9, s42
	s_addc_u32 s43, s76, s43
	s_and_b64 s[54:55], s[38:39], exec
	s_cselect_b32 s31, s43, s53
	s_cselect_b32 s59, s42, s52
	s_add_u32 s50, s50, 0x80080
	s_addc_u32 s51, s51, 0
	s_add_u32 s60, s52, 0x100
	s_addc_u32 s61, s53, 0
	s_mov_b32 s62, -2
	v_add_u32_e32 v226, 0x10000, v145
	s_add_u32 s52, s50, 0xfff80080
	s_addc_u32 s53, s51, -1
	s_add_i32 s63, 0, 0x10000
	s_cmp_eq_u32 s62, 28
	s_cselect_b32 s55, s37, s53
	s_cselect_b32 s54, s58, s52
	s_cselect_b32 s53, s31, s61
	s_cselect_b32 s52, s59, s60
	s_add_i32 s66, 0, 0x14000
	ds_read_b128 v[148:151], v226
	ds_read_b128 v[152:155], v226 offset:1024
	ds_read_b128 v[156:159], v226 offset:2048
	ds_read_b128 v[160:163], v226 offset:3072
	ds_read_b128 v[186:189], v226 offset:16384
	ds_read_b128 v[190:193], v226 offset:17408
	ds_read_b128 v[194:197], v226 offset:18432
	ds_read_b128 v[198:201], v226 offset:19456
	s_add_i32 m0, s12, 0xc000
	ds_read_b128 v[202:205], v147
	ds_read_b128 v[206:209], v147 offset:1024
	ds_read_b128 v[210:213], v147 offset:2048
	ds_read_b128 v[214:217], v147 offset:3072
	ds_read_b128 v[218:221], v147 offset:4096
	ds_read_b128 v[222:225], v147 offset:5120
	ds_read_b128 v[234:237], v147 offset:6144
	ds_read_b128 v[238:241], v147 offset:7168
	global_load_lds_dwordx4 v138, s[50:51]
	s_add_i32 m0, s12, 0xe000
	s_nop 0
	global_load_lds_dwordx4 v140, s[50:51]
	s_waitcnt vmcnt(8)
	s_waitcnt lgkmcnt(0)
	s_barrier
	v_mfma_f32_16x16x32_bf16 v[128:131], v[148:151], v[202:205], 0
	v_mfma_f32_16x16x32_bf16 v[124:127], v[156:159], v[202:205], 0
	v_mfma_f32_16x16x32_bf16 v[112:115], v[148:151], v[210:213], 0
	v_mfma_f32_16x16x32_bf16 v[108:111], v[156:159], v[210:213], 0
	v_mfma_f32_16x16x32_bf16 v[96:99], v[148:151], v[218:221], 0
	v_mfma_f32_16x16x32_bf16 v[92:95], v[156:159], v[218:221], 0
	v_mfma_f32_16x16x32_bf16 v[80:83], v[148:151], v[234:237], 0
	v_mfma_f32_16x16x32_bf16 v[76:79], v[156:159], v[234:237], 0
	v_mfma_f32_16x16x32_bf16 v[128:131], v[152:155], v[206:209], v[128:131]
	v_mfma_f32_16x16x32_bf16 v[124:127], v[160:163], v[206:209], v[124:127]
	v_mfma_f32_16x16x32_bf16 v[112:115], v[152:155], v[214:217], v[112:115]
	v_mfma_f32_16x16x32_bf16 v[108:111], v[160:163], v[214:217], v[108:111]
	v_mfma_f32_16x16x32_bf16 v[96:99], v[152:155], v[222:225], v[96:99]
	v_mfma_f32_16x16x32_bf16 v[92:95], v[160:163], v[222:225], v[92:95]
	v_mfma_f32_16x16x32_bf16 v[80:83], v[152:155], v[238:241], v[80:83]
	v_mfma_f32_16x16x32_bf16 v[76:79], v[160:163], v[238:241], v[76:79]
	v_mfma_f32_16x16x32_bf16 v[120:123], v[186:189], v[202:205], 0
	v_mfma_f32_16x16x32_bf16 v[116:119], v[194:197], v[202:205], 0
	v_mfma_f32_16x16x32_bf16 v[104:107], v[186:189], v[210:213], 0
	v_mfma_f32_16x16x32_bf16 v[100:103], v[194:197], v[210:213], 0
	v_mfma_f32_16x16x32_bf16 v[88:91], v[186:189], v[218:221], 0
	v_mfma_f32_16x16x32_bf16 v[84:87], v[194:197], v[218:221], 0
	v_mfma_f32_16x16x32_bf16 v[72:75], v[186:189], v[234:237], 0
	v_mfma_f32_16x16x32_bf16 v[68:71], v[194:197], v[234:237], 0
	v_mfma_f32_16x16x32_bf16 v[120:123], v[190:193], v[206:209], v[120:123]
	v_mfma_f32_16x16x32_bf16 v[116:119], v[198:201], v[206:209], v[116:119]
	v_mfma_f32_16x16x32_bf16 v[104:107], v[190:193], v[214:217], v[104:107]
	v_mfma_f32_16x16x32_bf16 v[100:103], v[198:201], v[214:217], v[100:103]
	v_mfma_f32_16x16x32_bf16 v[88:91], v[190:193], v[222:225], v[88:91]
	v_mfma_f32_16x16x32_bf16 v[84:87], v[198:201], v[222:225], v[84:87]
	v_mfma_f32_16x16x32_bf16 v[72:75], v[190:193], v[238:241], v[72:75]
	v_mfma_f32_16x16x32_bf16 v[68:71], v[198:201], v[238:241], v[68:71]
	s_barrier
	s_add_i32 s63, s63, s6
	s_mov_b32 m0, s63
	ds_read_b128 v[202:205], v147 offset:16384
	ds_read_b128 v[206:209], v147 offset:17408
	ds_read_b128 v[210:213], v147 offset:18432
	ds_read_b128 v[214:217], v147 offset:19456
	ds_read_b128 v[218:221], v147 offset:20480
	ds_read_b128 v[222:225], v147 offset:21504
	ds_read_b128 v[234:237], v147 offset:22528
	ds_read_b128 v[238:241], v147 offset:23552
	global_load_lds_dwordx4 v34, s[52:53]
	s_add_i32 m0, s63, 0x2000
	s_add_u32 s64, s52, 0x80000
	s_addc_u32 s65, s53, 0
	s_add_i32 s63, s66, s6
	global_load_lds_dwordx4 v132, s[52:53]
	s_mov_b32 m0, s63
	s_add_u32 s98, s54, 0x80
	s_addc_u32 s99, s55, 0
	global_load_lds_dwordx4 v34, s[64:65]
	s_add_i32 m0, s63, 0x2000
	s_nop 0
	global_load_lds_dwordx4 v132, s[64:65]
	s_mov_b32 m0, s12
	s_nop 0
	global_load_lds_dwordx4 v136, s[54:55]
	s_mov_b32 m0, s13
	s_nop 0
	global_load_lds_dwordx4 v134, s[54:55]
	s_waitcnt vmcnt(8)
	s_waitcnt lgkmcnt(0)
	s_barrier
	v_mfma_f32_16x16x32_bf16 v[64:67], v[148:151], v[202:205], 0
	v_mfma_f32_16x16x32_bf16 v[60:63], v[156:159], v[202:205], 0
	v_mfma_f32_16x16x32_bf16 v[48:51], v[148:151], v[210:213], 0
	v_mfma_f32_16x16x32_bf16 v[44:47], v[156:159], v[210:213], 0
	v_mfma_f32_16x16x32_bf16 v[30:33], v[148:151], v[218:221], 0
	v_mfma_f32_16x16x32_bf16 v[26:29], v[156:159], v[218:221], 0
	v_mfma_f32_16x16x32_bf16 v[14:17], v[148:151], v[234:237], 0
	v_mfma_f32_16x16x32_bf16 v[10:13], v[156:159], v[234:237], 0
	v_mfma_f32_16x16x32_bf16 v[64:67], v[152:155], v[206:209], v[64:67]
	v_mfma_f32_16x16x32_bf16 v[60:63], v[160:163], v[206:209], v[60:63]
	v_mfma_f32_16x16x32_bf16 v[48:51], v[152:155], v[214:217], v[48:51]
	v_mfma_f32_16x16x32_bf16 v[44:47], v[160:163], v[214:217], v[44:47]
	v_mfma_f32_16x16x32_bf16 v[30:33], v[152:155], v[222:225], v[30:33]
	v_mfma_f32_16x16x32_bf16 v[26:29], v[160:163], v[222:225], v[26:29]
	v_mfma_f32_16x16x32_bf16 v[14:17], v[152:155], v[238:241], v[14:17]
	v_mfma_f32_16x16x32_bf16 v[10:13], v[160:163], v[238:241], v[10:13]
	v_mfma_f32_16x16x32_bf16 v[56:59], v[186:189], v[202:205], 0
	v_mfma_f32_16x16x32_bf16 v[52:55], v[194:197], v[202:205], 0
	v_mfma_f32_16x16x32_bf16 v[40:43], v[186:189], v[210:213], 0
	v_mfma_f32_16x16x32_bf16 v[36:39], v[194:197], v[210:213], 0
	v_mfma_f32_16x16x32_bf16 v[22:25], v[186:189], v[218:221], 0
	v_mfma_f32_16x16x32_bf16 v[18:21], v[194:197], v[218:221], 0
	v_mfma_f32_16x16x32_bf16 v[6:9], v[186:189], v[234:237], 0
	v_mfma_f32_16x16x32_bf16 v[2:5], v[194:197], v[234:237], 0
	v_mfma_f32_16x16x32_bf16 v[56:59], v[190:193], v[206:209], v[56:59]
	v_mfma_f32_16x16x32_bf16 v[52:55], v[198:201], v[206:209], v[52:55]
	v_mfma_f32_16x16x32_bf16 v[40:43], v[190:193], v[214:217], v[40:43]
	v_mfma_f32_16x16x32_bf16 v[36:39], v[198:201], v[214:217], v[36:39]
	v_mfma_f32_16x16x32_bf16 v[22:25], v[190:193], v[222:225], v[22:25]
	v_mfma_f32_16x16x32_bf16 v[18:21], v[198:201], v[222:225], v[18:21]
	v_mfma_f32_16x16x32_bf16 v[6:9], v[190:193], v[238:241], v[6:9]
	v_mfma_f32_16x16x32_bf16 v[2:5], v[198:201], v[238:241], v[2:5]
	s_barrier
	s_branch .Lpeel_mid_608
	.p2align	6

; #define PG8_STAGE(bufoff, gbase, voff) do { _Pragma("unroll") for (int _i = 0; _i < 2; ++_i) \
;         __builtin_amdgcn_global_load_lds((const unsigned*)((const char*)(gbase) + (voff)[_i]), (PG8_LAS unsigned*)(lds + (bufoff) + ldsw + _i * 8192), 16, 0, 0); } while (0)
; #define PG8_LDA(dst, b, h) do { _Pragma("unroll") for (int m = 0; m < 4; ++m) _Pragma("unroll") for (int k = 0; k < 2; ++k) dst[m][k] = *(const PG8_LAS bf16x8*)(lds + PG8_SA(b, h) + aoff + m * 2048 + k * 1024); } while (0)
; #define PG8_LDB(dst, b, h) do { _Pragma("unroll") for (int n = 0; n < 2; ++n) _Pragma("unroll") for (int k = 0; k < 2; ++k) dst[n][k] = *(const PG8_LAS bf16x8*)(lds + PG8_SB(b, h) + boff + n * 2048 + k * 1024); } while (0)
; #define PG8_WAIT_V(n) asm volatile("s_waitcnt vmcnt(" #n ")" ::: "memory")
; #define PG8_WAIT_L(n) asm volatile("s_waitcnt lgkmcnt(" #n ")" ::: "memory")
; #define PG8_BAR __builtin_amdgcn_s_barrier()
; #define PG8_SCHED __builtin_amdgcn_sched_barrier(0)
;     ...
;             PG8_LDB(B0, 1, 0); PG8_LDB(B1, 1, 1); PG8_SCHED; PG8_LDA(At, 1, 0); PG8_STAGE(PG8_SA(0, 1), a2 + hstepA, voffA);
;             PG8_WAIT_V(8); PG8_WAIT_L(0); PG8_BAR; PG8_MMA(0, 0, At, B0); PG8_MMA(0, 1, At, B1); PG8_BAR; PG8_SCHED;
;             PG8_LDA(At, 1, 1); PG8_STAGE(PG8_SB(1, 0), b3, voffB); PG8_STAGE(PG8_SB(1, 1), b3 + hstepB, voffB); PG8_STAGE(PG8_SA(1, 0), a3, voffA);
;             PG8_WAIT_V(8); PG8_WAIT_L(0); PG8_BAR; PG8_MMA(1, 0, At, B0); PG8_MMA(1, 1, At, B1); PG8_BAR; PG8_SCHED;
.Lpeel_mid_608:
	s_add_i32 s63, 0, 0x18000
	s_add_i32 s64, 0, 0x1c000
	ds_read_b128 v[148:151], v226 offset:32768
	ds_read_b128 v[152:155], v226 offset:33792
	ds_read_b128 v[156:159], v226 offset:34816
	ds_read_b128 v[160:163], v226 offset:35840
	ds_read_b128 v[186:189], v226 offset:49152
	ds_read_b128 v[190:193], v226 offset:50176
	ds_read_b128 v[194:197], v226 offset:51200
	ds_read_b128 v[198:201], v226 offset:52224
	s_add_u32 s54, s54, 0x80000
	s_addc_u32 s55, s55, 0
	s_mov_b32 m0, s15
	ds_read_b128 v[202:205], v147 offset:32768
	ds_read_b128 v[206:209], v147 offset:33792
	ds_read_b128 v[210:213], v147 offset:34816
	ds_read_b128 v[214:217], v147 offset:35840
	ds_read_b128 v[218:221], v147 offset:36864
	ds_read_b128 v[222:225], v147 offset:37888
	ds_read_b128 v[234:237], v147 offset:38912
	ds_read_b128 v[238:241], v147 offset:39936
	global_load_lds_dwordx4 v136, s[54:55]
	s_mov_b32 m0, s34
	s_nop 0
	global_load_lds_dwordx4 v134, s[54:55]
	s_waitcnt vmcnt(8)
	s_waitcnt lgkmcnt(0)
	s_barrier
	v_mfma_f32_16x16x32_bf16 v[128:131], v[148:151], v[202:205], v[128:131]
	v_mfma_f32_16x16x32_bf16 v[124:127], v[156:159], v[202:205], v[124:127]
	v_mfma_f32_16x16x32_bf16 v[112:115], v[148:151], v[210:213], v[112:115]
	v_mfma_f32_16x16x32_bf16 v[108:111], v[156:159], v[210:213], v[108:111]
	v_mfma_f32_16x16x32_bf16 v[96:99], v[148:151], v[218:221], v[96:99]
	v_mfma_f32_16x16x32_bf16 v[92:95], v[156:159], v[218:221], v[92:95]
	v_mfma_f32_16x16x32_bf16 v[80:83], v[148:151], v[234:237], v[80:83]
	v_mfma_f32_16x16x32_bf16 v[76:79], v[156:159], v[234:237], v[76:79]
	v_mfma_f32_16x16x32_bf16 v[128:131], v[152:155], v[206:209], v[128:131]
	v_mfma_f32_16x16x32_bf16 v[124:127], v[160:163], v[206:209], v[124:127]
	v_mfma_f32_16x16x32_bf16 v[112:115], v[152:155], v[214:217], v[112:115]
	v_mfma_f32_16x16x32_bf16 v[108:111], v[160:163], v[214:217], v[108:111]
	v_mfma_f32_16x16x32_bf16 v[96:99], v[152:155], v[222:225], v[96:99]
	v_mfma_f32_16x16x32_bf16 v[92:95], v[160:163], v[222:225], v[92:95]
	v_mfma_f32_16x16x32_bf16 v[80:83], v[152:155], v[238:241], v[80:83]
	v_mfma_f32_16x16x32_bf16 v[76:79], v[160:163], v[238:241], v[76:79]
	v_mfma_f32_16x16x32_bf16 v[120:123], v[186:189], v[202:205], v[120:123]
	v_mfma_f32_16x16x32_bf16 v[116:119], v[194:197], v[202:205], v[116:119]
	v_mfma_f32_16x16x32_bf16 v[104:107], v[186:189], v[210:213], v[104:107]
	v_mfma_f32_16x16x32_bf16 v[100:103], v[194:197], v[210:213], v[100:103]
	v_mfma_f32_16x16x32_bf16 v[88:91], v[186:189], v[218:221], v[88:91]
	v_mfma_f32_16x16x32_bf16 v[84:87], v[194:197], v[218:221], v[84:87]
	v_mfma_f32_16x16x32_bf16 v[72:75], v[186:189], v[234:237], v[72:75]
	v_mfma_f32_16x16x32_bf16 v[68:71], v[194:197], v[234:237], v[68:71]
	v_mfma_f32_16x16x32_bf16 v[120:123], v[190:193], v[206:209], v[120:123]
	v_mfma_f32_16x16x32_bf16 v[116:119], v[198:201], v[206:209], v[116:119]
	v_mfma_f32_16x16x32_bf16 v[104:107], v[190:193], v[214:217], v[104:107]
	v_mfma_f32_16x16x32_bf16 v[100:103], v[198:201], v[214:217], v[100:103]
	v_mfma_f32_16x16x32_bf16 v[88:91], v[190:193], v[222:225], v[88:91]
	v_mfma_f32_16x16x32_bf16 v[84:87], v[198:201], v[222:225], v[84:87]
	v_mfma_f32_16x16x32_bf16 v[72:75], v[190:193], v[238:241], v[72:75]
	v_mfma_f32_16x16x32_bf16 v[68:71], v[198:201], v[238:241], v[68:71]
	s_barrier
	s_add_i32 s54, s63, s6
	s_mov_b32 m0, s54
	ds_read_b128 v[202:205], v147 offset:49152
	ds_read_b128 v[206:209], v147 offset:50176
	ds_read_b128 v[210:213], v147 offset:51200
	ds_read_b128 v[214:217], v147 offset:52224
	ds_read_b128 v[218:221], v147 offset:53248
	ds_read_b128 v[222:225], v147 offset:54272
	ds_read_b128 v[234:237], v147 offset:55296
	ds_read_b128 v[238:241], v147 offset:56320
	s_add_u32 vcc_lo, s52, 0x80
	s_addc_u32 vcc_hi, s53, 0
	global_load_lds_dwordx4 v34, vcc
	s_add_i32 m0, s54, 0x2000
	s_add_u32 s52, s52, 0x80080
	s_addc_u32 s53, s53, 0
	s_add_i32 s54, s64, s6
	s_add_u32 vcc_lo, s52, 0xfff80000
	s_addc_u32 vcc_hi, s53, -1
	global_load_lds_dwordx4 v132, vcc
	s_mov_b32 m0, s54
	s_nop 0
	global_load_lds_dwordx4 v34, s[52:53]
	s_add_i32 m0, s54, 0x2000
	s_nop 0
	global_load_lds_dwordx4 v132, s[52:53]
	s_mov_b32 m0, s24
	s_nop 0
	global_load_lds_dwordx4 v136, s[98:99]
	s_mov_b32 m0, s35
	s_nop 0
	global_load_lds_dwordx4 v134, s[98:99]
	s_waitcnt vmcnt(8)
	s_waitcnt lgkmcnt(0)
	s_barrier
	v_mfma_f32_16x16x32_bf16 v[64:67], v[148:151], v[202:205], v[64:67]
	v_mfma_f32_16x16x32_bf16 v[60:63], v[156:159], v[202:205], v[60:63]
	v_mfma_f32_16x16x32_bf16 v[48:51], v[148:151], v[210:213], v[48:51]
	v_mfma_f32_16x16x32_bf16 v[44:47], v[156:159], v[210:213], v[44:47]
	v_mfma_f32_16x16x32_bf16 v[30:33], v[148:151], v[218:221], v[30:33]
	v_mfma_f32_16x16x32_bf16 v[26:29], v[156:159], v[218:221], v[26:29]
	v_mfma_f32_16x16x32_bf16 v[14:17], v[148:151], v[234:237], v[14:17]
	v_mfma_f32_16x16x32_bf16 v[10:13], v[156:159], v[234:237], v[10:13]
	v_mfma_f32_16x16x32_bf16 v[64:67], v[152:155], v[206:209], v[64:67]
	v_mfma_f32_16x16x32_bf16 v[60:63], v[160:163], v[206:209], v[60:63]
	v_mfma_f32_16x16x32_bf16 v[48:51], v[152:155], v[214:217], v[48:51]
	v_mfma_f32_16x16x32_bf16 v[44:47], v[160:163], v[214:217], v[44:47]
	v_mfma_f32_16x16x32_bf16 v[30:33], v[152:155], v[222:225], v[30:33]
	v_mfma_f32_16x16x32_bf16 v[26:29], v[160:163], v[222:225], v[26:29]
	v_mfma_f32_16x16x32_bf16 v[14:17], v[152:155], v[238:241], v[14:17]
	v_mfma_f32_16x16x32_bf16 v[10:13], v[160:163], v[238:241], v[10:13]
	v_mfma_f32_16x16x32_bf16 v[56:59], v[186:189], v[202:205], v[56:59]
	v_mfma_f32_16x16x32_bf16 v[52:55], v[194:197], v[202:205], v[52:55]
	v_mfma_f32_16x16x32_bf16 v[40:43], v[186:189], v[210:213], v[40:43]
	v_mfma_f32_16x16x32_bf16 v[36:39], v[194:197], v[210:213], v[36:39]
	v_mfma_f32_16x16x32_bf16 v[22:25], v[186:189], v[218:221], v[22:25]
	v_mfma_f32_16x16x32_bf16 v[18:21], v[194:197], v[218:221], v[18:21]
	v_mfma_f32_16x16x32_bf16 v[6:9], v[186:189], v[234:237], v[6:9]
	v_mfma_f32_16x16x32_bf16 v[2:5], v[194:197], v[234:237], v[2:5]
	v_mfma_f32_16x16x32_bf16 v[56:59], v[190:193], v[206:209], v[56:59]
	v_mfma_f32_16x16x32_bf16 v[52:55], v[198:201], v[206:209], v[52:55]
	v_mfma_f32_16x16x32_bf16 v[40:43], v[190:193], v[214:217], v[40:43]
	v_mfma_f32_16x16x32_bf16 v[36:39], v[198:201], v[214:217], v[36:39]
	v_mfma_f32_16x16x32_bf16 v[22:25], v[190:193], v[222:225], v[22:25]
	v_mfma_f32_16x16x32_bf16 v[18:21], v[198:201], v[222:225], v[18:21]
	v_mfma_f32_16x16x32_bf16 v[6:9], v[190:193], v[238:241], v[6:9]
	v_mfma_f32_16x16x32_bf16 v[2:5], v[198:201], v[238:241], v[2:5]
	s_barrier
	s_add_i32 s62, s62, 2
	s_add_u32 s50, s50, 0x100
	s_addc_u32 s51, s51, 0
	s_add_u32 s60, s60, 0x100
	s_addc_u32 s61, s61, 0
	s_cmp_gt_u32 s62, 29
	s_cbranch_scc0 .LBB0_608
	s_and_b64 vcc, exec, s[28:29]
	s_cbranch_vccz .LBB0_611
	s_barrier

; #define PG8_STAGE(bufoff, gbase, voff) do { _Pragma("unroll") for (int _i = 0; _i < 2; ++_i) \
;         __builtin_amdgcn_global_load_lds((const unsigned*)((const char*)(gbase) + (voff)[_i]), (PG8_LAS unsigned*)(lds + (bufoff) + ldsw + _i * 8192), 16, 0, 0); } while (0)
; #define PG8_LDA(dst, b, h) do { _Pragma("unroll") for (int m = 0; m < 4; ++m) _Pragma("unroll") for (int k = 0; k < 2; ++k) dst[m][k] = *(const PG8_LAS bf16x8*)(lds + PG8_SA(b, h) + aoff + m * 2048 + k * 1024); } while (0)
; #define PG8_LDB(dst, b, h) do { _Pragma("unroll") for (int n = 0; n < 2; ++n) _Pragma("unroll") for (int k = 0; k < 2; ++k) dst[n][k] = *(const PG8_LAS bf16x8*)(lds + PG8_SB(b, h) + boff + n * 2048 + k * 1024); } while (0)
; #define PG8_WAIT_V(n) asm volatile("s_waitcnt vmcnt(" #n ")" ::: "memory")
; #define PG8_WAIT_L(n) asm volatile("s_waitcnt lgkmcnt(" #n ")" ::: "memory")
; #define PG8_BAR __builtin_amdgcn_s_barrier()
; #define PG8_SCHED __builtin_amdgcn_sched_barrier(0)
;     ...
; #pragma unroll
;     for (int a = 0; a < 2; ++a)
; #pragma unroll
;         for (int b = 0; b < 2; ++b)
; #pragma unroll
;             for (int m = 0; m < 4; ++m)
; #pragma unroll
;                 for (int n = 0; n < 2; ++n) acc[a][b][m][n] = (f32x4){0.f, 0.f, 0.f, 0.f};
;     ...
;             PG8_LDB(B0, 0, 0); PG8_LDB(B1, 0, 1); PG8_SCHED; PG8_LDA(At, 0, 0); PG8_STAGE(PG8_SA(1, 1), a1 + hstepA, voffA);
;             PG8_WAIT_V(8); PG8_WAIT_L(0); PG8_BAR; PG8_MMA(0, 0, At, B0); PG8_MMA(0, 1, At, B1); PG8_BAR; PG8_SCHED;
;             PG8_LDA(At, 0, 1); PG8_STAGE(PG8_SB(0, 0), b2, voffB); PG8_STAGE(PG8_SB(0, 1), b2 + hstepB, voffB); PG8_STAGE(PG8_SA(0, 0), a2, voffA);
;             PG8_WAIT_V(8); PG8_WAIT_L(0); PG8_BAR; PG8_MMA(1, 0, At, B0); PG8_MMA(1, 1, At, B1); PG8_BAR; PG8_SCHED;
.LBB0_693:
	s_add_u32 s64, s44, 0x100
	s_addc_u32 s65, s45, 0
	s_mov_b32 s66, -2
	v_add_u32_e32 v163, 0x10000, v143
	s_add_u32 s44, s42, 0x100
	s_addc_u32 s45, s43, 0
	s_add_i32 s67, 0, 0x10000
	s_cmpk_eq_i32 s66, 0x54
	s_cselect_b32 s53, s37, s45
	s_cselect_b32 s52, s36, s44
	s_cselect_b32 s51, s41, s65
	s_cselect_b32 s50, s40, s64
	s_add_i32 s68, 0, 0x14000
	ds_read_b128 v[146:149], v163
	ds_read_b128 v[150:153], v163 offset:1024
	ds_read_b128 v[154:157], v163 offset:2048
	ds_read_b128 v[158:161], v163 offset:3072
	ds_read_b128 v[186:189], v163 offset:16384
	ds_read_b128 v[190:193], v163 offset:17408
	ds_read_b128 v[194:197], v163 offset:18432
	ds_read_b128 v[198:201], v163 offset:19456
	s_add_i32 m0, s34, 0xc000
	ds_read_b128 v[202:205], v145
	ds_read_b128 v[206:209], v145 offset:1024
	ds_read_b128 v[210:213], v145 offset:2048
	ds_read_b128 v[214:217], v145 offset:3072
	ds_read_b128 v[218:221], v145 offset:4096
	ds_read_b128 v[222:225], v145 offset:5120
	ds_read_b128 v[234:237], v145 offset:6144
	ds_read_b128 v[238:241], v145 offset:7168
	global_load_lds_dwordx4 v138, s[42:43]
	s_add_i32 m0, s34, 0xe000
	s_nop 0
	global_load_lds_dwordx4 v140, s[42:43]
	s_waitcnt vmcnt(8)
	s_waitcnt lgkmcnt(0)
	s_barrier
	v_mfma_f32_16x16x32_bf16 v[128:131], v[146:149], v[202:205], 0
	v_mfma_f32_16x16x32_bf16 v[124:127], v[154:157], v[202:205], 0
	v_mfma_f32_16x16x32_bf16 v[120:123], v[146:149], v[210:213], 0
	v_mfma_f32_16x16x32_bf16 v[116:119], v[154:157], v[210:213], 0
	v_mfma_f32_16x16x32_bf16 v[104:107], v[146:149], v[218:221], 0
	v_mfma_f32_16x16x32_bf16 v[100:103], v[154:157], v[218:221], 0
	v_mfma_f32_16x16x32_bf16 v[88:91], v[146:149], v[234:237], 0
	v_mfma_f32_16x16x32_bf16 v[84:87], v[154:157], v[234:237], 0
	v_mfma_f32_16x16x32_bf16 v[128:131], v[150:153], v[206:209], v[128:131]
	v_mfma_f32_16x16x32_bf16 v[124:127], v[158:161], v[206:209], v[124:127]
	v_mfma_f32_16x16x32_bf16 v[120:123], v[150:153], v[214:217], v[120:123]
	v_mfma_f32_16x16x32_bf16 v[116:119], v[158:161], v[214:217], v[116:119]
	v_mfma_f32_16x16x32_bf16 v[104:107], v[150:153], v[222:225], v[104:107]
	v_mfma_f32_16x16x32_bf16 v[100:103], v[158:161], v[222:225], v[100:103]
	v_mfma_f32_16x16x32_bf16 v[88:91], v[150:153], v[238:241], v[88:91]
	v_mfma_f32_16x16x32_bf16 v[84:87], v[158:161], v[238:241], v[84:87]
	v_mfma_f32_16x16x32_bf16 v[112:115], v[186:189], v[202:205], 0
	v_mfma_f32_16x16x32_bf16 v[108:111], v[194:197], v[202:205], 0
	v_mfma_f32_16x16x32_bf16 v[96:99], v[186:189], v[210:213], 0
	v_mfma_f32_16x16x32_bf16 v[92:95], v[194:197], v[210:213], 0
	v_mfma_f32_16x16x32_bf16 v[80:83], v[186:189], v[218:221], 0
	v_mfma_f32_16x16x32_bf16 v[76:79], v[194:197], v[218:221], 0
	v_mfma_f32_16x16x32_bf16 v[72:75], v[186:189], v[234:237], 0
	v_mfma_f32_16x16x32_bf16 v[68:71], v[194:197], v[234:237], 0
	v_mfma_f32_16x16x32_bf16 v[112:115], v[190:193], v[206:209], v[112:115]
	v_mfma_f32_16x16x32_bf16 v[108:111], v[198:201], v[206:209], v[108:111]
	v_mfma_f32_16x16x32_bf16 v[96:99], v[190:193], v[214:217], v[96:99]
	v_mfma_f32_16x16x32_bf16 v[92:95], v[198:201], v[214:217], v[92:95]
	v_mfma_f32_16x16x32_bf16 v[80:83], v[190:193], v[222:225], v[80:83]
	v_mfma_f32_16x16x32_bf16 v[76:79], v[198:201], v[222:225], v[76:79]
	v_mfma_f32_16x16x32_bf16 v[72:75], v[190:193], v[238:241], v[72:75]
	v_mfma_f32_16x16x32_bf16 v[68:71], v[198:201], v[238:241], v[68:71]
	s_barrier
	s_add_i32 s42, s67, s15
	s_mov_b32 m0, s42
	ds_read_b128 v[202:205], v145 offset:16384
	ds_read_b128 v[206:209], v145 offset:17408
	ds_read_b128 v[210:213], v145 offset:18432
	ds_read_b128 v[214:217], v145 offset:19456
	ds_read_b128 v[218:221], v145 offset:20480
	ds_read_b128 v[222:225], v145 offset:21504
	ds_read_b128 v[234:237], v145 offset:22528
	ds_read_b128 v[238:241], v145 offset:23552
	global_load_lds_dwordx4 v34, s[50:51]
	s_add_i32 m0, s42, 0x2000
	s_add_u32 s42, s50, 0x160000
	s_addc_u32 s43, s51, 0
	s_add_u32 s98, s50, 0x80
	s_addc_u32 s99, s51, 0
	s_add_i32 s67, s68, s15
	global_load_lds_dwordx4 v136, s[50:51]
	s_mov_b32 m0, s67
	s_nop 0
	global_load_lds_dwordx4 v34, s[42:43]
	s_add_i32 m0, s67, 0x2000
	s_nop 0
	global_load_lds_dwordx4 v136, s[42:43]
	s_mov_b32 m0, s34
	s_nop 0
	global_load_lds_dwordx4 v132, s[52:53]
	s_mov_b32 m0, s35
	s_nop 0
	global_load_lds_dwordx4 v134, s[52:53]
	s_waitcnt vmcnt(8)
	s_waitcnt lgkmcnt(0)
	s_barrier
	v_mfma_f32_16x16x32_bf16 v[64:67], v[146:149], v[202:205], 0
	v_mfma_f32_16x16x32_bf16 v[60:63], v[154:157], v[202:205], 0
	v_mfma_f32_16x16x32_bf16 v[56:59], v[146:149], v[210:213], 0
	v_mfma_f32_16x16x32_bf16 v[52:55], v[154:157], v[210:213], 0
	v_mfma_f32_16x16x32_bf16 v[40:43], v[146:149], v[218:221], 0
	v_mfma_f32_16x16x32_bf16 v[36:39], v[154:157], v[218:221], 0
	v_mfma_f32_16x16x32_bf16 v[22:25], v[146:149], v[234:237], 0
	v_mfma_f32_16x16x32_bf16 v[18:21], v[154:157], v[234:237], 0
	v_mfma_f32_16x16x32_bf16 v[64:67], v[150:153], v[206:209], v[64:67]
	v_mfma_f32_16x16x32_bf16 v[60:63], v[158:161], v[206:209], v[60:63]
	v_mfma_f32_16x16x32_bf16 v[56:59], v[150:153], v[214:217], v[56:59]
	v_mfma_f32_16x16x32_bf16 v[52:55], v[158:161], v[214:217], v[52:55]
	v_mfma_f32_16x16x32_bf16 v[40:43], v[150:153], v[222:225], v[40:43]
	v_mfma_f32_16x16x32_bf16 v[36:39], v[158:161], v[222:225], v[36:39]
	v_mfma_f32_16x16x32_bf16 v[22:25], v[150:153], v[238:241], v[22:25]
	v_mfma_f32_16x16x32_bf16 v[18:21], v[158:161], v[238:241], v[18:21]
	v_mfma_f32_16x16x32_bf16 v[48:51], v[186:189], v[202:205], 0
	v_mfma_f32_16x16x32_bf16 v[44:47], v[194:197], v[202:205], 0
	v_mfma_f32_16x16x32_bf16 v[30:33], v[186:189], v[210:213], 0
	v_mfma_f32_16x16x32_bf16 v[26:29], v[194:197], v[210:213], 0
	v_mfma_f32_16x16x32_bf16 v[14:17], v[186:189], v[218:221], 0
	v_mfma_f32_16x16x32_bf16 v[10:13], v[194:197], v[218:221], 0
	v_mfma_f32_16x16x32_bf16 v[6:9], v[186:189], v[234:237], 0
	v_mfma_f32_16x16x32_bf16 v[2:5], v[194:197], v[234:237], 0
	v_mfma_f32_16x16x32_bf16 v[48:51], v[190:193], v[206:209], v[48:51]
	v_mfma_f32_16x16x32_bf16 v[44:47], v[198:201], v[206:209], v[44:47]
	v_mfma_f32_16x16x32_bf16 v[30:33], v[190:193], v[214:217], v[30:33]
	v_mfma_f32_16x16x32_bf16 v[26:29], v[198:201], v[214:217], v[26:29]
	v_mfma_f32_16x16x32_bf16 v[14:17], v[190:193], v[222:225], v[14:17]
	v_mfma_f32_16x16x32_bf16 v[10:13], v[198:201], v[222:225], v[10:13]
	v_mfma_f32_16x16x32_bf16 v[6:9], v[190:193], v[238:241], v[6:9]
	v_mfma_f32_16x16x32_bf16 v[2:5], v[198:201], v[238:241], v[2:5]
	s_barrier
	s_branch .Lpeel_mid_694
	.p2align	6

; #define PG8_STAGE(bufoff, gbase, voff) do { _Pragma("unroll") for (int _i = 0; _i < 2; ++_i) \
;         __builtin_amdgcn_global_load_lds((const unsigned*)((const char*)(gbase) + (voff)[_i]), (PG8_LAS unsigned*)(lds + (bufoff) + ldsw + _i * 8192), 16, 0, 0); } while (0)
; #define PG8_LDA(dst, b, h) do { _Pragma("unroll") for (int m = 0; m < 4; ++m) _Pragma("unroll") for (int k = 0; k < 2; ++k) dst[m][k] = *(const PG8_LAS bf16x8*)(lds + PG8_SA(b, h) + aoff + m * 2048 + k * 1024); } while (0)
; #define PG8_LDB(dst, b, h) do { _Pragma("unroll") for (int n = 0; n < 2; ++n) _Pragma("unroll") for (int k = 0; k < 2; ++k) dst[n][k] = *(const PG8_LAS bf16x8*)(lds + PG8_SB(b, h) + boff + n * 2048 + k * 1024); } while (0)
; #define PG8_WAIT_V(n) asm volatile("s_waitcnt vmcnt(" #n ")" ::: "memory")
; #define PG8_WAIT_L(n) asm volatile("s_waitcnt lgkmcnt(" #n ")" ::: "memory")
; #define PG8_BAR __builtin_amdgcn_s_barrier()
; #define PG8_SCHED __builtin_amdgcn_sched_barrier(0)
;     ...
;             PG8_LDB(B0, 1, 0); PG8_LDB(B1, 1, 1); PG8_SCHED; PG8_LDA(At, 1, 0); PG8_STAGE(PG8_SA(0, 1), a2 + hstepA, voffA);
;             PG8_WAIT_V(8); PG8_WAIT_L(0); PG8_BAR; PG8_MMA(0, 0, At, B0); PG8_MMA(0, 1, At, B1); PG8_BAR; PG8_SCHED;
;             PG8_LDA(At, 1, 1); PG8_STAGE(PG8_SB(1, 0), b3, voffB); PG8_STAGE(PG8_SB(1, 1), b3 + hstepB, voffB); PG8_STAGE(PG8_SA(1, 0), a3, voffA);
;             PG8_WAIT_V(8); PG8_WAIT_L(0); PG8_BAR; PG8_MMA(1, 0, At, B0); PG8_MMA(1, 1, At, B1); PG8_BAR; PG8_SCHED;
.Lpeel_mid_694:
	s_add_i32 s67, 0, 0x18000
	s_add_i32 s68, 0, 0x1c000
	ds_read_b128 v[146:149], v163 offset:32768
	ds_read_b128 v[150:153], v163 offset:33792
	ds_read_b128 v[154:157], v163 offset:34816
	ds_read_b128 v[158:161], v163 offset:35840
	ds_read_b128 v[186:189], v163 offset:49152
	ds_read_b128 v[190:193], v163 offset:50176
	ds_read_b128 v[194:197], v163 offset:51200
	ds_read_b128 v[198:201], v163 offset:52224
	s_add_u32 s42, s52, 0x160000
	s_addc_u32 s43, s53, 0
	s_mov_b32 m0, s54
	ds_read_b128 v[202:205], v145 offset:32768
	ds_read_b128 v[206:209], v145 offset:33792
	ds_read_b128 v[210:213], v145 offset:34816
	ds_read_b128 v[214:217], v145 offset:35840
	ds_read_b128 v[218:221], v145 offset:36864
	ds_read_b128 v[222:225], v145 offset:37888
	ds_read_b128 v[234:237], v145 offset:38912
	ds_read_b128 v[238:241], v145 offset:39936
	global_load_lds_dwordx4 v132, s[42:43]
	s_mov_b32 m0, s55
	s_nop 0
	global_load_lds_dwordx4 v134, s[42:43]
	s_waitcnt vmcnt(8)
	s_waitcnt lgkmcnt(0)
	s_barrier
	v_mfma_f32_16x16x32_bf16 v[128:131], v[146:149], v[202:205], v[128:131]
	v_mfma_f32_16x16x32_bf16 v[124:127], v[154:157], v[202:205], v[124:127]
	v_mfma_f32_16x16x32_bf16 v[120:123], v[146:149], v[210:213], v[120:123]
	v_mfma_f32_16x16x32_bf16 v[116:119], v[154:157], v[210:213], v[116:119]
	v_mfma_f32_16x16x32_bf16 v[104:107], v[146:149], v[218:221], v[104:107]
	v_mfma_f32_16x16x32_bf16 v[100:103], v[154:157], v[218:221], v[100:103]
	v_mfma_f32_16x16x32_bf16 v[88:91], v[146:149], v[234:237], v[88:91]
	v_mfma_f32_16x16x32_bf16 v[84:87], v[154:157], v[234:237], v[84:87]
	v_mfma_f32_16x16x32_bf16 v[128:131], v[150:153], v[206:209], v[128:131]
	v_mfma_f32_16x16x32_bf16 v[124:127], v[158:161], v[206:209], v[124:127]
	v_mfma_f32_16x16x32_bf16 v[120:123], v[150:153], v[214:217], v[120:123]
	v_mfma_f32_16x16x32_bf16 v[116:119], v[158:161], v[214:217], v[116:119]
	v_mfma_f32_16x16x32_bf16 v[104:107], v[150:153], v[222:225], v[104:107]
	v_mfma_f32_16x16x32_bf16 v[100:103], v[158:161], v[222:225], v[100:103]
	v_mfma_f32_16x16x32_bf16 v[88:91], v[150:153], v[238:241], v[88:91]
	v_mfma_f32_16x16x32_bf16 v[84:87], v[158:161], v[238:241], v[84:87]
	v_mfma_f32_16x16x32_bf16 v[112:115], v[186:189], v[202:205], v[112:115]
	v_mfma_f32_16x16x32_bf16 v[108:111], v[194:197], v[202:205], v[108:111]
	v_mfma_f32_16x16x32_bf16 v[96:99], v[186:189], v[210:213], v[96:99]
	v_mfma_f32_16x16x32_bf16 v[92:95], v[194:197], v[210:213], v[92:95]
	v_mfma_f32_16x16x32_bf16 v[80:83], v[186:189], v[218:221], v[80:83]
	v_mfma_f32_16x16x32_bf16 v[76:79], v[194:197], v[218:221], v[76:79]
	v_mfma_f32_16x16x32_bf16 v[72:75], v[186:189], v[234:237], v[72:75]
	v_mfma_f32_16x16x32_bf16 v[68:71], v[194:197], v[234:237], v[68:71]
	v_mfma_f32_16x16x32_bf16 v[112:115], v[190:193], v[206:209], v[112:115]
	v_mfma_f32_16x16x32_bf16 v[108:111], v[198:201], v[206:209], v[108:111]
	v_mfma_f32_16x16x32_bf16 v[96:99], v[190:193], v[214:217], v[96:99]
	v_mfma_f32_16x16x32_bf16 v[92:95], v[198:201], v[214:217], v[92:95]
	v_mfma_f32_16x16x32_bf16 v[80:83], v[190:193], v[222:225], v[80:83]
	v_mfma_f32_16x16x32_bf16 v[76:79], v[198:201], v[222:225], v[76:79]
	v_mfma_f32_16x16x32_bf16 v[72:75], v[190:193], v[238:241], v[72:75]
	v_mfma_f32_16x16x32_bf16 v[68:71], v[198:201], v[238:241], v[68:71]
	s_barrier
	s_add_i32 s42, s67, s15
	s_mov_b32 m0, s42
	ds_read_b128 v[202:205], v145 offset:49152
	ds_read_b128 v[206:209], v145 offset:50176
	ds_read_b128 v[210:213], v145 offset:51200
	ds_read_b128 v[214:217], v145 offset:52224
	ds_read_b128 v[218:221], v145 offset:53248
	ds_read_b128 v[222:225], v145 offset:54272
	ds_read_b128 v[234:237], v145 offset:55296
	ds_read_b128 v[238:241], v145 offset:56320
	s_add_u32 vcc_lo, s50, 0x80
	s_addc_u32 vcc_hi, s51, 0
	global_load_lds_dwordx4 v34, vcc
	s_add_i32 m0, s42, 0x2000
	s_add_u32 s42, s50, 0x160080
	s_addc_u32 s43, s51, 0
	s_add_i32 s50, s68, s15
	global_load_lds_dwordx4 v136, s[98:99]
	s_mov_b32 m0, s50
	s_nop 0
	global_load_lds_dwordx4 v34, s[42:43]
	s_add_i32 m0, s50, 0x2000
	s_nop 0
	global_load_lds_dwordx4 v136, s[42:43]
	s_mov_b32 m0, s56
	s_nop 0
	s_add_u32 vcc_lo, s52, 0x80
	s_addc_u32 vcc_hi, s53, 0
	global_load_lds_dwordx4 v132, vcc
	s_mov_b32 m0, s57
	s_nop 0
	s_add_u32 vcc_lo, s52, 0x80
	s_addc_u32 vcc_hi, s53, 0
	global_load_lds_dwordx4 v134, vcc
	s_waitcnt vmcnt(8)
	s_waitcnt lgkmcnt(0)
	s_barrier
	v_mfma_f32_16x16x32_bf16 v[64:67], v[146:149], v[202:205], v[64:67]
	v_mfma_f32_16x16x32_bf16 v[60:63], v[154:157], v[202:205], v[60:63]
	v_mfma_f32_16x16x32_bf16 v[56:59], v[146:149], v[210:213], v[56:59]
	v_mfma_f32_16x16x32_bf16 v[52:55], v[154:157], v[210:213], v[52:55]
	v_mfma_f32_16x16x32_bf16 v[40:43], v[146:149], v[218:221], v[40:43]
	v_mfma_f32_16x16x32_bf16 v[36:39], v[154:157], v[218:221], v[36:39]
	v_mfma_f32_16x16x32_bf16 v[22:25], v[146:149], v[234:237], v[22:25]
	v_mfma_f32_16x16x32_bf16 v[18:21], v[154:157], v[234:237], v[18:21]
	v_mfma_f32_16x16x32_bf16 v[64:67], v[150:153], v[206:209], v[64:67]
	v_mfma_f32_16x16x32_bf16 v[60:63], v[158:161], v[206:209], v[60:63]
	v_mfma_f32_16x16x32_bf16 v[56:59], v[150:153], v[214:217], v[56:59]
	v_mfma_f32_16x16x32_bf16 v[52:55], v[158:161], v[214:217], v[52:55]
	v_mfma_f32_16x16x32_bf16 v[40:43], v[150:153], v[222:225], v[40:43]
	v_mfma_f32_16x16x32_bf16 v[36:39], v[158:161], v[222:225], v[36:39]
	v_mfma_f32_16x16x32_bf16 v[22:25], v[150:153], v[238:241], v[22:25]
	v_mfma_f32_16x16x32_bf16 v[18:21], v[158:161], v[238:241], v[18:21]
	v_mfma_f32_16x16x32_bf16 v[48:51], v[186:189], v[202:205], v[48:51]
	v_mfma_f32_16x16x32_bf16 v[44:47], v[194:197], v[202:205], v[44:47]
	v_mfma_f32_16x16x32_bf16 v[30:33], v[186:189], v[210:213], v[30:33]
	v_mfma_f32_16x16x32_bf16 v[26:29], v[194:197], v[210:213], v[26:29]
	v_mfma_f32_16x16x32_bf16 v[14:17], v[186:189], v[218:221], v[14:17]
	v_mfma_f32_16x16x32_bf16 v[10:13], v[194:197], v[218:221], v[10:13]
	v_mfma_f32_16x16x32_bf16 v[6:9], v[186:189], v[234:237], v[6:9]
	v_mfma_f32_16x16x32_bf16 v[2:5], v[194:197], v[234:237], v[2:5]
	v_mfma_f32_16x16x32_bf16 v[48:51], v[190:193], v[206:209], v[48:51]
	v_mfma_f32_16x16x32_bf16 v[44:47], v[198:201], v[206:209], v[44:47]
	v_mfma_f32_16x16x32_bf16 v[30:33], v[190:193], v[214:217], v[30:33]
	v_mfma_f32_16x16x32_bf16 v[26:29], v[198:201], v[214:217], v[26:29]
	v_mfma_f32_16x16x32_bf16 v[14:17], v[190:193], v[222:225], v[14:17]
	v_mfma_f32_16x16x32_bf16 v[10:13], v[198:201], v[222:225], v[10:13]
	v_mfma_f32_16x16x32_bf16 v[6:9], v[190:193], v[238:241], v[6:9]
	v_mfma_f32_16x16x32_bf16 v[2:5], v[198:201], v[238:241], v[2:5]
	s_barrier
	s_add_i32 s66, s66, 2
	s_add_u32 s64, s64, 0x100
	s_addc_u32 s65, s65, 0
	s_cmpk_gt_u32 s66, 0x55
	s_mov_b64 s[42:43], s[44:45]
	s_cbranch_scc0 .LBB0_694
	s_and_b64 vcc, exec, s[30:31]
	s_cbranch_vccz .LBB0_697
	s_barrier

; #define PG8_STAGE(bufoff, gbase, voff) do { _Pragma("unroll") for (int _i = 0; _i < 2; ++_i) \
;         __builtin_amdgcn_global_load_lds((const unsigned*)((const char*)(gbase) + (voff)[_i]), (PG8_LAS unsigned*)(lds + (bufoff) + ldsw + _i * 8192), 16, 0, 0); } while (0)
; #define PG8_LDA(dst, b, h) do { _Pragma("unroll") for (int m = 0; m < 4; ++m) _Pragma("unroll") for (int k = 0; k < 2; ++k) dst[m][k] = *(const PG8_LAS bf16x8*)(lds + PG8_SA(b, h) + aoff + m * 2048 + k * 1024); } while (0)
; #define PG8_LDB(dst, b, h) do { _Pragma("unroll") for (int n = 0; n < 2; ++n) _Pragma("unroll") for (int k = 0; k < 2; ++k) dst[n][k] = *(const PG8_LAS bf16x8*)(lds + PG8_SB(b, h) + boff + n * 2048 + k * 1024); } while (0)
; #define PG8_WAIT_V(n) asm volatile("s_waitcnt vmcnt(" #n ")" ::: "memory")
; #define PG8_WAIT_L(n) asm volatile("s_waitcnt lgkmcnt(" #n ")" ::: "memory")
; #define PG8_BAR __builtin_amdgcn_s_barrier()
; #define PG8_SCHED __builtin_amdgcn_sched_barrier(0)
;     ...
; #pragma unroll
;     for (int a = 0; a < 2; ++a)
; #pragma unroll
;         for (int b = 0; b < 2; ++b)
; #pragma unroll
;             for (int m = 0; m < 4; ++m)
; #pragma unroll
;                 for (int n = 0; n < 2; ++n) acc[a][b][m][n] = (f32x4){0.f, 0.f, 0.f, 0.f};
;     ...
;             PG8_LDB(B0, 0, 0); PG8_LDB(B1, 0, 1); PG8_SCHED; PG8_LDA(At, 0, 0); PG8_STAGE(PG8_SA(1, 1), a1 + hstepA, voffA);
;             PG8_WAIT_V(8); PG8_WAIT_L(0); PG8_BAR; PG8_MMA(0, 0, At, B0); PG8_MMA(0, 1, At, B1); PG8_BAR; PG8_SCHED;
;             PG8_LDA(At, 0, 1); PG8_STAGE(PG8_SB(0, 0), b2, voffB); PG8_STAGE(PG8_SB(0, 1), b2 + hstepB, voffB); PG8_STAGE(PG8_SA(0, 0), a2, voffA);
;             PG8_WAIT_V(8); PG8_WAIT_L(0); PG8_BAR; PG8_MMA(1, 0, At, B0); PG8_MMA(1, 1, At, B1); PG8_BAR; PG8_SCHED;
.LBB0_725:
	s_add_u32 s61, s44, 0x100
	s_addc_u32 s62, s45, 0
	s_mov_b32 s63, -2
	v_add_u32_e32 v250, 0x10000, v209
	s_add_u32 s40, s42, 0x100
	s_addc_u32 s41, s43, 0
	s_add_i32 s64, 0, 0x10000
	s_cmp_eq_u32 s63, 40
	s_cselect_b32 s51, s31, s41
	s_cselect_b32 s50, s30, s40
	s_cselect_b32 s45, s37, s62
	s_cselect_b32 s44, s36, s61
	s_add_i32 s65, 0, 0x14000
	ds_read_b128 v[26:29], v250
	ds_read_b128 v[30:33], v250 offset:1024
	ds_read_b128 v[18:21], v250 offset:2048
	ds_read_b128 v[22:25], v250 offset:3072
	ds_read_b128 v[10:13], v250 offset:16384
	ds_read_b128 v[14:17], v250 offset:17408
	ds_read_b128 v[2:5], v250 offset:18432
	ds_read_b128 v[6:9], v250 offset:19456
	s_add_i32 m0, s21, 0xc000
	ds_read_b128 v[200:203], v211
	ds_read_b128 v[204:207], v211 offset:1024
	ds_read_b128 v[212:215], v211 offset:2048
	ds_read_b128 v[216:219], v211 offset:3072
	ds_read_b128 v[220:223], v211 offset:4096
	ds_read_b128 v[224:227], v211 offset:5120
	ds_read_b128 v[234:237], v211 offset:6144
	ds_read_b128 v[238:241], v211 offset:7168
	global_load_lds_dwordx4 v196, s[42:43]
	s_add_i32 m0, s21, 0xe000
	s_nop 0
	global_load_lds_dwordx4 v198, s[42:43]
	s_waitcnt vmcnt(8)
	s_waitcnt lgkmcnt(0)
	s_barrier
	v_mfma_f32_16x16x128_f8f6f4 v[160:163], v[26:33], v[200:207], 0
	v_mfma_f32_16x16x128_f8f6f4 v[156:159], v[18:25], v[200:207], 0
	v_mfma_f32_16x16x128_f8f6f4 v[152:155], v[26:33], v[212:219], 0
	v_mfma_f32_16x16x128_f8f6f4 v[144:147], v[18:25], v[212:219], 0
	v_mfma_f32_16x16x128_f8f6f4 v[136:139], v[26:33], v[220:227], 0
	v_mfma_f32_16x16x128_f8f6f4 v[128:131], v[18:25], v[220:227], 0
	v_mfma_f32_16x16x128_f8f6f4 v[120:123], v[26:33], v[234:241], 0
	v_mfma_f32_16x16x128_f8f6f4 v[112:115], v[18:25], v[234:241], 0
	v_mfma_f32_16x16x128_f8f6f4 v[148:151], v[10:17], v[200:207], 0
	v_mfma_f32_16x16x128_f8f6f4 v[140:143], v[2:9], v[200:207], 0
	v_mfma_f32_16x16x128_f8f6f4 v[132:135], v[10:17], v[212:219], 0
	v_mfma_f32_16x16x128_f8f6f4 v[124:127], v[2:9], v[212:219], 0
	v_mfma_f32_16x16x128_f8f6f4 v[116:119], v[10:17], v[220:227], 0
	v_mfma_f32_16x16x128_f8f6f4 v[108:111], v[2:9], v[220:227], 0
	v_mfma_f32_16x16x128_f8f6f4 v[104:107], v[10:17], v[234:241], 0
	v_mfma_f32_16x16x128_f8f6f4 v[100:103], v[2:9], v[234:241], 0
	s_barrier
	s_add_i32 s42, s64, s15
	s_mov_b32 m0, s42
	ds_read_b128 v[212:215], v211 offset:16384
	ds_read_b128 v[216:219], v211 offset:17408
	ds_read_b128 v[220:223], v211 offset:18432
	ds_read_b128 v[224:227], v211 offset:19456
	ds_read_b128 v[234:237], v211 offset:20480
	ds_read_b128 v[238:241], v211 offset:21504
	ds_read_b128 v[242:245], v211 offset:22528
	ds_read_b128 v[246:249], v211 offset:23552
	global_load_lds_dwordx4 v34, s[44:45]
	s_add_i32 m0, s42, 0x2000
	s_add_u32 s42, s44, 0xb0000
	s_addc_u32 s43, s45, 0
	s_add_u32 s98, s44, 0x80
	s_addc_u32 s99, s45, 0
	s_add_i32 s64, s65, s15
	global_load_lds_dwordx4 v190, s[44:45]
	s_mov_b32 m0, s64
	s_nop 0
	global_load_lds_dwordx4 v34, s[42:43]
	s_add_i32 m0, s64, 0x2000
	s_nop 0
	global_load_lds_dwordx4 v190, s[42:43]
	s_mov_b32 m0, s21
	s_nop 0
	global_load_lds_dwordx4 v186, s[50:51]
	s_mov_b32 m0, s34
	s_nop 0
	global_load_lds_dwordx4 v188, s[50:51]
	s_waitcnt vmcnt(8)
	s_waitcnt lgkmcnt(0)
	s_barrier
	v_mfma_f32_16x16x128_f8f6f4 v[96:99], v[26:33], v[212:219], 0
	v_mfma_f32_16x16x128_f8f6f4 v[92:95], v[18:25], v[212:219], 0
	v_mfma_f32_16x16x128_f8f6f4 v[88:91], v[26:33], v[220:227], 0
	v_mfma_f32_16x16x128_f8f6f4 v[80:83], v[18:25], v[220:227], 0
	v_mfma_f32_16x16x128_f8f6f4 v[72:75], v[26:33], v[234:241], 0
	v_mfma_f32_16x16x128_f8f6f4 v[64:67], v[18:25], v[234:241], 0
	v_mfma_f32_16x16x128_f8f6f4 v[56:59], v[26:33], v[242:249], 0
	v_mfma_f32_16x16x128_f8f6f4 v[48:51], v[18:25], v[242:249], 0
	v_mfma_f32_16x16x128_f8f6f4 v[84:87], v[10:17], v[212:219], 0
	v_mfma_f32_16x16x128_f8f6f4 v[76:79], v[2:9], v[212:219], 0
	v_mfma_f32_16x16x128_f8f6f4 v[68:71], v[10:17], v[220:227], 0
	v_mfma_f32_16x16x128_f8f6f4 v[60:63], v[2:9], v[220:227], 0
	v_mfma_f32_16x16x128_f8f6f4 v[52:55], v[10:17], v[234:241], 0
	v_mfma_f32_16x16x128_f8f6f4 v[44:47], v[2:9], v[234:241], 0
	v_mfma_f32_16x16x128_f8f6f4 v[40:43], v[10:17], v[242:249], 0
	v_mfma_f32_16x16x128_f8f6f4 v[36:39], v[2:9], v[242:249], 0
	s_barrier
	s_branch .Lpeel_mid_726
	.p2align	6

; #define PG8_STAGE(bufoff, gbase, voff) do { _Pragma("unroll") for (int _i = 0; _i < 2; ++_i) \
;         __builtin_amdgcn_global_load_lds((const unsigned*)((const char*)(gbase) + (voff)[_i]), (PG8_LAS unsigned*)(lds + (bufoff) + ldsw + _i * 8192), 16, 0, 0); } while (0)
; #define PG8_LDA(dst, b, h) do { _Pragma("unroll") for (int m = 0; m < 4; ++m) _Pragma("unroll") for (int k = 0; k < 2; ++k) dst[m][k] = *(const PG8_LAS bf16x8*)(lds + PG8_SA(b, h) + aoff + m * 2048 + k * 1024); } while (0)
; #define PG8_LDB(dst, b, h) do { _Pragma("unroll") for (int n = 0; n < 2; ++n) _Pragma("unroll") for (int k = 0; k < 2; ++k) dst[n][k] = *(const PG8_LAS bf16x8*)(lds + PG8_SB(b, h) + boff + n * 2048 + k * 1024); } while (0)
; #define PG8_WAIT_V(n) asm volatile("s_waitcnt vmcnt(" #n ")" ::: "memory")
; #define PG8_WAIT_L(n) asm volatile("s_waitcnt lgkmcnt(" #n ")" ::: "memory")
; #define PG8_BAR __builtin_amdgcn_s_barrier()
; #define PG8_SCHED __builtin_amdgcn_sched_barrier(0)
;     ...
;             PG8_LDB(B0, 1, 0); PG8_LDB(B1, 1, 1); PG8_SCHED; PG8_LDA(At, 1, 0); PG8_STAGE(PG8_SA(0, 1), a2 + hstepA, voffA);
;             PG8_WAIT_V(8); PG8_WAIT_L(0); PG8_BAR; PG8_MMA(0, 0, At, B0); PG8_MMA(0, 1, At, B1); PG8_BAR; PG8_SCHED;
;             PG8_LDA(At, 1, 1); PG8_STAGE(PG8_SB(1, 0), b3, voffB); PG8_STAGE(PG8_SB(1, 1), b3 + hstepB, voffB); PG8_STAGE(PG8_SA(1, 0), a3, voffA);
;             PG8_WAIT_V(8); PG8_WAIT_L(0); PG8_BAR; PG8_MMA(1, 0, At, B0); PG8_MMA(1, 1, At, B1); PG8_BAR; PG8_SCHED;
.Lpeel_mid_726:
	s_add_i32 s64, 0, 0x18000
	s_add_i32 s65, 0, 0x1c000
	ds_read_b128 v[2:5], v250 offset:32768
	ds_read_b128 v[6:9], v250 offset:33792
	ds_read_b128 v[10:13], v250 offset:34816
	ds_read_b128 v[14:17], v250 offset:35840
	ds_read_b128 v[18:21], v250 offset:49152
	ds_read_b128 v[22:25], v250 offset:50176
	ds_read_b128 v[26:29], v250 offset:51200
	ds_read_b128 v[30:33], v250 offset:52224
	s_add_u32 s42, s50, 0xb0000
	s_addc_u32 s43, s51, 0
	s_mov_b32 m0, s35
	ds_read_b128 v[212:215], v211 offset:32768
	ds_read_b128 v[216:219], v211 offset:33792
	ds_read_b128 v[220:223], v211 offset:34816
	ds_read_b128 v[224:227], v211 offset:35840
	ds_read_b128 v[234:237], v211 offset:36864
	ds_read_b128 v[238:241], v211 offset:37888
	ds_read_b128 v[242:245], v211 offset:38912
	ds_read_b128 v[246:249], v211 offset:39936
	global_load_lds_dwordx4 v186, s[42:43]
	s_mov_b32 m0, s52
	s_nop 0
	global_load_lds_dwordx4 v188, s[42:43]
	s_waitcnt vmcnt(8)
	s_waitcnt lgkmcnt(0)
	s_barrier
	v_mfma_f32_16x16x128_f8f6f4 v[160:163], v[2:9], v[212:219], v[160:163]
	v_mfma_f32_16x16x128_f8f6f4 v[156:159], v[10:17], v[212:219], v[156:159]
	v_mfma_f32_16x16x128_f8f6f4 v[152:155], v[2:9], v[220:227], v[152:155]
	v_mfma_f32_16x16x128_f8f6f4 v[144:147], v[10:17], v[220:227], v[144:147]
	v_mfma_f32_16x16x128_f8f6f4 v[136:139], v[2:9], v[234:241], v[136:139]
	v_mfma_f32_16x16x128_f8f6f4 v[128:131], v[10:17], v[234:241], v[128:131]
	v_mfma_f32_16x16x128_f8f6f4 v[120:123], v[2:9], v[242:249], v[120:123]
	v_mfma_f32_16x16x128_f8f6f4 v[112:115], v[10:17], v[242:249], v[112:115]
	v_mfma_f32_16x16x128_f8f6f4 v[148:151], v[18:25], v[212:219], v[148:151]
	v_mfma_f32_16x16x128_f8f6f4 v[140:143], v[26:33], v[212:219], v[140:143]
	v_mfma_f32_16x16x128_f8f6f4 v[132:135], v[18:25], v[220:227], v[132:135]
	v_mfma_f32_16x16x128_f8f6f4 v[124:127], v[26:33], v[220:227], v[124:127]
	v_mfma_f32_16x16x128_f8f6f4 v[116:119], v[18:25], v[234:241], v[116:119]
	v_mfma_f32_16x16x128_f8f6f4 v[108:111], v[26:33], v[234:241], v[108:111]
	v_mfma_f32_16x16x128_f8f6f4 v[104:107], v[18:25], v[242:249], v[104:107]
	v_mfma_f32_16x16x128_f8f6f4 v[100:103], v[26:33], v[242:249], v[100:103]
	s_barrier
	s_add_i32 s42, s64, s15
	s_mov_b32 m0, s42
	ds_read_b128 v[212:215], v211 offset:49152
	ds_read_b128 v[216:219], v211 offset:50176
	ds_read_b128 v[220:223], v211 offset:51200
	ds_read_b128 v[224:227], v211 offset:52224
	ds_read_b128 v[234:237], v211 offset:53248
	ds_read_b128 v[238:241], v211 offset:54272
	ds_read_b128 v[242:245], v211 offset:55296
	ds_read_b128 v[246:249], v211 offset:56320
	s_add_u32 vcc_lo, s44, 0x80
	s_addc_u32 vcc_hi, s45, 0
	global_load_lds_dwordx4 v34, vcc
	s_add_i32 m0, s42, 0x2000
	s_add_u32 s42, s44, 0xb0080
	s_addc_u32 s43, s45, 0
	s_add_i32 s44, s65, s15
	global_load_lds_dwordx4 v190, s[98:99]
	s_mov_b32 m0, s44
	s_nop 0
	global_load_lds_dwordx4 v34, s[42:43]
	s_add_i32 m0, s44, 0x2000
	s_nop 0
	global_load_lds_dwordx4 v190, s[42:43]
	s_mov_b32 m0, s53
	s_nop 0
	s_add_u32 vcc_lo, s50, 0x80
	s_addc_u32 vcc_hi, s51, 0
	global_load_lds_dwordx4 v186, vcc
	s_mov_b32 m0, s54
	s_nop 0
	s_add_u32 vcc_lo, s50, 0x80
	s_addc_u32 vcc_hi, s51, 0
	global_load_lds_dwordx4 v188, vcc
	s_waitcnt vmcnt(8)
	s_waitcnt lgkmcnt(0)
	s_barrier
	v_mfma_f32_16x16x128_f8f6f4 v[96:99], v[2:9], v[212:219], v[96:99]
	v_mfma_f32_16x16x128_f8f6f4 v[92:95], v[10:17], v[212:219], v[92:95]
	v_mfma_f32_16x16x128_f8f6f4 v[88:91], v[2:9], v[220:227], v[88:91]
	v_mfma_f32_16x16x128_f8f6f4 v[80:83], v[10:17], v[220:227], v[80:83]
	v_mfma_f32_16x16x128_f8f6f4 v[72:75], v[2:9], v[234:241], v[72:75]
	v_mfma_f32_16x16x128_f8f6f4 v[64:67], v[10:17], v[234:241], v[64:67]
	v_mfma_f32_16x16x128_f8f6f4 v[56:59], v[2:9], v[242:249], v[56:59]
	v_mfma_f32_16x16x128_f8f6f4 v[48:51], v[10:17], v[242:249], v[48:51]
	v_mfma_f32_16x16x128_f8f6f4 v[84:87], v[18:25], v[212:219], v[84:87]
	v_mfma_f32_16x16x128_f8f6f4 v[76:79], v[26:33], v[212:219], v[76:79]
	v_mfma_f32_16x16x128_f8f6f4 v[68:71], v[18:25], v[220:227], v[68:71]
	v_mfma_f32_16x16x128_f8f6f4 v[60:63], v[26:33], v[220:227], v[60:63]
	v_mfma_f32_16x16x128_f8f6f4 v[52:55], v[18:25], v[234:241], v[52:55]
	v_mfma_f32_16x16x128_f8f6f4 v[44:47], v[26:33], v[234:241], v[44:47]
	v_mfma_f32_16x16x128_f8f6f4 v[40:43], v[18:25], v[242:249], v[40:43]
	v_mfma_f32_16x16x128_f8f6f4 v[36:39], v[26:33], v[242:249], v[36:39]
	s_barrier
	s_add_i32 s63, s63, 2
	s_add_u32 s61, s61, 0x100
	s_addc_u32 s62, s62, 0
	s_cmp_gt_u32 s63, 41
	s_mov_b64 s[42:43], s[40:41]
	s_cbranch_scc0 .LBB0_726
	s_and_b64 vcc, exec, s[28:29]
	s_cbranch_vccz .LBB0_729
	s_barrier

; #define PG8_STAGE(bufoff, gbase, voff) do { _Pragma("unroll") for (int _i = 0; _i < 2; ++_i) \
;         __builtin_amdgcn_global_load_lds((const unsigned*)((const char*)(gbase) + (voff)[_i]), (PG8_LAS unsigned*)(lds + (bufoff) + ldsw + _i * 8192), 16, 0, 0); } while (0)
; #define PG8_LDA(dst, b, h) do { _Pragma("unroll") for (int m = 0; m < 4; ++m) _Pragma("unroll") for (int k = 0; k < 2; ++k) dst[m][k] = *(const PG8_LAS bf16x8*)(lds + PG8_SA(b, h) + aoff + m * 2048 + k * 1024); } while (0)
; #define PG8_LDB(dst, b, h) do { _Pragma("unroll") for (int n = 0; n < 2; ++n) _Pragma("unroll") for (int k = 0; k < 2; ++k) dst[n][k] = *(const PG8_LAS bf16x8*)(lds + PG8_SB(b, h) + boff + n * 2048 + k * 1024); } while (0)
; #define PG8_WAIT_V(n) asm volatile("s_waitcnt vmcnt(" #n ")" ::: "memory")
; #define PG8_WAIT_L(n) asm volatile("s_waitcnt lgkmcnt(" #n ")" ::: "memory")
; #define PG8_BAR __builtin_amdgcn_s_barrier()
; #define PG8_SCHED __builtin_amdgcn_sched_barrier(0)
;     ...
; #pragma unroll
;     for (int a = 0; a < 2; ++a)
; #pragma unroll
;         for (int b = 0; b < 2; ++b)
; #pragma unroll
;             for (int m = 0; m < 4; ++m)
; #pragma unroll
;                 for (int n = 0; n < 2; ++n) acc[a][b][m][n] = (f32x4){0.f, 0.f, 0.f, 0.f};
;     ...
;             PG8_LDB(B0, 0, 0); PG8_LDB(B1, 0, 1); PG8_SCHED; PG8_LDA(At, 0, 0); PG8_STAGE(PG8_SA(1, 1), a1 + hstepA, voffA);
;             PG8_WAIT_V(8); PG8_WAIT_L(0); PG8_BAR; PG8_MMA(0, 0, At, B0); PG8_MMA(0, 1, At, B1); PG8_BAR; PG8_SCHED;
;             PG8_LDA(At, 0, 1); PG8_STAGE(PG8_SB(0, 0), b2, voffB); PG8_STAGE(PG8_SB(0, 1), b2 + hstepB, voffB); PG8_STAGE(PG8_SA(0, 0), a2, voffA);
;             PG8_WAIT_V(8); PG8_WAIT_L(0); PG8_BAR; PG8_MMA(1, 0, At, B0); PG8_MMA(1, 1, At, B1); PG8_BAR; PG8_SCHED;
.LBB0_922:
	s_ashr_i32 s47, s46, 31
	s_lshl_b64 s[34:35], s[46:47], 20
	s_add_u32 s48, s60, s34
	s_addc_u32 s49, s61, s35
	s_and_b64 s[34:35], s[38:39], exec
	s_cselect_b32 s6, s49, s53
	s_cselect_b32 s15, s48, s52
	s_ashr_i32 s37, s36, 31
	s_lshl_b64 s[34:35], s[36:37], 20
	s_add_u32 s50, s62, s34
	s_addc_u32 s51, s63, s35
	s_and_b64 s[34:35], s[38:39], exec
	s_cselect_b32 s34, s51, s57
	s_cselect_b32 s35, s50, s56
	s_add_u32 s52, s52, 0x80080
	s_addc_u32 s53, s53, 0
	s_add_u32 s37, s56, 0x100
	s_addc_u32 s41, s57, 0
	s_mov_b32 s47, -2
	v_add_u32_e32 v226, 0x10000, v153
	s_add_u32 s56, s52, 0xfff80080
	s_addc_u32 s57, s53, -1
	s_add_i32 s68, 0, 0x10000
	s_cmp_eq_u32 s47, 28
	s_cselect_b32 s59, s6, s57
	s_cselect_b32 s58, s15, s56
	s_cselect_b32 s57, s34, s41
	s_cselect_b32 s56, s35, s37
	s_add_i32 s76, 0, 0x14000
	s_waitcnt vmcnt(0)
	ds_read_b128 v[132:135], v226
	ds_read_b128 v[136:139], v226 offset:1024
	ds_read_b128 v[156:159], v226 offset:2048
	ds_read_b128 v[160:163], v226 offset:3072
	ds_read_b128 v[186:189], v226 offset:16384
	ds_read_b128 v[190:193], v226 offset:17408
	ds_read_b128 v[194:197], v226 offset:18432
	ds_read_b128 v[198:201], v226 offset:19456
	s_add_i32 m0, s10, 0xc000
	ds_read_b128 v[202:205], v155
	ds_read_b128 v[206:209], v155 offset:1024
	ds_read_b128 v[210:213], v155 offset:2048
	ds_read_b128 v[214:217], v155 offset:3072
	ds_read_b128 v[218:221], v155 offset:4096
	ds_read_b128 v[222:225], v155 offset:5120
	ds_read_b128 v[234:237], v155 offset:6144
	ds_read_b128 v[238:241], v155 offset:7168
	global_load_lds_dwordx4 v148, s[52:53]
	s_add_i32 m0, s10, 0xe000
	s_nop 0
	global_load_lds_dwordx4 v150, s[52:53]
	s_waitcnt vmcnt(8)
	s_waitcnt lgkmcnt(0)
	s_barrier
	v_mfma_f32_16x16x32_bf16 v[128:131], v[132:135], v[202:205], 0
	v_mfma_f32_16x16x32_bf16 v[124:127], v[156:159], v[202:205], 0
	v_mfma_f32_16x16x32_bf16 v[112:115], v[132:135], v[210:213], 0
	v_mfma_f32_16x16x32_bf16 v[108:111], v[156:159], v[210:213], 0
	v_mfma_f32_16x16x32_bf16 v[96:99], v[132:135], v[218:221], 0
	v_mfma_f32_16x16x32_bf16 v[92:95], v[156:159], v[218:221], 0
	v_mfma_f32_16x16x32_bf16 v[80:83], v[132:135], v[234:237], 0
	v_mfma_f32_16x16x32_bf16 v[76:79], v[156:159], v[234:237], 0
	v_mfma_f32_16x16x32_bf16 v[128:131], v[136:139], v[206:209], v[128:131]
	v_mfma_f32_16x16x32_bf16 v[124:127], v[160:163], v[206:209], v[124:127]
	v_mfma_f32_16x16x32_bf16 v[112:115], v[136:139], v[214:217], v[112:115]
	v_mfma_f32_16x16x32_bf16 v[108:111], v[160:163], v[214:217], v[108:111]
	v_mfma_f32_16x16x32_bf16 v[96:99], v[136:139], v[222:225], v[96:99]
	v_mfma_f32_16x16x32_bf16 v[92:95], v[160:163], v[222:225], v[92:95]
	v_mfma_f32_16x16x32_bf16 v[80:83], v[136:139], v[238:241], v[80:83]
	v_mfma_f32_16x16x32_bf16 v[76:79], v[160:163], v[238:241], v[76:79]
	v_mfma_f32_16x16x32_bf16 v[120:123], v[186:189], v[202:205], 0
	v_mfma_f32_16x16x32_bf16 v[116:119], v[194:197], v[202:205], 0
	v_mfma_f32_16x16x32_bf16 v[104:107], v[186:189], v[210:213], 0
	v_mfma_f32_16x16x32_bf16 v[100:103], v[194:197], v[210:213], 0
	v_mfma_f32_16x16x32_bf16 v[88:91], v[186:189], v[218:221], 0
	v_mfma_f32_16x16x32_bf16 v[84:87], v[194:197], v[218:221], 0
	v_mfma_f32_16x16x32_bf16 v[72:75], v[186:189], v[234:237], 0
	v_mfma_f32_16x16x32_bf16 v[68:71], v[194:197], v[234:237], 0
	v_mfma_f32_16x16x32_bf16 v[120:123], v[190:193], v[206:209], v[120:123]
	v_mfma_f32_16x16x32_bf16 v[116:119], v[198:201], v[206:209], v[116:119]
	v_mfma_f32_16x16x32_bf16 v[104:107], v[190:193], v[214:217], v[104:107]
	v_mfma_f32_16x16x32_bf16 v[100:103], v[198:201], v[214:217], v[100:103]
	v_mfma_f32_16x16x32_bf16 v[88:91], v[190:193], v[222:225], v[88:91]
	v_mfma_f32_16x16x32_bf16 v[84:87], v[198:201], v[222:225], v[84:87]
	v_mfma_f32_16x16x32_bf16 v[72:75], v[190:193], v[238:241], v[72:75]
	v_mfma_f32_16x16x32_bf16 v[68:71], v[198:201], v[238:241], v[68:71]
	s_barrier
	s_add_i32 s68, s68, s9
	s_mov_b32 m0, s68
	ds_read_b128 v[202:205], v155 offset:16384
	ds_read_b128 v[206:209], v155 offset:17408
	ds_read_b128 v[210:213], v155 offset:18432
	ds_read_b128 v[214:217], v155 offset:19456
	ds_read_b128 v[218:221], v155 offset:20480
	ds_read_b128 v[222:225], v155 offset:21504
	ds_read_b128 v[234:237], v155 offset:22528
	ds_read_b128 v[238:241], v155 offset:23552
	global_load_lds_dwordx4 v142, s[56:57]
	s_add_i32 m0, s68, 0x2000
	s_add_u32 s70, s56, 0x80000
	s_addc_u32 s71, s57, 0
	s_add_i32 s68, s76, s9
	global_load_lds_dwordx4 v146, s[56:57]
	s_mov_b32 m0, s68
	s_add_u32 s98, s58, 0x80
	s_addc_u32 s99, s59, 0
	global_load_lds_dwordx4 v142, s[70:71]
	s_add_i32 m0, s68, 0x2000
	s_nop 0
	global_load_lds_dwordx4 v146, s[70:71]
	s_mov_b32 m0, s10
	s_nop 0
	global_load_lds_dwordx4 v140, s[58:59]
	s_mov_b32 m0, s11
	s_nop 0
	global_load_lds_dwordx4 v144, s[58:59]
	s_waitcnt vmcnt(8)
	s_waitcnt lgkmcnt(0)
	s_barrier
	v_mfma_f32_16x16x32_bf16 v[64:67], v[132:135], v[202:205], 0
	v_mfma_f32_16x16x32_bf16 v[60:63], v[156:159], v[202:205], 0
	v_mfma_f32_16x16x32_bf16 v[48:51], v[132:135], v[210:213], 0
	v_mfma_f32_16x16x32_bf16 v[44:47], v[156:159], v[210:213], 0
	v_mfma_f32_16x16x32_bf16 v[30:33], v[132:135], v[218:221], 0
	v_mfma_f32_16x16x32_bf16 v[26:29], v[156:159], v[218:221], 0
	v_mfma_f32_16x16x32_bf16 v[14:17], v[132:135], v[234:237], 0
	v_mfma_f32_16x16x32_bf16 v[10:13], v[156:159], v[234:237], 0
	v_mfma_f32_16x16x32_bf16 v[64:67], v[136:139], v[206:209], v[64:67]
	v_mfma_f32_16x16x32_bf16 v[60:63], v[160:163], v[206:209], v[60:63]
	v_mfma_f32_16x16x32_bf16 v[48:51], v[136:139], v[214:217], v[48:51]
	v_mfma_f32_16x16x32_bf16 v[44:47], v[160:163], v[214:217], v[44:47]
	v_mfma_f32_16x16x32_bf16 v[30:33], v[136:139], v[222:225], v[30:33]
	v_mfma_f32_16x16x32_bf16 v[26:29], v[160:163], v[222:225], v[26:29]
	v_mfma_f32_16x16x32_bf16 v[14:17], v[136:139], v[238:241], v[14:17]
	v_mfma_f32_16x16x32_bf16 v[10:13], v[160:163], v[238:241], v[10:13]
	v_mfma_f32_16x16x32_bf16 v[56:59], v[186:189], v[202:205], 0
	v_mfma_f32_16x16x32_bf16 v[52:55], v[194:197], v[202:205], 0
	v_mfma_f32_16x16x32_bf16 v[40:43], v[186:189], v[210:213], 0
	v_mfma_f32_16x16x32_bf16 v[36:39], v[194:197], v[210:213], 0
	v_mfma_f32_16x16x32_bf16 v[22:25], v[186:189], v[218:221], 0
	v_mfma_f32_16x16x32_bf16 v[18:21], v[194:197], v[218:221], 0
	v_mfma_f32_16x16x32_bf16 v[6:9], v[186:189], v[234:237], 0
	v_mfma_f32_16x16x32_bf16 v[2:5], v[194:197], v[234:237], 0
	v_mfma_f32_16x16x32_bf16 v[56:59], v[190:193], v[206:209], v[56:59]
	v_mfma_f32_16x16x32_bf16 v[52:55], v[198:201], v[206:209], v[52:55]
	v_mfma_f32_16x16x32_bf16 v[40:43], v[190:193], v[214:217], v[40:43]
	v_mfma_f32_16x16x32_bf16 v[36:39], v[198:201], v[214:217], v[36:39]
	v_mfma_f32_16x16x32_bf16 v[22:25], v[190:193], v[222:225], v[22:25]
	v_mfma_f32_16x16x32_bf16 v[18:21], v[198:201], v[222:225], v[18:21]
	v_mfma_f32_16x16x32_bf16 v[6:9], v[190:193], v[238:241], v[6:9]
	v_mfma_f32_16x16x32_bf16 v[2:5], v[198:201], v[238:241], v[2:5]
	s_barrier
	s_branch .Lpeel_mid_923
	.p2align	6

; #define PG8_STAGE(bufoff, gbase, voff) do { _Pragma("unroll") for (int _i = 0; _i < 2; ++_i) \
;         __builtin_amdgcn_global_load_lds((const unsigned*)((const char*)(gbase) + (voff)[_i]), (PG8_LAS unsigned*)(lds + (bufoff) + ldsw + _i * 8192), 16, 0, 0); } while (0)
; #define PG8_LDA(dst, b, h) do { _Pragma("unroll") for (int m = 0; m < 4; ++m) _Pragma("unroll") for (int k = 0; k < 2; ++k) dst[m][k] = *(const PG8_LAS bf16x8*)(lds + PG8_SA(b, h) + aoff + m * 2048 + k * 1024); } while (0)
; #define PG8_LDB(dst, b, h) do { _Pragma("unroll") for (int n = 0; n < 2; ++n) _Pragma("unroll") for (int k = 0; k < 2; ++k) dst[n][k] = *(const PG8_LAS bf16x8*)(lds + PG8_SB(b, h) + boff + n * 2048 + k * 1024); } while (0)
; #define PG8_WAIT_V(n) asm volatile("s_waitcnt vmcnt(" #n ")" ::: "memory")
; #define PG8_WAIT_L(n) asm volatile("s_waitcnt lgkmcnt(" #n ")" ::: "memory")
; #define PG8_BAR __builtin_amdgcn_s_barrier()
; #define PG8_SCHED __builtin_amdgcn_sched_barrier(0)
;     ...
;             PG8_LDB(B0, 1, 0); PG8_LDB(B1, 1, 1); PG8_SCHED; PG8_LDA(At, 1, 0); PG8_STAGE(PG8_SA(0, 1), a2 + hstepA, voffA);
;             PG8_WAIT_V(8); PG8_WAIT_L(0); PG8_BAR; PG8_MMA(0, 0, At, B0); PG8_MMA(0, 1, At, B1); PG8_BAR; PG8_SCHED;
;             PG8_LDA(At, 1, 1); PG8_STAGE(PG8_SB(1, 0), b3, voffB); PG8_STAGE(PG8_SB(1, 1), b3 + hstepB, voffB); PG8_STAGE(PG8_SA(1, 0), a3, voffA);
;             PG8_WAIT_V(8); PG8_WAIT_L(0); PG8_BAR; PG8_MMA(1, 0, At, B0); PG8_MMA(1, 1, At, B1); PG8_BAR; PG8_SCHED;
.Lpeel_mid_923:
	s_add_i32 s68, 0, 0x18000
	s_add_i32 s70, 0, 0x1c000
	ds_read_b128 v[132:135], v226 offset:32768
	ds_read_b128 v[136:139], v226 offset:33792
	ds_read_b128 v[156:159], v226 offset:34816
	ds_read_b128 v[160:163], v226 offset:35840
	ds_read_b128 v[186:189], v226 offset:49152
	ds_read_b128 v[190:193], v226 offset:50176
	ds_read_b128 v[194:197], v226 offset:51200
	ds_read_b128 v[198:201], v226 offset:52224
	s_add_u32 s58, s58, 0x80000
	s_addc_u32 s59, s59, 0
	s_mov_b32 m0, s12
	ds_read_b128 v[202:205], v155 offset:32768
	ds_read_b128 v[206:209], v155 offset:33792
	ds_read_b128 v[210:213], v155 offset:34816
	ds_read_b128 v[214:217], v155 offset:35840
	ds_read_b128 v[218:221], v155 offset:36864
	ds_read_b128 v[222:225], v155 offset:37888
	ds_read_b128 v[234:237], v155 offset:38912
	ds_read_b128 v[238:241], v155 offset:39936
	global_load_lds_dwordx4 v140, s[58:59]
	s_mov_b32 m0, s13
	s_nop 0
	global_load_lds_dwordx4 v144, s[58:59]
	s_waitcnt vmcnt(8)
	s_waitcnt lgkmcnt(0)
	s_barrier
	v_mfma_f32_16x16x32_bf16 v[128:131], v[132:135], v[202:205], v[128:131]
	v_mfma_f32_16x16x32_bf16 v[124:127], v[156:159], v[202:205], v[124:127]
	v_mfma_f32_16x16x32_bf16 v[112:115], v[132:135], v[210:213], v[112:115]
	v_mfma_f32_16x16x32_bf16 v[108:111], v[156:159], v[210:213], v[108:111]
	v_mfma_f32_16x16x32_bf16 v[96:99], v[132:135], v[218:221], v[96:99]
	v_mfma_f32_16x16x32_bf16 v[92:95], v[156:159], v[218:221], v[92:95]
	v_mfma_f32_16x16x32_bf16 v[80:83], v[132:135], v[234:237], v[80:83]
	v_mfma_f32_16x16x32_bf16 v[76:79], v[156:159], v[234:237], v[76:79]
	v_mfma_f32_16x16x32_bf16 v[128:131], v[136:139], v[206:209], v[128:131]
	v_mfma_f32_16x16x32_bf16 v[124:127], v[160:163], v[206:209], v[124:127]
	v_mfma_f32_16x16x32_bf16 v[112:115], v[136:139], v[214:217], v[112:115]
	v_mfma_f32_16x16x32_bf16 v[108:111], v[160:163], v[214:217], v[108:111]
	v_mfma_f32_16x16x32_bf16 v[96:99], v[136:139], v[222:225], v[96:99]
	v_mfma_f32_16x16x32_bf16 v[92:95], v[160:163], v[222:225], v[92:95]
	v_mfma_f32_16x16x32_bf16 v[80:83], v[136:139], v[238:241], v[80:83]
	v_mfma_f32_16x16x32_bf16 v[76:79], v[160:163], v[238:241], v[76:79]
	v_mfma_f32_16x16x32_bf16 v[120:123], v[186:189], v[202:205], v[120:123]
	v_mfma_f32_16x16x32_bf16 v[116:119], v[194:197], v[202:205], v[116:119]
	v_mfma_f32_16x16x32_bf16 v[104:107], v[186:189], v[210:213], v[104:107]
	v_mfma_f32_16x16x32_bf16 v[100:103], v[194:197], v[210:213], v[100:103]
	v_mfma_f32_16x16x32_bf16 v[88:91], v[186:189], v[218:221], v[88:91]
	v_mfma_f32_16x16x32_bf16 v[84:87], v[194:197], v[218:221], v[84:87]
	v_mfma_f32_16x16x32_bf16 v[72:75], v[186:189], v[234:237], v[72:75]
	v_mfma_f32_16x16x32_bf16 v[68:71], v[194:197], v[234:237], v[68:71]
	v_mfma_f32_16x16x32_bf16 v[120:123], v[190:193], v[206:209], v[120:123]
	v_mfma_f32_16x16x32_bf16 v[116:119], v[198:201], v[206:209], v[116:119]
	v_mfma_f32_16x16x32_bf16 v[104:107], v[190:193], v[214:217], v[104:107]
	v_mfma_f32_16x16x32_bf16 v[100:103], v[198:201], v[214:217], v[100:103]
	v_mfma_f32_16x16x32_bf16 v[88:91], v[190:193], v[222:225], v[88:91]
	v_mfma_f32_16x16x32_bf16 v[84:87], v[198:201], v[222:225], v[84:87]
	v_mfma_f32_16x16x32_bf16 v[72:75], v[190:193], v[238:241], v[72:75]
	v_mfma_f32_16x16x32_bf16 v[68:71], v[198:201], v[238:241], v[68:71]
	s_barrier
	s_add_i32 s58, s68, s9
	s_mov_b32 m0, s58
	ds_read_b128 v[202:205], v155 offset:49152
	ds_read_b128 v[206:209], v155 offset:50176
	ds_read_b128 v[210:213], v155 offset:51200
	ds_read_b128 v[214:217], v155 offset:52224
	ds_read_b128 v[218:221], v155 offset:53248
	ds_read_b128 v[222:225], v155 offset:54272
	ds_read_b128 v[234:237], v155 offset:55296
	ds_read_b128 v[238:241], v155 offset:56320
	s_add_u32 vcc_lo, s56, 0x80
	s_addc_u32 vcc_hi, s57, 0
	global_load_lds_dwordx4 v142, vcc
	s_add_i32 m0, s58, 0x2000
	s_add_u32 s56, s56, 0x80080
	s_addc_u32 s57, s57, 0
	s_add_i32 s58, s70, s9
	s_add_u32 vcc_lo, s56, 0xfff80000
	s_addc_u32 vcc_hi, s57, -1
	global_load_lds_dwordx4 v146, vcc
	s_mov_b32 m0, s58
	s_nop 0
	global_load_lds_dwordx4 v142, s[56:57]
	s_add_i32 m0, s58, 0x2000
	s_nop 0
	global_load_lds_dwordx4 v146, s[56:57]
	s_mov_b32 m0, s55
	s_nop 0
	global_load_lds_dwordx4 v140, s[98:99]
	s_mov_b32 m0, s66
	s_nop 0
	global_load_lds_dwordx4 v144, s[98:99]
	s_waitcnt vmcnt(8)
	s_waitcnt lgkmcnt(0)
	s_barrier
	v_mfma_f32_16x16x32_bf16 v[64:67], v[132:135], v[202:205], v[64:67]
	v_mfma_f32_16x16x32_bf16 v[60:63], v[156:159], v[202:205], v[60:63]
	v_mfma_f32_16x16x32_bf16 v[48:51], v[132:135], v[210:213], v[48:51]
	v_mfma_f32_16x16x32_bf16 v[44:47], v[156:159], v[210:213], v[44:47]
	v_mfma_f32_16x16x32_bf16 v[30:33], v[132:135], v[218:221], v[30:33]
	v_mfma_f32_16x16x32_bf16 v[26:29], v[156:159], v[218:221], v[26:29]
	v_mfma_f32_16x16x32_bf16 v[14:17], v[132:135], v[234:237], v[14:17]
	v_mfma_f32_16x16x32_bf16 v[10:13], v[156:159], v[234:237], v[10:13]
	v_mfma_f32_16x16x32_bf16 v[64:67], v[136:139], v[206:209], v[64:67]
	v_mfma_f32_16x16x32_bf16 v[60:63], v[160:163], v[206:209], v[60:63]
	v_mfma_f32_16x16x32_bf16 v[48:51], v[136:139], v[214:217], v[48:51]
	v_mfma_f32_16x16x32_bf16 v[44:47], v[160:163], v[214:217], v[44:47]
	v_mfma_f32_16x16x32_bf16 v[30:33], v[136:139], v[222:225], v[30:33]
	v_mfma_f32_16x16x32_bf16 v[26:29], v[160:163], v[222:225], v[26:29]
	v_mfma_f32_16x16x32_bf16 v[14:17], v[136:139], v[238:241], v[14:17]
	v_mfma_f32_16x16x32_bf16 v[10:13], v[160:163], v[238:241], v[10:13]
	v_mfma_f32_16x16x32_bf16 v[56:59], v[186:189], v[202:205], v[56:59]
	v_mfma_f32_16x16x32_bf16 v[52:55], v[194:197], v[202:205], v[52:55]
	v_mfma_f32_16x16x32_bf16 v[40:43], v[186:189], v[210:213], v[40:43]
	v_mfma_f32_16x16x32_bf16 v[36:39], v[194:197], v[210:213], v[36:39]
	v_mfma_f32_16x16x32_bf16 v[22:25], v[186:189], v[218:221], v[22:25]
	v_mfma_f32_16x16x32_bf16 v[18:21], v[194:197], v[218:221], v[18:21]
	v_mfma_f32_16x16x32_bf16 v[6:9], v[186:189], v[234:237], v[6:9]
	v_mfma_f32_16x16x32_bf16 v[2:5], v[194:197], v[234:237], v[2:5]
	v_mfma_f32_16x16x32_bf16 v[56:59], v[190:193], v[206:209], v[56:59]
	v_mfma_f32_16x16x32_bf16 v[52:55], v[198:201], v[206:209], v[52:55]
	v_mfma_f32_16x16x32_bf16 v[40:43], v[190:193], v[214:217], v[40:43]
	v_mfma_f32_16x16x32_bf16 v[36:39], v[198:201], v[214:217], v[36:39]
	v_mfma_f32_16x16x32_bf16 v[22:25], v[190:193], v[222:225], v[22:25]
	v_mfma_f32_16x16x32_bf16 v[18:21], v[198:201], v[222:225], v[18:21]
	v_mfma_f32_16x16x32_bf16 v[6:9], v[190:193], v[238:241], v[6:9]
	v_mfma_f32_16x16x32_bf16 v[2:5], v[198:201], v[238:241], v[2:5]
	s_barrier
	s_add_i32 s47, s47, 2
	s_add_u32 s52, s52, 0x100
	s_addc_u32 s53, s53, 0
	s_add_u32 s37, s37, 0x100
	s_addc_u32 s41, s41, 0
	s_cmp_gt_u32 s47, 29
	s_cbranch_scc0 .LBB0_923
	s_and_b64 vcc, exec, s[30:31]
	s_cbranch_vccz .LBB0_926
	s_barrier

;     __device__ __forceinline__ const char* pa(const Gemm& g, const Unit& u, size_t tstep) const { return (const char*)g.A + (size_t)u.pm * tstep; }
;     __device__ __forceinline__ const char* pb(const Gemm& g, const Unit& u, size_t tstep) const { return (const char*)g.Bt + (size_t)u.pn * tstep; }
;     __device__ __forceinline__ const char* pa(const Gemm& g, const Unit& u, size_t tstep) const { return (const char*)g.A + (size_t)(u.pn >> 1) * 512 + (size_t)u.pm * tstep; }
;     __device__ __forceinline__ const char* pa(const Gemm& g, const Unit& u, size_t tstep) const { return (const char*)g.A + (size_t)u.seg * astride + (size_t)u.pm * tstep; }
;     __device__ __forceinline__ const char* pb(const Gemm& g, const Unit& u, size_t tstep) const { return (const char*)g.Bt + (size_t)u.seg * bstride + (size_t)u.pn * tstep; }
; #define PG8_STAGE(bufoff, gbase, voff) do { _Pragma("unroll") for (int _i = 0; _i < 2; ++_i) \
;         __builtin_amdgcn_global_load_lds((const unsigned*)((const char*)(gbase) + (voff)[_i]), (PG8_LAS unsigned*)(lds + (bufoff) + ldsw + _i * 8192), 16, 0, 0); } while (0)
; #define PG8_WAIT_V(n) asm volatile("s_waitcnt vmcnt(" #n ")" ::: "memory")
; #define PG8_WAIT_L(n) asm volatile("s_waitcnt lgkmcnt(" #n ")" ::: "memory")
; #define PG8_BAR __builtin_amdgcn_s_barrier()
;     ...
;         const char* nA = has_next ? S.pa(g, nxt, tstepA) : cA; const char* nB = has_next ? S.pb(g, nxt, tstepB) : cB;
;         for (int t = 0; t < nt; t += 2) {
;             const bool last = (t == nt - 2);
;             const char* a1 = cA + (size_t)(t + 1) * kstep;
;             const char* a2 = last ? nA : cA + (size_t)(t + 2) * kstep; const char* b2 = last ? nB : cB + (size_t)(t + 2) * kstep;
;             const char* a3 = a2 + kstep; const char* b3 = b2 + kstep;
;             if (last && has_next) S.a_ready(nxt);
;             if constexpr (SP2) {
;             PG8_LDB(B0, 0, 0); PG8_LDB(B1, 0, 1); PG8_SCHED; PG8_LDA(At, 0, 0); PG8_STAGE(PG8_SA(1, 1), a1 + hstepA, voffA);
;             PG8_WAIT_V(8); PG8_WAIT_L(0); PG8_BAR; PG8_MMA(0, 0, At, B0); PG8_MMA(0, 1, At, B1); PG8_BAR; PG8_SCHED;
;             PG8_LDA(At, 0, 1); PG8_STAGE(PG8_SB(0, 0), b2, voffB); PG8_STAGE(PG8_SB(0, 1), b2 + hstepB, voffB); PG8_STAGE(PG8_SA(0, 0), a2, voffA);
;             PG8_WAIT_V(8); PG8_WAIT_L(0); PG8_BAR; PG8_MMA(1, 0, At, B0); PG8_MMA(1, 1, At, B1); PG8_BAR; PG8_SCHED;
.LBB0_1132:
	s_ashr_i32 s37, s36, 31
	s_lshl_b64 s[40:41], s[36:37], 19
	s_add_u32 s40, s12, s40
	s_addc_u32 s41, s13, s41
	s_and_b64 s[46:47], s[38:39], exec
	s_cselect_b32 s37, s41, s51
	s_cselect_b32 s67, s40, s50
	s_ashr_i32 s31, s30, 31
	s_lshl_b64 s[46:47], s[30:31], 19
	s_add_u32 s46, s7, s46
	s_addc_u32 s47, s8, s47
	s_and_b64 s[54:55], s[38:39], exec
	s_cselect_b32 s31, s47, s53
	s_cselect_b32 s68, s46, s52
	s_add_u32 s50, s50, 0x40080
	s_addc_u32 s51, s51, 0
	s_add_u32 s70, s52, 0x100
	s_addc_u32 s71, s53, 0
	s_mov_b32 s74, -2
	v_add_u32_e32 v226, 0x10000, v208
	s_add_u32 s52, s50, 0xfffc0080
	s_addc_u32 s53, s51, -1
	s_add_i32 s75, 0, 0x10000
	s_cmp_eq_u32 s74, 12
	s_cselect_b32 s55, s37, s53
	s_cselect_b32 s54, s67, s52
	s_cselect_b32 s53, s31, s71
	s_cselect_b32 s52, s68, s70
	s_add_i32 s76, 0, 0x14000
	ds_read_b128 v[26:29], v226
	ds_read_b128 v[30:33], v226 offset:1024
	ds_read_b128 v[18:21], v226 offset:2048
	ds_read_b128 v[22:25], v226 offset:3072
	ds_read_b128 v[10:13], v226 offset:16384
	ds_read_b128 v[14:17], v226 offset:17408
	ds_read_b128 v[2:5], v226 offset:18432
	ds_read_b128 v[6:9], v226 offset:19456
	s_add_i32 m0, s57, 0xc000
	ds_read_b128 v[198:201], v209
	ds_read_b128 v[202:205], v209 offset:1024
	ds_read_b128 v[210:213], v209 offset:2048
	ds_read_b128 v[214:217], v209 offset:3072
	ds_read_b128 v[218:221], v209 offset:4096
	ds_read_b128 v[222:225], v209 offset:5120
	ds_read_b128 v[234:237], v209 offset:6144
	ds_read_b128 v[238:241], v209 offset:7168
	global_load_lds_dwordx4 v194, s[50:51]
	s_add_i32 m0, s57, 0xe000
	s_nop 0
	global_load_lds_dwordx4 v196, s[50:51]
	s_waitcnt vmcnt(8)
	s_waitcnt lgkmcnt(0)
	s_barrier
	v_mfma_f32_16x16x128_f8f6f4 v[160:163], v[26:33], v[198:205], 0
	v_mfma_f32_16x16x128_f8f6f4 v[156:159], v[18:25], v[198:205], 0
	v_mfma_f32_16x16x128_f8f6f4 v[144:147], v[26:33], v[210:217], 0
	v_mfma_f32_16x16x128_f8f6f4 v[140:143], v[18:25], v[210:217], 0
	v_mfma_f32_16x16x128_f8f6f4 v[128:131], v[26:33], v[218:225], 0
	v_mfma_f32_16x16x128_f8f6f4 v[124:127], v[18:25], v[218:225], 0
	v_mfma_f32_16x16x128_f8f6f4 v[112:115], v[26:33], v[234:241], 0
	v_mfma_f32_16x16x128_f8f6f4 v[108:111], v[18:25], v[234:241], 0
	v_mfma_f32_16x16x128_f8f6f4 v[152:155], v[10:17], v[198:205], 0
	v_mfma_f32_16x16x128_f8f6f4 v[148:151], v[2:9], v[198:205], 0
	v_mfma_f32_16x16x128_f8f6f4 v[136:139], v[10:17], v[210:217], 0
	v_mfma_f32_16x16x128_f8f6f4 v[132:135], v[2:9], v[210:217], 0
	v_mfma_f32_16x16x128_f8f6f4 v[120:123], v[10:17], v[218:225], 0
	v_mfma_f32_16x16x128_f8f6f4 v[116:119], v[2:9], v[218:225], 0
	v_mfma_f32_16x16x128_f8f6f4 v[104:107], v[10:17], v[234:241], 0
	v_mfma_f32_16x16x128_f8f6f4 v[100:103], v[2:9], v[234:241], 0
	s_barrier
	s_add_i32 s75, s75, s11
	s_mov_b32 m0, s75
	ds_read_b128 v[210:213], v209 offset:16384
	ds_read_b128 v[214:217], v209 offset:17408
	ds_read_b128 v[218:221], v209 offset:18432
	ds_read_b128 v[222:225], v209 offset:19456
	ds_read_b128 v[234:237], v209 offset:20480
	ds_read_b128 v[238:241], v209 offset:21504
	ds_read_b128 v[242:245], v209 offset:22528
	ds_read_b128 v[246:249], v209 offset:23552
	global_load_lds_dwordx4 v34, s[52:53]
	s_add_i32 m0, s75, 0x2000
	s_add_u32 s78, s52, 0x40000
	s_addc_u32 s79, s53, 0
	s_add_i32 s75, s76, s11
	global_load_lds_dwordx4 v186, s[52:53]
	s_mov_b32 m0, s75
	s_add_u32 s98, s54, 0x80
	s_addc_u32 s99, s55, 0
	global_load_lds_dwordx4 v34, s[78:79]
	s_add_i32 m0, s75, 0x2000
	s_nop 0
	global_load_lds_dwordx4 v186, s[78:79]
	s_mov_b32 m0, s57
	s_nop 0
	global_load_lds_dwordx4 v190, s[54:55]
	s_mov_b32 m0, s6
	s_nop 0
	global_load_lds_dwordx4 v188, s[54:55]
	s_waitcnt vmcnt(8)
	s_waitcnt lgkmcnt(0)
	s_barrier
	v_mfma_f32_16x16x128_f8f6f4 v[96:99], v[26:33], v[210:217], 0
	v_mfma_f32_16x16x128_f8f6f4 v[92:95], v[18:25], v[210:217], 0
	v_mfma_f32_16x16x128_f8f6f4 v[80:83], v[26:33], v[218:225], 0
	v_mfma_f32_16x16x128_f8f6f4 v[76:79], v[18:25], v[218:225], 0
	v_mfma_f32_16x16x128_f8f6f4 v[64:67], v[26:33], v[234:241], 0
	v_mfma_f32_16x16x128_f8f6f4 v[60:63], v[18:25], v[234:241], 0
	v_mfma_f32_16x16x128_f8f6f4 v[48:51], v[26:33], v[242:249], 0
	v_mfma_f32_16x16x128_f8f6f4 v[44:47], v[18:25], v[242:249], 0
	v_mfma_f32_16x16x128_f8f6f4 v[88:91], v[10:17], v[210:217], 0
	v_mfma_f32_16x16x128_f8f6f4 v[84:87], v[2:9], v[210:217], 0
	v_mfma_f32_16x16x128_f8f6f4 v[72:75], v[10:17], v[218:225], 0
	v_mfma_f32_16x16x128_f8f6f4 v[68:71], v[2:9], v[218:225], 0
	v_mfma_f32_16x16x128_f8f6f4 v[56:59], v[10:17], v[234:241], 0
	v_mfma_f32_16x16x128_f8f6f4 v[52:55], v[2:9], v[234:241], 0
	v_mfma_f32_16x16x128_f8f6f4 v[40:43], v[10:17], v[242:249], 0
	v_mfma_f32_16x16x128_f8f6f4 v[36:39], v[2:9], v[242:249], 0
	s_barrier
	s_branch .Lpeel_mid_1133
	.p2align	6

; #define PG8_STAGE(bufoff, gbase, voff) do { _Pragma("unroll") for (int _i = 0; _i < 2; ++_i) \
;         __builtin_amdgcn_global_load_lds((const unsigned*)((const char*)(gbase) + (voff)[_i]), (PG8_LAS unsigned*)(lds + (bufoff) + ldsw + _i * 8192), 16, 0, 0); } while (0)
; #define PG8_LDA(dst, b, h) do { _Pragma("unroll") for (int m = 0; m < 4; ++m) _Pragma("unroll") for (int k = 0; k < 2; ++k) dst[m][k] = *(const PG8_LAS bf16x8*)(lds + PG8_SA(b, h) + aoff + m * 2048 + k * 1024); } while (0)
; #define PG8_LDB(dst, b, h) do { _Pragma("unroll") for (int n = 0; n < 2; ++n) _Pragma("unroll") for (int k = 0; k < 2; ++k) dst[n][k] = *(const PG8_LAS bf16x8*)(lds + PG8_SB(b, h) + boff + n * 2048 + k * 1024); } while (0)
; #define PG8_WAIT_V(n) asm volatile("s_waitcnt vmcnt(" #n ")" ::: "memory")
; #define PG8_WAIT_L(n) asm volatile("s_waitcnt lgkmcnt(" #n ")" ::: "memory")
; #define PG8_BAR __builtin_amdgcn_s_barrier()
;     ...
;         for (int t = 0; t < nt; t += 2) {
;             const bool last = (t == nt - 2);
;             const char* a1 = cA + (size_t)(t + 1) * kstep;
;             const char* a2 = last ? nA : cA + (size_t)(t + 2) * kstep; const char* b2 = last ? nB : cB + (size_t)(t + 2) * kstep;
;             const char* a3 = a2 + kstep; const char* b3 = b2 + kstep;
;             if (last && has_next) S.a_ready(nxt);
;             if constexpr (SP2) {
;             PG8_LDB(B0, 0, 0); PG8_LDB(B1, 0, 1); PG8_SCHED; PG8_LDA(At, 0, 0); PG8_STAGE(PG8_SA(1, 1), a1 + hstepA, voffA);
;             PG8_WAIT_V(8); PG8_WAIT_L(0); PG8_BAR; PG8_MMA(0, 0, At, B0); PG8_MMA(0, 1, At, B1); PG8_BAR; PG8_SCHED;
;             PG8_LDA(At, 0, 1); PG8_STAGE(PG8_SB(0, 0), b2, voffB); PG8_STAGE(PG8_SB(0, 1), b2 + hstepB, voffB); PG8_STAGE(PG8_SA(0, 0), a2, voffA);
;             PG8_WAIT_V(8); PG8_WAIT_L(0); PG8_BAR; PG8_MMA(1, 0, At, B0); PG8_MMA(1, 1, At, B1); PG8_BAR; PG8_SCHED;
;             PG8_LDB(B0, 1, 0); PG8_LDB(B1, 1, 1); PG8_SCHED; PG8_LDA(At, 1, 0); PG8_STAGE(PG8_SA(0, 1), a2 + hstepA, voffA);
;             PG8_WAIT_V(8); PG8_WAIT_L(0); PG8_BAR; PG8_MMA(0, 0, At, B0); PG8_MMA(0, 1, At, B1); PG8_BAR; PG8_SCHED;
;             PG8_LDA(At, 1, 1); PG8_STAGE(PG8_SB(1, 0), b3, voffB); PG8_STAGE(PG8_SB(1, 1), b3 + hstepB, voffB); PG8_STAGE(PG8_SA(1, 0), a3, voffA);
;             PG8_WAIT_V(8); PG8_WAIT_L(0); PG8_BAR; PG8_MMA(1, 0, At, B0); PG8_MMA(1, 1, At, B1); PG8_BAR; PG8_SCHED;
.Lpeel_mid_1133:
	s_add_i32 s75, 0, 0x18000
	s_add_i32 s76, 0, 0x1c000
	ds_read_b128 v[2:5], v226 offset:32768
	ds_read_b128 v[6:9], v226 offset:33792
	ds_read_b128 v[10:13], v226 offset:34816
	ds_read_b128 v[14:17], v226 offset:35840
	ds_read_b128 v[18:21], v226 offset:49152
	ds_read_b128 v[22:25], v226 offset:50176
	ds_read_b128 v[26:29], v226 offset:51200
	ds_read_b128 v[30:33], v226 offset:52224
	s_add_u32 s54, s54, 0x40000
	s_addc_u32 s55, s55, 0
	s_mov_b32 m0, s15
	ds_read_b128 v[210:213], v209 offset:32768
	ds_read_b128 v[214:217], v209 offset:33792
	ds_read_b128 v[218:221], v209 offset:34816
	ds_read_b128 v[222:225], v209 offset:35840
	ds_read_b128 v[234:237], v209 offset:36864
	ds_read_b128 v[238:241], v209 offset:37888
	ds_read_b128 v[242:245], v209 offset:38912
	ds_read_b128 v[246:249], v209 offset:39936
	global_load_lds_dwordx4 v190, s[54:55]
	s_mov_b32 m0, s34
	s_nop 0
	global_load_lds_dwordx4 v188, s[54:55]
	s_waitcnt vmcnt(8)
	s_waitcnt lgkmcnt(0)
	s_barrier
	v_mfma_f32_16x16x128_f8f6f4 v[160:163], v[2:9], v[210:217], v[160:163]
	v_mfma_f32_16x16x128_f8f6f4 v[156:159], v[10:17], v[210:217], v[156:159]
	v_mfma_f32_16x16x128_f8f6f4 v[144:147], v[2:9], v[218:225], v[144:147]
	v_mfma_f32_16x16x128_f8f6f4 v[140:143], v[10:17], v[218:225], v[140:143]
	v_mfma_f32_16x16x128_f8f6f4 v[128:131], v[2:9], v[234:241], v[128:131]
	v_mfma_f32_16x16x128_f8f6f4 v[124:127], v[10:17], v[234:241], v[124:127]
	v_mfma_f32_16x16x128_f8f6f4 v[112:115], v[2:9], v[242:249], v[112:115]
	v_mfma_f32_16x16x128_f8f6f4 v[108:111], v[10:17], v[242:249], v[108:111]
	v_mfma_f32_16x16x128_f8f6f4 v[152:155], v[18:25], v[210:217], v[152:155]
	v_mfma_f32_16x16x128_f8f6f4 v[148:151], v[26:33], v[210:217], v[148:151]
	v_mfma_f32_16x16x128_f8f6f4 v[136:139], v[18:25], v[218:225], v[136:139]
	v_mfma_f32_16x16x128_f8f6f4 v[132:135], v[26:33], v[218:225], v[132:135]
	v_mfma_f32_16x16x128_f8f6f4 v[120:123], v[18:25], v[234:241], v[120:123]
	v_mfma_f32_16x16x128_f8f6f4 v[116:119], v[26:33], v[234:241], v[116:119]
	v_mfma_f32_16x16x128_f8f6f4 v[104:107], v[18:25], v[242:249], v[104:107]
	v_mfma_f32_16x16x128_f8f6f4 v[100:103], v[26:33], v[242:249], v[100:103]
	s_barrier
	s_add_i32 s54, s75, s11
	s_mov_b32 m0, s54
	ds_read_b128 v[210:213], v209 offset:49152
	ds_read_b128 v[214:217], v209 offset:50176
	ds_read_b128 v[218:221], v209 offset:51200
	ds_read_b128 v[222:225], v209 offset:52224
	ds_read_b128 v[234:237], v209 offset:53248
	ds_read_b128 v[238:241], v209 offset:54272
	ds_read_b128 v[242:245], v209 offset:55296
	ds_read_b128 v[246:249], v209 offset:56320
	s_add_u32 vcc_lo, s52, 0x80
	s_addc_u32 vcc_hi, s53, 0
	global_load_lds_dwordx4 v34, vcc
	s_add_i32 m0, s54, 0x2000
	s_add_u32 s52, s52, 0x40080
	s_addc_u32 s53, s53, 0
	s_add_i32 s54, s76, s11
	s_add_u32 vcc_lo, s52, 0xfffc0000
	s_addc_u32 vcc_hi, s53, -1
	global_load_lds_dwordx4 v186, vcc
	s_mov_b32 m0, s54
	s_nop 0
	global_load_lds_dwordx4 v34, s[52:53]
	s_add_i32 m0, s54, 0x2000
	s_nop 0
	global_load_lds_dwordx4 v186, s[52:53]
	s_mov_b32 m0, s35
	s_nop 0
	global_load_lds_dwordx4 v190, s[98:99]
	s_mov_b32 m0, s58
	s_nop 0
	global_load_lds_dwordx4 v188, s[98:99]
	s_waitcnt vmcnt(8)
	s_waitcnt lgkmcnt(0)
	s_barrier
	v_mfma_f32_16x16x128_f8f6f4 v[96:99], v[2:9], v[210:217], v[96:99]
	v_mfma_f32_16x16x128_f8f6f4 v[92:95], v[10:17], v[210:217], v[92:95]
	v_mfma_f32_16x16x128_f8f6f4 v[80:83], v[2:9], v[218:225], v[80:83]
	v_mfma_f32_16x16x128_f8f6f4 v[76:79], v[10:17], v[218:225], v[76:79]
	v_mfma_f32_16x16x128_f8f6f4 v[64:67], v[2:9], v[234:241], v[64:67]
	v_mfma_f32_16x16x128_f8f6f4 v[60:63], v[10:17], v[234:241], v[60:63]
	v_mfma_f32_16x16x128_f8f6f4 v[48:51], v[2:9], v[242:249], v[48:51]
	v_mfma_f32_16x16x128_f8f6f4 v[44:47], v[10:17], v[242:249], v[44:47]
	v_mfma_f32_16x16x128_f8f6f4 v[88:91], v[18:25], v[210:217], v[88:91]
	v_mfma_f32_16x16x128_f8f6f4 v[84:87], v[26:33], v[210:217], v[84:87]
	v_mfma_f32_16x16x128_f8f6f4 v[72:75], v[18:25], v[218:225], v[72:75]
	v_mfma_f32_16x16x128_f8f6f4 v[68:71], v[26:33], v[218:225], v[68:71]
	v_mfma_f32_16x16x128_f8f6f4 v[56:59], v[18:25], v[234:241], v[56:59]
	v_mfma_f32_16x16x128_f8f6f4 v[52:55], v[26:33], v[234:241], v[52:55]
	v_mfma_f32_16x16x128_f8f6f4 v[40:43], v[18:25], v[242:249], v[40:43]
	v_mfma_f32_16x16x128_f8f6f4 v[36:39], v[26:33], v[242:249], v[36:39]
	s_barrier
	s_add_i32 s74, s74, 2
	s_add_u32 s50, s50, 0x100
	s_addc_u32 s51, s51, 0
	s_add_u32 s70, s70, 0x100
	s_addc_u32 s71, s71, 0
	s_cmp_gt_u32 s74, 13
	s_cbranch_scc0 .LBB0_1133
	s_and_b64 vcc, exec, s[28:29]
	s_cbranch_vccz .LBB0_1136
	s_barrier

;     __device__ __forceinline__ const char* pa(const Gemm& g, const Unit& u, size_t tstep) const { return (const char*)g.A + (size_t)u.pm * tstep; }
;     __device__ __forceinline__ const char* pb(const Gemm& g, const Unit& u, size_t tstep) const { return (const char*)g.Bt + (size_t)u.pn * tstep; }
;     __device__ __forceinline__ const char* pa(const Gemm& g, const Unit& u, size_t tstep) const { return (const char*)g.A + (size_t)(u.pn >> 1) * 512 + (size_t)u.pm * tstep; }
;     __device__ __forceinline__ const char* pa(const Gemm& g, const Unit& u, size_t tstep) const { return (const char*)g.A + (size_t)u.seg * astride + (size_t)u.pm * tstep; }
;     __device__ __forceinline__ const char* pb(const Gemm& g, const Unit& u, size_t tstep) const { return (const char*)g.Bt + (size_t)u.seg * bstride + (size_t)u.pn * tstep; }
; #define PG8_STAGE(bufoff, gbase, voff) do { _Pragma("unroll") for (int _i = 0; _i < 2; ++_i) \
;         __builtin_amdgcn_global_load_lds((const unsigned*)((const char*)(gbase) + (voff)[_i]), (PG8_LAS unsigned*)(lds + (bufoff) + ldsw + _i * 8192), 16, 0, 0); } while (0)
; #define PG8_WAIT_V(n) asm volatile("s_waitcnt vmcnt(" #n ")" ::: "memory")
; #define PG8_WAIT_L(n) asm volatile("s_waitcnt lgkmcnt(" #n ")" ::: "memory")
; #define PG8_BAR __builtin_amdgcn_s_barrier()
;     ...
;         const char* nA = has_next ? S.pa(g, nxt, tstepA) : cA; const char* nB = has_next ? S.pb(g, nxt, tstepB) : cB;
;         for (int t = 0; t < nt; t += 2) {
;             const bool last = (t == nt - 2);
;             const char* a1 = cA + (size_t)(t + 1) * kstep;
;             const char* a2 = last ? nA : cA + (size_t)(t + 2) * kstep; const char* b2 = last ? nB : cB + (size_t)(t + 2) * kstep;
;             const char* a3 = a2 + kstep; const char* b3 = b2 + kstep;
;             if (last && has_next) S.a_ready(nxt);
;             if constexpr (SP2) {
;             PG8_LDB(B0, 0, 0); PG8_LDB(B1, 0, 1); PG8_SCHED; PG8_LDA(At, 0, 0); PG8_STAGE(PG8_SA(1, 1), a1 + hstepA, voffA);
;             PG8_WAIT_V(8); PG8_WAIT_L(0); PG8_BAR; PG8_MMA(0, 0, At, B0); PG8_MMA(0, 1, At, B1); PG8_BAR; PG8_SCHED;
;             PG8_LDA(At, 0, 1); PG8_STAGE(PG8_SB(0, 0), b2, voffB); PG8_STAGE(PG8_SB(0, 1), b2 + hstepB, voffB); PG8_STAGE(PG8_SA(0, 0), a2, voffA);
;             PG8_WAIT_V(8); PG8_WAIT_L(0); PG8_BAR; PG8_MMA(1, 0, At, B0); PG8_MMA(1, 1, At, B1); PG8_BAR; PG8_SCHED;
.LBB0_1152:
	s_ashr_i32 s49, s48, 31
	s_lshl_b64 s[10:11], s[48:49], 20
	s_add_u32 s50, s60, s10
	s_addc_u32 s51, s61, s11
	s_and_b64 s[10:11], s[38:39], exec
	s_cselect_b32 s6, s51, s27
	s_cselect_b32 s10, s50, s26
	s_ashr_i32 s19, s18, 31
	s_lshl_b64 s[12:13], s[18:19], 20
	s_add_u32 s52, s62, s12
	s_addc_u32 s53, s63, s13
	s_and_b64 s[12:13], s[38:39], exec
	s_cselect_b32 s11, s53, s41
	s_cselect_b32 s12, s52, s40
	s_add_u32 s26, s26, 0x80080
	s_addc_u32 s27, s27, 0
	s_add_u32 s13, s40, 0x100
	s_addc_u32 s15, s41, 0
	s_mov_b32 s19, -2
	v_add_u32_e32 v162, 0x10000, v155
	s_add_u32 s34, s26, 0xfff80080
	s_addc_u32 s35, s27, -1
	s_add_i32 s37, 0, 0x10000
	s_cmp_eq_u32 s19, 28
	s_cselect_b32 s57, s6, s35
	s_cselect_b32 s56, s10, s34
	s_cselect_b32 s41, s11, s15
	s_cselect_b32 s40, s12, s13
	s_add_i32 s49, 0, 0x14000
	ds_read_b128 v[132:135], v162
	ds_read_b128 v[136:139], v162 offset:1024
	s_waitcnt vmcnt(0)
	ds_read_b128 v[158:161], v162 offset:2048
	ds_read_b128 v[186:189], v162 offset:3072
	ds_read_b128 v[190:193], v162 offset:16384
	ds_read_b128 v[194:197], v162 offset:17408
	ds_read_b128 v[198:201], v162 offset:18432
	ds_read_b128 v[202:205], v162 offset:19456
	s_add_i32 m0, s8, 0xc000
	ds_read_b128 v[206:209], v157
	ds_read_b128 v[210:213], v157 offset:1024
	ds_read_b128 v[214:217], v157 offset:2048
	ds_read_b128 v[218:221], v157 offset:3072
	ds_read_b128 v[222:225], v157 offset:4096
	ds_read_b128 v[234:237], v157 offset:5120
	ds_read_b128 v[238:241], v157 offset:6144
	ds_read_b128 v[242:245], v157 offset:7168
	global_load_lds_dwordx4 v150, s[26:27]
	s_add_i32 m0, s8, 0xe000
	s_nop 0
	global_load_lds_dwordx4 v152, s[26:27]
	s_waitcnt vmcnt(8)
	s_waitcnt lgkmcnt(0)
	s_barrier
	v_mfma_f32_16x16x32_bf16 v[128:131], v[132:135], v[206:209], 0
	v_mfma_f32_16x16x32_bf16 v[124:127], v[158:161], v[206:209], 0
	v_mfma_f32_16x16x32_bf16 v[112:115], v[132:135], v[214:217], 0
	v_mfma_f32_16x16x32_bf16 v[108:111], v[158:161], v[214:217], 0
	v_mfma_f32_16x16x32_bf16 v[96:99], v[132:135], v[222:225], 0
	v_mfma_f32_16x16x32_bf16 v[92:95], v[158:161], v[222:225], 0
	v_mfma_f32_16x16x32_bf16 v[80:83], v[132:135], v[238:241], 0
	v_mfma_f32_16x16x32_bf16 v[76:79], v[158:161], v[238:241], 0
	v_mfma_f32_16x16x32_bf16 v[128:131], v[136:139], v[210:213], v[128:131]
	v_mfma_f32_16x16x32_bf16 v[124:127], v[186:189], v[210:213], v[124:127]
	v_mfma_f32_16x16x32_bf16 v[112:115], v[136:139], v[218:221], v[112:115]
	v_mfma_f32_16x16x32_bf16 v[108:111], v[186:189], v[218:221], v[108:111]
	v_mfma_f32_16x16x32_bf16 v[96:99], v[136:139], v[234:237], v[96:99]
	v_mfma_f32_16x16x32_bf16 v[92:95], v[186:189], v[234:237], v[92:95]
	v_mfma_f32_16x16x32_bf16 v[80:83], v[136:139], v[242:245], v[80:83]
	v_mfma_f32_16x16x32_bf16 v[76:79], v[186:189], v[242:245], v[76:79]
	v_mfma_f32_16x16x32_bf16 v[120:123], v[190:193], v[206:209], 0
	v_mfma_f32_16x16x32_bf16 v[116:119], v[198:201], v[206:209], 0
	v_mfma_f32_16x16x32_bf16 v[104:107], v[190:193], v[214:217], 0
	v_mfma_f32_16x16x32_bf16 v[100:103], v[198:201], v[214:217], 0
	v_mfma_f32_16x16x32_bf16 v[88:91], v[190:193], v[222:225], 0
	v_mfma_f32_16x16x32_bf16 v[84:87], v[198:201], v[222:225], 0
	v_mfma_f32_16x16x32_bf16 v[72:75], v[190:193], v[238:241], 0
	v_mfma_f32_16x16x32_bf16 v[68:71], v[198:201], v[238:241], 0
	v_mfma_f32_16x16x32_bf16 v[120:123], v[194:197], v[210:213], v[120:123]
	v_mfma_f32_16x16x32_bf16 v[116:119], v[202:205], v[210:213], v[116:119]
	v_mfma_f32_16x16x32_bf16 v[104:107], v[194:197], v[218:221], v[104:107]
	v_mfma_f32_16x16x32_bf16 v[100:103], v[202:205], v[218:221], v[100:103]
	v_mfma_f32_16x16x32_bf16 v[88:91], v[194:197], v[234:237], v[88:91]
	v_mfma_f32_16x16x32_bf16 v[84:87], v[202:205], v[234:237], v[84:87]
	v_mfma_f32_16x16x32_bf16 v[72:75], v[194:197], v[242:245], v[72:75]
	v_mfma_f32_16x16x32_bf16 v[68:71], v[202:205], v[242:245], v[68:71]
	s_barrier
	s_add_i32 s34, s37, s7
	s_mov_b32 m0, s34
	ds_read_b128 v[206:209], v157 offset:16384
	ds_read_b128 v[210:213], v157 offset:17408
	ds_read_b128 v[214:217], v157 offset:18432
	ds_read_b128 v[218:221], v157 offset:19456
	ds_read_b128 v[222:225], v157 offset:20480
	ds_read_b128 v[234:237], v157 offset:21504
	ds_read_b128 v[238:241], v157 offset:22528
	ds_read_b128 v[242:245], v157 offset:23552
	global_load_lds_dwordx4 v142, s[40:41]
	s_add_i32 m0, s34, 0x2000
	s_add_u32 s34, s40, 0x80000
	s_addc_u32 s35, s41, 0
	s_add_i32 s37, s49, s7
	global_load_lds_dwordx4 v146, s[40:41]
	s_mov_b32 m0, s37
	s_nop 0
	global_load_lds_dwordx4 v142, s[34:35]
	s_add_i32 m0, s37, 0x2000
	s_nop 0
	global_load_lds_dwordx4 v146, s[34:35]
	s_mov_b32 m0, s8
	s_nop 0
	global_load_lds_dwordx4 v140, s[56:57]
	s_mov_b32 m0, s9
	s_nop 0
	global_load_lds_dwordx4 v144, s[56:57]
	s_waitcnt vmcnt(8)
	s_waitcnt lgkmcnt(0)
	s_barrier
	v_mfma_f32_16x16x32_bf16 v[64:67], v[132:135], v[206:209], 0
	v_mfma_f32_16x16x32_bf16 v[60:63], v[158:161], v[206:209], 0
	v_mfma_f32_16x16x32_bf16 v[48:51], v[132:135], v[214:217], 0
	v_mfma_f32_16x16x32_bf16 v[44:47], v[158:161], v[214:217], 0
	v_mfma_f32_16x16x32_bf16 v[30:33], v[132:135], v[222:225], 0
	v_mfma_f32_16x16x32_bf16 v[26:29], v[158:161], v[222:225], 0
	v_mfma_f32_16x16x32_bf16 v[14:17], v[132:135], v[238:241], 0
	v_mfma_f32_16x16x32_bf16 v[10:13], v[158:161], v[238:241], 0
	v_mfma_f32_16x16x32_bf16 v[64:67], v[136:139], v[210:213], v[64:67]
	v_mfma_f32_16x16x32_bf16 v[60:63], v[186:189], v[210:213], v[60:63]
	v_mfma_f32_16x16x32_bf16 v[48:51], v[136:139], v[218:221], v[48:51]
	v_mfma_f32_16x16x32_bf16 v[44:47], v[186:189], v[218:221], v[44:47]
	v_mfma_f32_16x16x32_bf16 v[30:33], v[136:139], v[234:237], v[30:33]
	v_mfma_f32_16x16x32_bf16 v[26:29], v[186:189], v[234:237], v[26:29]
	v_mfma_f32_16x16x32_bf16 v[14:17], v[136:139], v[242:245], v[14:17]
	v_mfma_f32_16x16x32_bf16 v[10:13], v[186:189], v[242:245], v[10:13]
	v_mfma_f32_16x16x32_bf16 v[56:59], v[190:193], v[206:209], 0
	v_mfma_f32_16x16x32_bf16 v[52:55], v[198:201], v[206:209], 0
	v_mfma_f32_16x16x32_bf16 v[40:43], v[190:193], v[214:217], 0
	v_mfma_f32_16x16x32_bf16 v[36:39], v[198:201], v[214:217], 0
	v_mfma_f32_16x16x32_bf16 v[22:25], v[190:193], v[222:225], 0
	v_mfma_f32_16x16x32_bf16 v[18:21], v[198:201], v[222:225], 0
	v_mfma_f32_16x16x32_bf16 v[6:9], v[190:193], v[238:241], 0
	v_mfma_f32_16x16x32_bf16 v[2:5], v[198:201], v[238:241], 0
	v_mfma_f32_16x16x32_bf16 v[56:59], v[194:197], v[210:213], v[56:59]
	v_mfma_f32_16x16x32_bf16 v[52:55], v[202:205], v[210:213], v[52:55]
	v_mfma_f32_16x16x32_bf16 v[40:43], v[194:197], v[218:221], v[40:43]
	v_mfma_f32_16x16x32_bf16 v[36:39], v[202:205], v[218:221], v[36:39]
	v_mfma_f32_16x16x32_bf16 v[22:25], v[194:197], v[234:237], v[22:25]
	v_mfma_f32_16x16x32_bf16 v[18:21], v[202:205], v[234:237], v[18:21]
	v_mfma_f32_16x16x32_bf16 v[6:9], v[194:197], v[242:245], v[6:9]
	v_mfma_f32_16x16x32_bf16 v[2:5], v[202:205], v[242:245], v[2:5]
	s_barrier
	s_branch .Lpeel_mid_1153
	.p2align	6

; #define PG8_STAGE(bufoff, gbase, voff) do { _Pragma("unroll") for (int _i = 0; _i < 2; ++_i) \
;         __builtin_amdgcn_global_load_lds((const unsigned*)((const char*)(gbase) + (voff)[_i]), (PG8_LAS unsigned*)(lds + (bufoff) + ldsw + _i * 8192), 16, 0, 0); } while (0)
; #define PG8_LDA(dst, b, h) do { _Pragma("unroll") for (int m = 0; m < 4; ++m) _Pragma("unroll") for (int k = 0; k < 2; ++k) dst[m][k] = *(const PG8_LAS bf16x8*)(lds + PG8_SA(b, h) + aoff + m * 2048 + k * 1024); } while (0)
; #define PG8_LDB(dst, b, h) do { _Pragma("unroll") for (int n = 0; n < 2; ++n) _Pragma("unroll") for (int k = 0; k < 2; ++k) dst[n][k] = *(const PG8_LAS bf16x8*)(lds + PG8_SB(b, h) + boff + n * 2048 + k * 1024); } while (0)
; #define PG8_WAIT_V(n) asm volatile("s_waitcnt vmcnt(" #n ")" ::: "memory")
; #define PG8_WAIT_L(n) asm volatile("s_waitcnt lgkmcnt(" #n ")" ::: "memory")
; #define PG8_BAR __builtin_amdgcn_s_barrier()
;     ...
;         for (int t = 0; t < nt; t += 2) {
;             const bool last = (t == nt - 2);
;             const char* a1 = cA + (size_t)(t + 1) * kstep;
;             const char* a2 = last ? nA : cA + (size_t)(t + 2) * kstep; const char* b2 = last ? nB : cB + (size_t)(t + 2) * kstep;
;             const char* a3 = a2 + kstep; const char* b3 = b2 + kstep;
;             if (last && has_next) S.a_ready(nxt);
;             if constexpr (SP2) {
;             PG8_LDB(B0, 0, 0); PG8_LDB(B1, 0, 1); PG8_SCHED; PG8_LDA(At, 0, 0); PG8_STAGE(PG8_SA(1, 1), a1 + hstepA, voffA);
;             PG8_WAIT_V(8); PG8_WAIT_L(0); PG8_BAR; PG8_MMA(0, 0, At, B0); PG8_MMA(0, 1, At, B1); PG8_BAR; PG8_SCHED;
;             PG8_LDA(At, 0, 1); PG8_STAGE(PG8_SB(0, 0), b2, voffB); PG8_STAGE(PG8_SB(0, 1), b2 + hstepB, voffB); PG8_STAGE(PG8_SA(0, 0), a2, voffA);
;             PG8_WAIT_V(8); PG8_WAIT_L(0); PG8_BAR; PG8_MMA(1, 0, At, B0); PG8_MMA(1, 1, At, B1); PG8_BAR; PG8_SCHED;
;             PG8_LDB(B0, 1, 0); PG8_LDB(B1, 1, 1); PG8_SCHED; PG8_LDA(At, 1, 0); PG8_STAGE(PG8_SA(0, 1), a2 + hstepA, voffA);
;             PG8_WAIT_V(8); PG8_WAIT_L(0); PG8_BAR; PG8_MMA(0, 0, At, B0); PG8_MMA(0, 1, At, B1); PG8_BAR; PG8_SCHED;
;             PG8_LDA(At, 1, 1); PG8_STAGE(PG8_SB(1, 0), b3, voffB); PG8_STAGE(PG8_SB(1, 1), b3 + hstepB, voffB); PG8_STAGE(PG8_SA(1, 0), a3, voffA);
;             PG8_WAIT_V(8); PG8_WAIT_L(0); PG8_BAR; PG8_MMA(1, 0, At, B0); PG8_MMA(1, 1, At, B1); PG8_BAR; PG8_SCHED;
.Lpeel_mid_1153:
	s_add_i32 s37, 0, 0x18000
	s_add_i32 s49, 0, 0x1c000
	ds_read_b128 v[132:135], v162 offset:32768
	ds_read_b128 v[136:139], v162 offset:33792
	ds_read_b128 v[158:161], v162 offset:34816
	ds_read_b128 v[186:189], v162 offset:35840
	ds_read_b128 v[190:193], v162 offset:49152
	ds_read_b128 v[194:197], v162 offset:50176
	ds_read_b128 v[198:201], v162 offset:51200
	ds_read_b128 v[202:205], v162 offset:52224
	s_add_u32 s34, s56, 0x80000
	s_addc_u32 s35, s57, 0
	s_mov_b32 m0, s58
	ds_read_b128 v[206:209], v157 offset:32768
	ds_read_b128 v[210:213], v157 offset:33792
	ds_read_b128 v[214:217], v157 offset:34816
	ds_read_b128 v[218:221], v157 offset:35840
	ds_read_b128 v[222:225], v157 offset:36864
	ds_read_b128 v[234:237], v157 offset:37888
	ds_read_b128 v[238:241], v157 offset:38912
	ds_read_b128 v[242:245], v157 offset:39936
	global_load_lds_dwordx4 v140, s[34:35]
	s_mov_b32 m0, s59
	s_nop 0
	global_load_lds_dwordx4 v144, s[34:35]
	s_waitcnt vmcnt(8)
	s_waitcnt lgkmcnt(0)
	s_barrier
	v_mfma_f32_16x16x32_bf16 v[128:131], v[132:135], v[206:209], v[128:131]
	v_mfma_f32_16x16x32_bf16 v[124:127], v[158:161], v[206:209], v[124:127]
	v_mfma_f32_16x16x32_bf16 v[112:115], v[132:135], v[214:217], v[112:115]
	v_mfma_f32_16x16x32_bf16 v[108:111], v[158:161], v[214:217], v[108:111]
	v_mfma_f32_16x16x32_bf16 v[96:99], v[132:135], v[222:225], v[96:99]
	v_mfma_f32_16x16x32_bf16 v[92:95], v[158:161], v[222:225], v[92:95]
	v_mfma_f32_16x16x32_bf16 v[80:83], v[132:135], v[238:241], v[80:83]
	v_mfma_f32_16x16x32_bf16 v[76:79], v[158:161], v[238:241], v[76:79]
	v_mfma_f32_16x16x32_bf16 v[128:131], v[136:139], v[210:213], v[128:131]
	v_mfma_f32_16x16x32_bf16 v[124:127], v[186:189], v[210:213], v[124:127]
	v_mfma_f32_16x16x32_bf16 v[112:115], v[136:139], v[218:221], v[112:115]
	v_mfma_f32_16x16x32_bf16 v[108:111], v[186:189], v[218:221], v[108:111]
	v_mfma_f32_16x16x32_bf16 v[96:99], v[136:139], v[234:237], v[96:99]
	v_mfma_f32_16x16x32_bf16 v[92:95], v[186:189], v[234:237], v[92:95]
	v_mfma_f32_16x16x32_bf16 v[80:83], v[136:139], v[242:245], v[80:83]
	v_mfma_f32_16x16x32_bf16 v[76:79], v[186:189], v[242:245], v[76:79]
	v_mfma_f32_16x16x32_bf16 v[120:123], v[190:193], v[206:209], v[120:123]
	v_mfma_f32_16x16x32_bf16 v[116:119], v[198:201], v[206:209], v[116:119]
	v_mfma_f32_16x16x32_bf16 v[104:107], v[190:193], v[214:217], v[104:107]
	v_mfma_f32_16x16x32_bf16 v[100:103], v[198:201], v[214:217], v[100:103]
	v_mfma_f32_16x16x32_bf16 v[88:91], v[190:193], v[222:225], v[88:91]
	v_mfma_f32_16x16x32_bf16 v[84:87], v[198:201], v[222:225], v[84:87]
	v_mfma_f32_16x16x32_bf16 v[72:75], v[190:193], v[238:241], v[72:75]
	v_mfma_f32_16x16x32_bf16 v[68:71], v[198:201], v[238:241], v[68:71]
	v_mfma_f32_16x16x32_bf16 v[120:123], v[194:197], v[210:213], v[120:123]
	v_mfma_f32_16x16x32_bf16 v[116:119], v[202:205], v[210:213], v[116:119]
	v_mfma_f32_16x16x32_bf16 v[104:107], v[194:197], v[218:221], v[104:107]
	v_mfma_f32_16x16x32_bf16 v[100:103], v[202:205], v[218:221], v[100:103]
	v_mfma_f32_16x16x32_bf16 v[88:91], v[194:197], v[234:237], v[88:91]
	v_mfma_f32_16x16x32_bf16 v[84:87], v[202:205], v[234:237], v[84:87]
	v_mfma_f32_16x16x32_bf16 v[72:75], v[194:197], v[242:245], v[72:75]
	v_mfma_f32_16x16x32_bf16 v[68:71], v[202:205], v[242:245], v[68:71]
	s_barrier
	s_add_i32 s34, s37, s7
	s_mov_b32 m0, s34
	ds_read_b128 v[206:209], v157 offset:49152
	ds_read_b128 v[210:213], v157 offset:50176
	ds_read_b128 v[214:217], v157 offset:51200
	ds_read_b128 v[218:221], v157 offset:52224
	ds_read_b128 v[222:225], v157 offset:53248
	ds_read_b128 v[234:237], v157 offset:54272
	ds_read_b128 v[238:241], v157 offset:55296
	ds_read_b128 v[242:245], v157 offset:56320
	s_add_u32 vcc_lo, s40, 0x80
	s_addc_u32 vcc_hi, s41, 0
	global_load_lds_dwordx4 v142, vcc
	s_add_i32 m0, s34, 0x2000
	s_add_u32 s34, s40, 0x80080
	s_addc_u32 s35, s41, 0
	s_add_i32 s37, s49, s7
	s_add_u32 vcc_lo, s40, 0x80
	s_addc_u32 vcc_hi, s41, 0
	global_load_lds_dwordx4 v146, vcc
	s_mov_b32 m0, s37
	s_nop 0
	global_load_lds_dwordx4 v142, s[34:35]
	s_add_i32 m0, s37, 0x2000
	s_nop 0
	global_load_lds_dwordx4 v146, s[34:35]
	s_mov_b32 m0, s66
	s_nop 0
	s_add_u32 vcc_lo, s56, 0x80
	s_addc_u32 vcc_hi, s57, 0
	global_load_lds_dwordx4 v140, vcc
	s_mov_b32 m0, s67
	s_nop 0
	s_add_u32 vcc_lo, s56, 0x80
	s_addc_u32 vcc_hi, s57, 0
	global_load_lds_dwordx4 v144, vcc
	s_waitcnt vmcnt(8)
	s_waitcnt lgkmcnt(0)
	s_barrier
	v_mfma_f32_16x16x32_bf16 v[64:67], v[132:135], v[206:209], v[64:67]
	v_mfma_f32_16x16x32_bf16 v[60:63], v[158:161], v[206:209], v[60:63]
	v_mfma_f32_16x16x32_bf16 v[48:51], v[132:135], v[214:217], v[48:51]
	v_mfma_f32_16x16x32_bf16 v[44:47], v[158:161], v[214:217], v[44:47]
	v_mfma_f32_16x16x32_bf16 v[30:33], v[132:135], v[222:225], v[30:33]
	v_mfma_f32_16x16x32_bf16 v[26:29], v[158:161], v[222:225], v[26:29]
	v_mfma_f32_16x16x32_bf16 v[14:17], v[132:135], v[238:241], v[14:17]
	v_mfma_f32_16x16x32_bf16 v[10:13], v[158:161], v[238:241], v[10:13]
	v_mfma_f32_16x16x32_bf16 v[64:67], v[136:139], v[210:213], v[64:67]
	v_mfma_f32_16x16x32_bf16 v[60:63], v[186:189], v[210:213], v[60:63]
	v_mfma_f32_16x16x32_bf16 v[48:51], v[136:139], v[218:221], v[48:51]
	v_mfma_f32_16x16x32_bf16 v[44:47], v[186:189], v[218:221], v[44:47]
	v_mfma_f32_16x16x32_bf16 v[30:33], v[136:139], v[234:237], v[30:33]
	v_mfma_f32_16x16x32_bf16 v[26:29], v[186:189], v[234:237], v[26:29]
	v_mfma_f32_16x16x32_bf16 v[14:17], v[136:139], v[242:245], v[14:17]
	v_mfma_f32_16x16x32_bf16 v[10:13], v[186:189], v[242:245], v[10:13]
	v_mfma_f32_16x16x32_bf16 v[56:59], v[190:193], v[206:209], v[56:59]
	v_mfma_f32_16x16x32_bf16 v[52:55], v[198:201], v[206:209], v[52:55]
	v_mfma_f32_16x16x32_bf16 v[40:43], v[190:193], v[214:217], v[40:43]
	v_mfma_f32_16x16x32_bf16 v[36:39], v[198:201], v[214:217], v[36:39]
	v_mfma_f32_16x16x32_bf16 v[22:25], v[190:193], v[222:225], v[22:25]
	v_mfma_f32_16x16x32_bf16 v[18:21], v[198:201], v[222:225], v[18:21]
	v_mfma_f32_16x16x32_bf16 v[6:9], v[190:193], v[238:241], v[6:9]
	v_mfma_f32_16x16x32_bf16 v[2:5], v[198:201], v[238:241], v[2:5]
	v_mfma_f32_16x16x32_bf16 v[56:59], v[194:197], v[210:213], v[56:59]
	v_mfma_f32_16x16x32_bf16 v[52:55], v[202:205], v[210:213], v[52:55]
	v_mfma_f32_16x16x32_bf16 v[40:43], v[194:197], v[218:221], v[40:43]
	v_mfma_f32_16x16x32_bf16 v[36:39], v[202:205], v[218:221], v[36:39]
	v_mfma_f32_16x16x32_bf16 v[22:25], v[194:197], v[234:237], v[22:25]
	v_mfma_f32_16x16x32_bf16 v[18:21], v[202:205], v[234:237], v[18:21]
	v_mfma_f32_16x16x32_bf16 v[6:9], v[194:197], v[242:245], v[6:9]
	v_mfma_f32_16x16x32_bf16 v[2:5], v[202:205], v[242:245], v[2:5]
	s_barrier
	s_add_i32 s19, s19, 2
	s_add_u32 s26, s26, 0x100
	s_addc_u32 s27, s27, 0
	s_add_u32 s13, s13, 0x100
	s_addc_u32 s15, s15, 0
	s_cmp_gt_u32 s19, 29
	s_cbranch_scc0 .LBB0_1153
	s_and_b64 vcc, exec, s[46:47]
	s_cbranch_vccz .LBB0_1156
	s_barrier

;     __device__ __forceinline__ const char* pa(const Gemm& g, const Unit& u, size_t tstep) const { return (const char*)g.A + (size_t)u.pm * tstep; }
;     __device__ __forceinline__ const char* pb(const Gemm& g, const Unit& u, size_t tstep) const { return (const char*)g.Bt + (size_t)u.pn * tstep; }
;     __device__ __forceinline__ const char* pa(const Gemm& g, const Unit& u, size_t tstep) const { return (const char*)g.A + (size_t)(u.pn >> 1) * 512 + (size_t)u.pm * tstep; }
;     __device__ __forceinline__ const char* pa(const Gemm& g, const Unit& u, size_t tstep) const { return (const char*)g.A + (size_t)u.seg * astride + (size_t)u.pm * tstep; }
;     __device__ __forceinline__ const char* pb(const Gemm& g, const Unit& u, size_t tstep) const { return (const char*)g.Bt + (size_t)u.seg * bstride + (size_t)u.pn * tstep; }
; #define PG8_STAGE(bufoff, gbase, voff) do { _Pragma("unroll") for (int _i = 0; _i < 2; ++_i) \
;         __builtin_amdgcn_global_load_lds((const unsigned*)((const char*)(gbase) + (voff)[_i]), (PG8_LAS unsigned*)(lds + (bufoff) + ldsw + _i * 8192), 16, 0, 0); } while (0)
; #define PG8_WAIT_V(n) asm volatile("s_waitcnt vmcnt(" #n ")" ::: "memory")
; #define PG8_WAIT_L(n) asm volatile("s_waitcnt lgkmcnt(" #n ")" ::: "memory")
; #define PG8_BAR __builtin_amdgcn_s_barrier()
;     ...
;         const char* nA = has_next ? S.pa(g, nxt, tstepA) : cA; const char* nB = has_next ? S.pb(g, nxt, tstepB) : cB;
;         for (int t = 0; t < nt; t += 2) {
;             const bool last = (t == nt - 2);
;             const char* a1 = cA + (size_t)(t + 1) * kstep;
;             const char* a2 = last ? nA : cA + (size_t)(t + 2) * kstep; const char* b2 = last ? nB : cB + (size_t)(t + 2) * kstep;
;             const char* a3 = a2 + kstep; const char* b3 = b2 + kstep;
;             if (last && has_next) S.a_ready(nxt);
;             if constexpr (SP2) {
;             PG8_LDB(B0, 0, 0); PG8_LDB(B1, 0, 1); PG8_SCHED; PG8_LDA(At, 0, 0); PG8_STAGE(PG8_SA(1, 1), a1 + hstepA, voffA);
;             PG8_WAIT_V(8); PG8_WAIT_L(0); PG8_BAR; PG8_MMA(0, 0, At, B0); PG8_MMA(0, 1, At, B1); PG8_BAR; PG8_SCHED;
;             PG8_LDA(At, 0, 1); PG8_STAGE(PG8_SB(0, 0), b2, voffB); PG8_STAGE(PG8_SB(0, 1), b2 + hstepB, voffB); PG8_STAGE(PG8_SA(0, 0), a2, voffA);
;             PG8_WAIT_V(8); PG8_WAIT_L(0); PG8_BAR; PG8_MMA(1, 0, At, B0); PG8_MMA(1, 1, At, B1); PG8_BAR; PG8_SCHED;
.LBB0_2137:
	s_ashr_i32 s41, s40, 31
	s_lshl_b64 s[42:43], s[40:41], 20
	s_add_u32 s42, s10, s42
	s_addc_u32 s43, s11, s43
	s_and_b64 s[44:45], s[38:39], exec
	s_cselect_b32 s41, s43, s47
	s_cselect_b32 s56, s42, s46
	s_ashr_i32 s37, s36, 31
	s_lshl_b64 s[44:45], s[36:37], 20
	s_add_u32 s44, s12, s44
	s_addc_u32 s45, s13, s45
	s_and_b64 s[50:51], s[38:39], exec
	s_cselect_b32 s37, s45, s49
	s_cselect_b32 s57, s44, s48
	s_add_u32 s46, s46, 0x80080
	s_addc_u32 s47, s47, 0
	s_add_u32 s58, s48, 0x100
	s_addc_u32 s59, s49, 0
	s_mov_b32 s60, -2
	v_add_u32_e32 v163, 0x10000, v143
	s_add_u32 s48, s46, 0xfff80080
	s_addc_u32 s49, s47, -1
	s_add_i32 s61, 0, 0x10000
	s_cmp_eq_u32 s60, 28
	s_cselect_b32 s51, s41, s49
	s_cselect_b32 s50, s56, s48
	s_cselect_b32 s49, s37, s59
	s_cselect_b32 s48, s57, s58
	s_add_i32 s64, 0, 0x14000
	ds_read_b128 v[146:149], v163
	ds_read_b128 v[150:153], v163 offset:1024
	ds_read_b128 v[154:157], v163 offset:2048
	ds_read_b128 v[158:161], v163 offset:3072
	ds_read_b128 v[186:189], v163 offset:16384
	ds_read_b128 v[190:193], v163 offset:17408
	ds_read_b128 v[194:197], v163 offset:18432
	ds_read_b128 v[198:201], v163 offset:19456
	s_add_i32 m0, s21, 0xc000
	ds_read_b128 v[202:205], v145
	ds_read_b128 v[206:209], v145 offset:1024
	ds_read_b128 v[210:213], v145 offset:2048
	ds_read_b128 v[214:217], v145 offset:3072
	ds_read_b128 v[218:221], v145 offset:4096
	ds_read_b128 v[222:225], v145 offset:5120
	ds_read_b128 v[234:237], v145 offset:6144
	ds_read_b128 v[238:241], v145 offset:7168
	global_load_lds_dwordx4 v138, s[46:47]
	s_add_i32 m0, s21, 0xe000
	s_nop 0
	global_load_lds_dwordx4 v140, s[46:47]
	s_waitcnt vmcnt(8)
	s_waitcnt lgkmcnt(0)
	s_barrier
	v_mfma_f32_16x16x32_bf16 v[128:131], v[146:149], v[202:205], 0
	v_mfma_f32_16x16x32_bf16 v[124:127], v[154:157], v[202:205], 0
	v_mfma_f32_16x16x32_bf16 v[120:123], v[146:149], v[210:213], 0
	v_mfma_f32_16x16x32_bf16 v[116:119], v[154:157], v[210:213], 0
	v_mfma_f32_16x16x32_bf16 v[104:107], v[146:149], v[218:221], 0
	v_mfma_f32_16x16x32_bf16 v[100:103], v[154:157], v[218:221], 0
	v_mfma_f32_16x16x32_bf16 v[88:91], v[146:149], v[234:237], 0
	v_mfma_f32_16x16x32_bf16 v[84:87], v[154:157], v[234:237], 0
	v_mfma_f32_16x16x32_bf16 v[128:131], v[150:153], v[206:209], v[128:131]
	v_mfma_f32_16x16x32_bf16 v[124:127], v[158:161], v[206:209], v[124:127]
	v_mfma_f32_16x16x32_bf16 v[120:123], v[150:153], v[214:217], v[120:123]
	v_mfma_f32_16x16x32_bf16 v[116:119], v[158:161], v[214:217], v[116:119]
	v_mfma_f32_16x16x32_bf16 v[104:107], v[150:153], v[222:225], v[104:107]
	v_mfma_f32_16x16x32_bf16 v[100:103], v[158:161], v[222:225], v[100:103]
	v_mfma_f32_16x16x32_bf16 v[88:91], v[150:153], v[238:241], v[88:91]
	v_mfma_f32_16x16x32_bf16 v[84:87], v[158:161], v[238:241], v[84:87]
	v_mfma_f32_16x16x32_bf16 v[112:115], v[186:189], v[202:205], 0
	v_mfma_f32_16x16x32_bf16 v[108:111], v[194:197], v[202:205], 0
	v_mfma_f32_16x16x32_bf16 v[96:99], v[186:189], v[210:213], 0
	v_mfma_f32_16x16x32_bf16 v[92:95], v[194:197], v[210:213], 0
	v_mfma_f32_16x16x32_bf16 v[80:83], v[186:189], v[218:221], 0
	v_mfma_f32_16x16x32_bf16 v[76:79], v[194:197], v[218:221], 0
	v_mfma_f32_16x16x32_bf16 v[72:75], v[186:189], v[234:237], 0
	v_mfma_f32_16x16x32_bf16 v[68:71], v[194:197], v[234:237], 0
	v_mfma_f32_16x16x32_bf16 v[112:115], v[190:193], v[206:209], v[112:115]
	v_mfma_f32_16x16x32_bf16 v[108:111], v[198:201], v[206:209], v[108:111]
	v_mfma_f32_16x16x32_bf16 v[96:99], v[190:193], v[214:217], v[96:99]
	v_mfma_f32_16x16x32_bf16 v[92:95], v[198:201], v[214:217], v[92:95]
	v_mfma_f32_16x16x32_bf16 v[80:83], v[190:193], v[222:225], v[80:83]
	v_mfma_f32_16x16x32_bf16 v[76:79], v[198:201], v[222:225], v[76:79]
	v_mfma_f32_16x16x32_bf16 v[72:75], v[190:193], v[238:241], v[72:75]
	v_mfma_f32_16x16x32_bf16 v[68:71], v[198:201], v[238:241], v[68:71]
	s_barrier
	s_add_i32 s61, s61, s15
	s_mov_b32 m0, s61
	ds_read_b128 v[202:205], v145 offset:16384
	ds_read_b128 v[206:209], v145 offset:17408
	ds_read_b128 v[210:213], v145 offset:18432
	ds_read_b128 v[214:217], v145 offset:19456
	ds_read_b128 v[218:221], v145 offset:20480
	ds_read_b128 v[222:225], v145 offset:21504
	ds_read_b128 v[234:237], v145 offset:22528
	ds_read_b128 v[238:241], v145 offset:23552
	global_load_lds_dwordx4 v34, s[48:49]
	s_add_i32 m0, s61, 0x2000
	s_add_u32 s62, s48, 0x80000
	s_addc_u32 s63, s49, 0
	s_add_i32 s61, s64, s15
	global_load_lds_dwordx4 v136, s[48:49]
	s_mov_b32 m0, s61
	s_add_u32 s98, s50, 0x80
	s_addc_u32 s99, s51, 0
	global_load_lds_dwordx4 v34, s[62:63]
	s_add_i32 m0, s61, 0x2000
	s_nop 0
	global_load_lds_dwordx4 v136, s[62:63]
	s_mov_b32 m0, s21
	s_nop 0
	global_load_lds_dwordx4 v132, s[50:51]
	s_mov_b32 m0, s34
	s_nop 0
	global_load_lds_dwordx4 v134, s[50:51]
	s_waitcnt vmcnt(8)
	s_waitcnt lgkmcnt(0)
	s_barrier
	v_mfma_f32_16x16x32_bf16 v[64:67], v[146:149], v[202:205], 0
	v_mfma_f32_16x16x32_bf16 v[60:63], v[154:157], v[202:205], 0
	v_mfma_f32_16x16x32_bf16 v[56:59], v[146:149], v[210:213], 0
	v_mfma_f32_16x16x32_bf16 v[52:55], v[154:157], v[210:213], 0
	v_mfma_f32_16x16x32_bf16 v[40:43], v[146:149], v[218:221], 0
	v_mfma_f32_16x16x32_bf16 v[36:39], v[154:157], v[218:221], 0
	v_mfma_f32_16x16x32_bf16 v[22:25], v[146:149], v[234:237], 0
	v_mfma_f32_16x16x32_bf16 v[18:21], v[154:157], v[234:237], 0
	v_mfma_f32_16x16x32_bf16 v[64:67], v[150:153], v[206:209], v[64:67]
	v_mfma_f32_16x16x32_bf16 v[60:63], v[158:161], v[206:209], v[60:63]
	v_mfma_f32_16x16x32_bf16 v[56:59], v[150:153], v[214:217], v[56:59]
	v_mfma_f32_16x16x32_bf16 v[52:55], v[158:161], v[214:217], v[52:55]
	v_mfma_f32_16x16x32_bf16 v[40:43], v[150:153], v[222:225], v[40:43]
	v_mfma_f32_16x16x32_bf16 v[36:39], v[158:161], v[222:225], v[36:39]
	v_mfma_f32_16x16x32_bf16 v[22:25], v[150:153], v[238:241], v[22:25]
	v_mfma_f32_16x16x32_bf16 v[18:21], v[158:161], v[238:241], v[18:21]
	v_mfma_f32_16x16x32_bf16 v[48:51], v[186:189], v[202:205], 0
	v_mfma_f32_16x16x32_bf16 v[44:47], v[194:197], v[202:205], 0
	v_mfma_f32_16x16x32_bf16 v[30:33], v[186:189], v[210:213], 0
	v_mfma_f32_16x16x32_bf16 v[26:29], v[194:197], v[210:213], 0
	v_mfma_f32_16x16x32_bf16 v[14:17], v[186:189], v[218:221], 0
	v_mfma_f32_16x16x32_bf16 v[10:13], v[194:197], v[218:221], 0
	v_mfma_f32_16x16x32_bf16 v[6:9], v[186:189], v[234:237], 0
	v_mfma_f32_16x16x32_bf16 v[2:5], v[194:197], v[234:237], 0
	v_mfma_f32_16x16x32_bf16 v[48:51], v[190:193], v[206:209], v[48:51]
	v_mfma_f32_16x16x32_bf16 v[44:47], v[198:201], v[206:209], v[44:47]
	v_mfma_f32_16x16x32_bf16 v[30:33], v[190:193], v[214:217], v[30:33]
	v_mfma_f32_16x16x32_bf16 v[26:29], v[198:201], v[214:217], v[26:29]
	v_mfma_f32_16x16x32_bf16 v[14:17], v[190:193], v[222:225], v[14:17]
	v_mfma_f32_16x16x32_bf16 v[10:13], v[198:201], v[222:225], v[10:13]
	v_mfma_f32_16x16x32_bf16 v[6:9], v[190:193], v[238:241], v[6:9]
	v_mfma_f32_16x16x32_bf16 v[2:5], v[198:201], v[238:241], v[2:5]
	s_barrier
	s_branch .Lpeel_mid_2138
	.p2align	6

; #define PG8_STAGE(bufoff, gbase, voff) do { _Pragma("unroll") for (int _i = 0; _i < 2; ++_i) \
;         __builtin_amdgcn_global_load_lds((const unsigned*)((const char*)(gbase) + (voff)[_i]), (PG8_LAS unsigned*)(lds + (bufoff) + ldsw + _i * 8192), 16, 0, 0); } while (0)
; #define PG8_LDA(dst, b, h) do { _Pragma("unroll") for (int m = 0; m < 4; ++m) _Pragma("unroll") for (int k = 0; k < 2; ++k) dst[m][k] = *(const PG8_LAS bf16x8*)(lds + PG8_SA(b, h) + aoff + m * 2048 + k * 1024); } while (0)
; #define PG8_LDB(dst, b, h) do { _Pragma("unroll") for (int n = 0; n < 2; ++n) _Pragma("unroll") for (int k = 0; k < 2; ++k) dst[n][k] = *(const PG8_LAS bf16x8*)(lds + PG8_SB(b, h) + boff + n * 2048 + k * 1024); } while (0)
; #define PG8_WAIT_V(n) asm volatile("s_waitcnt vmcnt(" #n ")" ::: "memory")
; #define PG8_WAIT_L(n) asm volatile("s_waitcnt lgkmcnt(" #n ")" ::: "memory")
; #define PG8_BAR __builtin_amdgcn_s_barrier()
;     ...
;         for (int t = 0; t < nt; t += 2) {
;             const bool last = (t == nt - 2);
;             const char* a1 = cA + (size_t)(t + 1) * kstep;
;             const char* a2 = last ? nA : cA + (size_t)(t + 2) * kstep; const char* b2 = last ? nB : cB + (size_t)(t + 2) * kstep;
;             const char* a3 = a2 + kstep; const char* b3 = b2 + kstep;
;             if (last && has_next) S.a_ready(nxt);
;             if constexpr (SP2) {
;             PG8_LDB(B0, 0, 0); PG8_LDB(B1, 0, 1); PG8_SCHED; PG8_LDA(At, 0, 0); PG8_STAGE(PG8_SA(1, 1), a1 + hstepA, voffA);
;             PG8_WAIT_V(8); PG8_WAIT_L(0); PG8_BAR; PG8_MMA(0, 0, At, B0); PG8_MMA(0, 1, At, B1); PG8_BAR; PG8_SCHED;
;             PG8_LDA(At, 0, 1); PG8_STAGE(PG8_SB(0, 0), b2, voffB); PG8_STAGE(PG8_SB(0, 1), b2 + hstepB, voffB); PG8_STAGE(PG8_SA(0, 0), a2, voffA);
;             PG8_WAIT_V(8); PG8_WAIT_L(0); PG8_BAR; PG8_MMA(1, 0, At, B0); PG8_MMA(1, 1, At, B1); PG8_BAR; PG8_SCHED;
;             PG8_LDB(B0, 1, 0); PG8_LDB(B1, 1, 1); PG8_SCHED; PG8_LDA(At, 1, 0); PG8_STAGE(PG8_SA(0, 1), a2 + hstepA, voffA);
;             PG8_WAIT_V(8); PG8_WAIT_L(0); PG8_BAR; PG8_MMA(0, 0, At, B0); PG8_MMA(0, 1, At, B1); PG8_BAR; PG8_SCHED;
;             PG8_LDA(At, 1, 1); PG8_STAGE(PG8_SB(1, 0), b3, voffB); PG8_STAGE(PG8_SB(1, 1), b3 + hstepB, voffB); PG8_STAGE(PG8_SA(1, 0), a3, voffA);
;             PG8_WAIT_V(8); PG8_WAIT_L(0); PG8_BAR; PG8_MMA(1, 0, At, B0); PG8_MMA(1, 1, At, B1); PG8_BAR; PG8_SCHED;
.Lpeel_mid_2138:
	s_add_i32 s61, 0, 0x18000
	s_add_i32 s62, 0, 0x1c000
	ds_read_b128 v[146:149], v163 offset:32768
	ds_read_b128 v[150:153], v163 offset:33792
	ds_read_b128 v[154:157], v163 offset:34816
	ds_read_b128 v[158:161], v163 offset:35840
	ds_read_b128 v[186:189], v163 offset:49152
	ds_read_b128 v[190:193], v163 offset:50176
	ds_read_b128 v[194:197], v163 offset:51200
	ds_read_b128 v[198:201], v163 offset:52224
	s_add_u32 s50, s50, 0x80000
	s_addc_u32 s51, s51, 0
	s_mov_b32 m0, s35
	ds_read_b128 v[202:205], v145 offset:32768
	ds_read_b128 v[206:209], v145 offset:33792
	ds_read_b128 v[210:213], v145 offset:34816
	ds_read_b128 v[214:217], v145 offset:35840
	ds_read_b128 v[218:221], v145 offset:36864
	ds_read_b128 v[222:225], v145 offset:37888
	ds_read_b128 v[234:237], v145 offset:38912
	ds_read_b128 v[238:241], v145 offset:39936
	global_load_lds_dwordx4 v132, s[50:51]
	s_mov_b32 m0, s52
	s_nop 0
	global_load_lds_dwordx4 v134, s[50:51]
	s_waitcnt vmcnt(8)
	s_waitcnt lgkmcnt(0)
	s_barrier
	v_mfma_f32_16x16x32_bf16 v[128:131], v[146:149], v[202:205], v[128:131]
	v_mfma_f32_16x16x32_bf16 v[124:127], v[154:157], v[202:205], v[124:127]
	v_mfma_f32_16x16x32_bf16 v[120:123], v[146:149], v[210:213], v[120:123]
	v_mfma_f32_16x16x32_bf16 v[116:119], v[154:157], v[210:213], v[116:119]
	v_mfma_f32_16x16x32_bf16 v[104:107], v[146:149], v[218:221], v[104:107]
	v_mfma_f32_16x16x32_bf16 v[100:103], v[154:157], v[218:221], v[100:103]
	v_mfma_f32_16x16x32_bf16 v[88:91], v[146:149], v[234:237], v[88:91]
	v_mfma_f32_16x16x32_bf16 v[84:87], v[154:157], v[234:237], v[84:87]
	v_mfma_f32_16x16x32_bf16 v[128:131], v[150:153], v[206:209], v[128:131]
	v_mfma_f32_16x16x32_bf16 v[124:127], v[158:161], v[206:209], v[124:127]
	v_mfma_f32_16x16x32_bf16 v[120:123], v[150:153], v[214:217], v[120:123]
	v_mfma_f32_16x16x32_bf16 v[116:119], v[158:161], v[214:217], v[116:119]
	v_mfma_f32_16x16x32_bf16 v[104:107], v[150:153], v[222:225], v[104:107]
	v_mfma_f32_16x16x32_bf16 v[100:103], v[158:161], v[222:225], v[100:103]
	v_mfma_f32_16x16x32_bf16 v[88:91], v[150:153], v[238:241], v[88:91]
	v_mfma_f32_16x16x32_bf16 v[84:87], v[158:161], v[238:241], v[84:87]
	v_mfma_f32_16x16x32_bf16 v[112:115], v[186:189], v[202:205], v[112:115]
	v_mfma_f32_16x16x32_bf16 v[108:111], v[194:197], v[202:205], v[108:111]
	v_mfma_f32_16x16x32_bf16 v[96:99], v[186:189], v[210:213], v[96:99]
	v_mfma_f32_16x16x32_bf16 v[92:95], v[194:197], v[210:213], v[92:95]
	v_mfma_f32_16x16x32_bf16 v[80:83], v[186:189], v[218:221], v[80:83]
	v_mfma_f32_16x16x32_bf16 v[76:79], v[194:197], v[218:221], v[76:79]
	v_mfma_f32_16x16x32_bf16 v[72:75], v[186:189], v[234:237], v[72:75]
	v_mfma_f32_16x16x32_bf16 v[68:71], v[194:197], v[234:237], v[68:71]
	v_mfma_f32_16x16x32_bf16 v[112:115], v[190:193], v[206:209], v[112:115]
	v_mfma_f32_16x16x32_bf16 v[108:111], v[198:201], v[206:209], v[108:111]
	v_mfma_f32_16x16x32_bf16 v[96:99], v[190:193], v[214:217], v[96:99]
	v_mfma_f32_16x16x32_bf16 v[92:95], v[198:201], v[214:217], v[92:95]
	v_mfma_f32_16x16x32_bf16 v[80:83], v[190:193], v[222:225], v[80:83]
	v_mfma_f32_16x16x32_bf16 v[76:79], v[198:201], v[222:225], v[76:79]
	v_mfma_f32_16x16x32_bf16 v[72:75], v[190:193], v[238:241], v[72:75]
	v_mfma_f32_16x16x32_bf16 v[68:71], v[198:201], v[238:241], v[68:71]
	s_barrier
	s_add_i32 s50, s61, s15
	s_mov_b32 m0, s50
	ds_read_b128 v[202:205], v145 offset:49152
	ds_read_b128 v[206:209], v145 offset:50176
	ds_read_b128 v[210:213], v145 offset:51200
	ds_read_b128 v[214:217], v145 offset:52224
	ds_read_b128 v[218:221], v145 offset:53248
	ds_read_b128 v[222:225], v145 offset:54272
	ds_read_b128 v[234:237], v145 offset:55296
	ds_read_b128 v[238:241], v145 offset:56320
	s_add_u32 vcc_lo, s48, 0x80
	s_addc_u32 vcc_hi, s49, 0
	global_load_lds_dwordx4 v34, vcc
	s_add_i32 m0, s50, 0x2000
	s_add_u32 s48, s48, 0x80080
	s_addc_u32 s49, s49, 0
	s_add_i32 s50, s62, s15
	s_add_u32 vcc_lo, s48, 0xfff80000
	s_addc_u32 vcc_hi, s49, -1
	global_load_lds_dwordx4 v136, vcc
	s_mov_b32 m0, s50
	s_nop 0
	global_load_lds_dwordx4 v34, s[48:49]
	s_add_i32 m0, s50, 0x2000
	s_nop 0
	global_load_lds_dwordx4 v136, s[48:49]
	s_mov_b32 m0, s24
	s_nop 0
	global_load_lds_dwordx4 v132, s[98:99]
	s_mov_b32 m0, s53
	s_nop 0
	global_load_lds_dwordx4 v134, s[98:99]
	s_waitcnt vmcnt(8)
	s_waitcnt lgkmcnt(0)
	s_barrier
	v_mfma_f32_16x16x32_bf16 v[64:67], v[146:149], v[202:205], v[64:67]
	v_mfma_f32_16x16x32_bf16 v[60:63], v[154:157], v[202:205], v[60:63]
	v_mfma_f32_16x16x32_bf16 v[56:59], v[146:149], v[210:213], v[56:59]
	v_mfma_f32_16x16x32_bf16 v[52:55], v[154:157], v[210:213], v[52:55]
	v_mfma_f32_16x16x32_bf16 v[40:43], v[146:149], v[218:221], v[40:43]
	v_mfma_f32_16x16x32_bf16 v[36:39], v[154:157], v[218:221], v[36:39]
	v_mfma_f32_16x16x32_bf16 v[22:25], v[146:149], v[234:237], v[22:25]
	v_mfma_f32_16x16x32_bf16 v[18:21], v[154:157], v[234:237], v[18:21]
	v_mfma_f32_16x16x32_bf16 v[64:67], v[150:153], v[206:209], v[64:67]
	v_mfma_f32_16x16x32_bf16 v[60:63], v[158:161], v[206:209], v[60:63]
	v_mfma_f32_16x16x32_bf16 v[56:59], v[150:153], v[214:217], v[56:59]
	v_mfma_f32_16x16x32_bf16 v[52:55], v[158:161], v[214:217], v[52:55]
	v_mfma_f32_16x16x32_bf16 v[40:43], v[150:153], v[222:225], v[40:43]
	v_mfma_f32_16x16x32_bf16 v[36:39], v[158:161], v[222:225], v[36:39]
	v_mfma_f32_16x16x32_bf16 v[22:25], v[150:153], v[238:241], v[22:25]
	v_mfma_f32_16x16x32_bf16 v[18:21], v[158:161], v[238:241], v[18:21]
	v_mfma_f32_16x16x32_bf16 v[48:51], v[186:189], v[202:205], v[48:51]
	v_mfma_f32_16x16x32_bf16 v[44:47], v[194:197], v[202:205], v[44:47]
	v_mfma_f32_16x16x32_bf16 v[30:33], v[186:189], v[210:213], v[30:33]
	v_mfma_f32_16x16x32_bf16 v[26:29], v[194:197], v[210:213], v[26:29]
	v_mfma_f32_16x16x32_bf16 v[14:17], v[186:189], v[218:221], v[14:17]
	v_mfma_f32_16x16x32_bf16 v[10:13], v[194:197], v[218:221], v[10:13]
	v_mfma_f32_16x16x32_bf16 v[6:9], v[186:189], v[234:237], v[6:9]
	v_mfma_f32_16x16x32_bf16 v[2:5], v[194:197], v[234:237], v[2:5]
	v_mfma_f32_16x16x32_bf16 v[48:51], v[190:193], v[206:209], v[48:51]
	v_mfma_f32_16x16x32_bf16 v[44:47], v[198:201], v[206:209], v[44:47]
	v_mfma_f32_16x16x32_bf16 v[30:33], v[190:193], v[214:217], v[30:33]
	v_mfma_f32_16x16x32_bf16 v[26:29], v[198:201], v[214:217], v[26:29]
	v_mfma_f32_16x16x32_bf16 v[14:17], v[190:193], v[222:225], v[14:17]
	v_mfma_f32_16x16x32_bf16 v[10:13], v[198:201], v[222:225], v[10:13]
	v_mfma_f32_16x16x32_bf16 v[6:9], v[190:193], v[238:241], v[6:9]
	v_mfma_f32_16x16x32_bf16 v[2:5], v[198:201], v[238:241], v[2:5]
	s_barrier
	s_add_i32 s60, s60, 2
	s_add_u32 s46, s46, 0x100
	s_addc_u32 s47, s47, 0
	s_add_u32 s58, s58, 0x100
	s_addc_u32 s59, s59, 0
	s_cmp_gt_u32 s60, 29
	s_cbranch_scc0 .LBB0_2138
	s_and_b64 vcc, exec, s[28:29]
	s_cbranch_vccz .LBB0_2141
	s_barrier
